# v78 + role-staggered issue order in K-loop load segments: even waves DMA-first, odd waves ds_read-first (per-wave branch on a wave-parity SGPR)
# baseline (speedup 1.0000x reference)
.Lprio_skip_21:
	v_readfirstlane_b32 s97, v206
	s_nop 3
	s_lshr_b32 s97, s97, 6
	.p2align	3
	s_nop 0
.LBB0_163:
	s_bitcmp1_b32 s97, 0
	s_cbranch_scc1 .Lstg_21_0_b
	s_cmp_eq_i32 s55, -2
	s_cbranch_scc1 .Lbal_first_21
	s_mov_b32 m0, s45
	s_nop 0
	global_load_lds_dwordx4 v221, s[100:101]
	s_mov_b32 m0, s46
	s_nop 0
	global_load_lds_dwordx4 v205, s[100:101]
.Lbal_first_21:
	s_add_u32 s26, s24, 0xfffc0080
	s_addc_u32 s27, s25, -1
	s_cmp_eq_u32 s55, 12
	s_cselect_b32 s29, s19, s27
	s_cselect_b32 s28, s51, s26
	s_cselect_b32 s27, s17, s54
	s_cselect_b32 s26, s52, s53
	s_add_i32 m0, s38, 0xc000
	s_nop 0
	global_load_lds_dwordx4 v138, s[24:25]
	s_add_i32 m0, s38, 0xe000
	s_nop 0
	global_load_lds_dwordx4 v136, s[24:25]
	ds_read_b128 v[144:147], v151
	ds_read_b128 v[156:159], v151 offset:1024
	ds_read_b128 v[160:163], v151 offset:2048
	ds_read_b128 v[164:167], v151 offset:3072
	ds_read_b128 v[168:171], v152
	ds_read_b128 v[172:175], v152 offset:1024
	ds_read_b128 v[176:179], v152 offset:2048
	ds_read_b128 v[180:183], v152 offset:3072
	ds_read_b128 v[184:187], v153
	ds_read_b128 v[188:191], v153 offset:1024
	ds_read_b128 v[192:195], v153 offset:2048
	ds_read_b128 v[196:199], v153 offset:3072
	ds_read_b128 v[200:203], v153 offset:4096
	ds_read_b128 v[208:211], v153 offset:5120
	ds_read_b128 v[212:215], v153 offset:6144
	ds_read_b128 v[216:219], v153 offset:7168
	s_branch .Lstg_21_0_j

.Lbal_first_21_b:
	ds_read_b128 v[144:147], v151
	ds_read_b128 v[156:159], v151 offset:1024
	ds_read_b128 v[160:163], v151 offset:2048
	ds_read_b128 v[164:167], v151 offset:3072
	ds_read_b128 v[168:171], v152
	ds_read_b128 v[172:175], v152 offset:1024
	ds_read_b128 v[176:179], v152 offset:2048
	ds_read_b128 v[180:183], v152 offset:3072
	s_add_u32 s26, s24, 0xfffc0080
	s_addc_u32 s27, s25, -1
	s_cmp_eq_u32 s55, 12
	s_cselect_b32 s29, s19, s27
	s_cselect_b32 s28, s51, s26
	s_cselect_b32 s27, s17, s54
	s_cselect_b32 s26, s52, s53
	s_add_i32 m0, s38, 0xc000
	ds_read_b128 v[184:187], v153
	ds_read_b128 v[188:191], v153 offset:1024
	ds_read_b128 v[192:195], v153 offset:2048
	ds_read_b128 v[196:199], v153 offset:3072
	ds_read_b128 v[200:203], v153 offset:4096
	ds_read_b128 v[208:211], v153 offset:5120
	ds_read_b128 v[212:215], v153 offset:6144
	ds_read_b128 v[216:219], v153 offset:7168
	global_load_lds_dwordx4 v138, s[24:25]
	s_add_i32 m0, s38, 0xe000
	s_nop 0
	global_load_lds_dwordx4 v136, s[24:25]
.Lstg_21_0_j:
	s_waitcnt vmcnt(8)
	s_waitcnt lgkmcnt(0)
	s_barrier
	s_waitcnt lgkmcnt(0)
	v_mfma_f32_16x16x32_bf16 v[124:127], v[144:147], v[184:187], v[124:127]
	v_mfma_f32_16x16x32_bf16 v[120:123], v[160:163], v[184:187], v[120:123]
	v_mfma_f32_16x16x32_bf16 v[108:111], v[144:147], v[192:195], v[108:111]
	v_mfma_f32_16x16x32_bf16 v[104:107], v[160:163], v[192:195], v[104:107]
	v_mfma_f32_16x16x32_bf16 v[92:95], v[144:147], v[200:203], v[92:95]
	v_mfma_f32_16x16x32_bf16 v[88:91], v[160:163], v[200:203], v[88:91]
	v_mfma_f32_16x16x32_bf16 v[76:79], v[144:147], v[212:215], v[76:79]
	v_mfma_f32_16x16x32_bf16 v[72:75], v[160:163], v[212:215], v[72:75]
	v_mfma_f32_16x16x32_bf16 v[124:127], v[156:159], v[188:191], v[124:127]
	v_mfma_f32_16x16x32_bf16 v[120:123], v[164:167], v[188:191], v[120:123]
	v_mfma_f32_16x16x32_bf16 v[108:111], v[156:159], v[196:199], v[108:111]
	v_mfma_f32_16x16x32_bf16 v[104:107], v[164:167], v[196:199], v[104:107]
	v_mfma_f32_16x16x32_bf16 v[92:95], v[156:159], v[208:211], v[92:95]
	v_mfma_f32_16x16x32_bf16 v[88:91], v[164:167], v[208:211], v[88:91]
	v_mfma_f32_16x16x32_bf16 v[76:79], v[156:159], v[216:219], v[76:79]
	v_mfma_f32_16x16x32_bf16 v[72:75], v[164:167], v[216:219], v[72:75]
	v_mfma_f32_16x16x32_bf16 v[116:119], v[168:171], v[184:187], v[116:119]
	v_mfma_f32_16x16x32_bf16 v[112:115], v[176:179], v[184:187], v[112:115]
	v_mfma_f32_16x16x32_bf16 v[100:103], v[168:171], v[192:195], v[100:103]
	v_mfma_f32_16x16x32_bf16 v[96:99], v[176:179], v[192:195], v[96:99]
	v_mfma_f32_16x16x32_bf16 v[84:87], v[168:171], v[200:203], v[84:87]
	v_mfma_f32_16x16x32_bf16 v[80:83], v[176:179], v[200:203], v[80:83]
	v_mfma_f32_16x16x32_bf16 v[68:71], v[168:171], v[212:215], v[68:71]
	v_mfma_f32_16x16x32_bf16 v[64:67], v[176:179], v[212:215], v[64:67]
	v_mfma_f32_16x16x32_bf16 v[116:119], v[172:175], v[188:191], v[116:119]
	v_mfma_f32_16x16x32_bf16 v[112:115], v[180:183], v[188:191], v[112:115]
	v_mfma_f32_16x16x32_bf16 v[100:103], v[172:175], v[196:199], v[100:103]
	v_mfma_f32_16x16x32_bf16 v[96:99], v[180:183], v[196:199], v[96:99]
	v_mfma_f32_16x16x32_bf16 v[84:87], v[172:175], v[208:211], v[84:87]
	v_mfma_f32_16x16x32_bf16 v[80:83], v[180:183], v[208:211], v[80:83]
	v_mfma_f32_16x16x32_bf16 v[68:71], v[172:175], v[216:219], v[68:71]
	v_mfma_f32_16x16x32_bf16 v[64:67], v[180:183], v[216:219], v[64:67]
	s_barrier
	s_bitcmp1_b32 s97, 0
	s_cbranch_scc1 .Lstg_21_1_b
	s_add_i32 s56, s48, s35
	s_mov_b32 m0, s56
	s_nop 0
	global_load_lds_dwordx4 v132, s[26:27]
	s_add_i32 m0, s56, 0x2000
	s_add_u32 s56, s26, 0x40000
	s_mov_b64 s[98:99], s[26:27]
	s_addc_u32 s57, s27, 0
	s_add_i32 s58, s49, s35
	global_load_lds_dwordx4 v128, s[26:27]
	s_mov_b32 m0, s58
	s_mov_b64 s[100:101], s[28:29]
	global_load_lds_dwordx4 v132, s[56:57]
	s_add_i32 m0, s58, 0x2000
	s_nop 0
	global_load_lds_dwordx4 v128, s[56:57]
	ds_read_b128 v[184:187], v153 offset:16384
	ds_read_b128 v[188:191], v153 offset:17408
	ds_read_b128 v[192:195], v153 offset:18432
	ds_read_b128 v[196:199], v153 offset:19456
	ds_read_b128 v[200:203], v153 offset:20480
	ds_read_b128 v[208:211], v153 offset:21504
	ds_read_b128 v[212:215], v153 offset:22528
	ds_read_b128 v[216:219], v153 offset:23552
	s_branch .Lstg_21_1_j
.Lstg_21_1_b:
	s_add_i32 s56, s48, s35
	s_mov_b32 m0, s56
	ds_read_b128 v[184:187], v153 offset:16384
	ds_read_b128 v[188:191], v153 offset:17408
	ds_read_b128 v[192:195], v153 offset:18432
	ds_read_b128 v[196:199], v153 offset:19456
	ds_read_b128 v[200:203], v153 offset:20480
	ds_read_b128 v[208:211], v153 offset:21504
	ds_read_b128 v[212:215], v153 offset:22528
	ds_read_b128 v[216:219], v153 offset:23552
	global_load_lds_dwordx4 v132, s[26:27]
	s_add_i32 m0, s56, 0x2000
	s_add_u32 s56, s26, 0x40000
	s_mov_b64 s[98:99], s[26:27]
	s_addc_u32 s57, s27, 0
	s_add_i32 s58, s49, s35
	global_load_lds_dwordx4 v128, s[26:27]
	s_mov_b32 m0, s58
	s_mov_b64 s[100:101], s[28:29]
	global_load_lds_dwordx4 v132, s[56:57]
	s_add_i32 m0, s58, 0x2000
	s_nop 0
	global_load_lds_dwordx4 v128, s[56:57]
.Lstg_21_1_j:
	s_waitcnt vmcnt(6)
	s_waitcnt lgkmcnt(0)
	s_barrier
	s_waitcnt lgkmcnt(0)
	v_mfma_f32_16x16x32_bf16 v[60:63], v[144:147], v[184:187], v[60:63]
	v_mfma_f32_16x16x32_bf16 v[56:59], v[160:163], v[184:187], v[56:59]
	v_mfma_f32_16x16x32_bf16 v[44:47], v[144:147], v[192:195], v[44:47]
	v_mfma_f32_16x16x32_bf16 v[40:43], v[160:163], v[192:195], v[40:43]
	v_mfma_f32_16x16x32_bf16 v[28:31], v[144:147], v[200:203], v[28:31]
	v_mfma_f32_16x16x32_bf16 v[24:27], v[160:163], v[200:203], v[24:27]
	v_mfma_f32_16x16x32_bf16 v[12:15], v[144:147], v[212:215], v[12:15]
	v_mfma_f32_16x16x32_bf16 v[8:11], v[160:163], v[212:215], v[8:11]
	v_mfma_f32_16x16x32_bf16 v[60:63], v[156:159], v[188:191], v[60:63]
	v_mfma_f32_16x16x32_bf16 v[56:59], v[164:167], v[188:191], v[56:59]
	v_mfma_f32_16x16x32_bf16 v[44:47], v[156:159], v[196:199], v[44:47]
	v_mfma_f32_16x16x32_bf16 v[40:43], v[164:167], v[196:199], v[40:43]
	v_mfma_f32_16x16x32_bf16 v[28:31], v[156:159], v[208:211], v[28:31]
	v_mfma_f32_16x16x32_bf16 v[24:27], v[164:167], v[208:211], v[24:27]
	v_mfma_f32_16x16x32_bf16 v[12:15], v[156:159], v[216:219], v[12:15]
	v_mfma_f32_16x16x32_bf16 v[8:11], v[164:167], v[216:219], v[8:11]
	v_mfma_f32_16x16x32_bf16 v[52:55], v[168:171], v[184:187], v[52:55]
	v_mfma_f32_16x16x32_bf16 v[48:51], v[176:179], v[184:187], v[48:51]
	v_mfma_f32_16x16x32_bf16 v[36:39], v[168:171], v[192:195], v[36:39]
	v_mfma_f32_16x16x32_bf16 v[32:35], v[176:179], v[192:195], v[32:35]
	v_mfma_f32_16x16x32_bf16 v[20:23], v[168:171], v[200:203], v[20:23]
	v_mfma_f32_16x16x32_bf16 v[16:19], v[176:179], v[200:203], v[16:19]
	v_mfma_f32_16x16x32_bf16 v[4:7], v[168:171], v[212:215], v[4:7]
	v_mfma_f32_16x16x32_bf16 v[0:3], v[176:179], v[212:215], v[0:3]
	v_mfma_f32_16x16x32_bf16 v[52:55], v[172:175], v[188:191], v[52:55]
	v_mfma_f32_16x16x32_bf16 v[48:51], v[180:183], v[188:191], v[48:51]
	v_mfma_f32_16x16x32_bf16 v[36:39], v[172:175], v[196:199], v[36:39]
	v_mfma_f32_16x16x32_bf16 v[32:35], v[180:183], v[196:199], v[32:35]
	v_mfma_f32_16x16x32_bf16 v[20:23], v[172:175], v[208:211], v[20:23]
	v_mfma_f32_16x16x32_bf16 v[16:19], v[180:183], v[208:211], v[16:19]
	v_mfma_f32_16x16x32_bf16 v[4:7], v[172:175], v[216:219], v[4:7]
	v_mfma_f32_16x16x32_bf16 v[0:3], v[180:183], v[216:219], v[0:3]
	s_barrier
	s_bitcmp1_b32 s97, 0
	s_cbranch_scc1 .Lstg_21_2_b
	s_mov_b32 m0, s38
	s_nop 0
	global_load_lds_dwordx4 v134, s[28:29]
	s_mov_b32 m0, s39
	s_nop 0
	global_load_lds_dwordx4 v130, s[28:29]
	s_add_i32 s56, 0, 0x18000
	s_add_i32 s57, 0, 0x1c000
	s_add_u32 s28, s28, 0x40000
	s_addc_u32 s29, s29, 0
	s_mov_b32 m0, s40
	s_nop 0
	global_load_lds_dwordx4 v134, s[28:29]
	s_mov_b32 m0, s41
	s_nop 0
	global_load_lds_dwordx4 v130, s[28:29]
	v_add_u32_e32 v164, s56, v149
	v_add_u32_e32 v180, s57, v149
	ds_read_b128 v[144:147], v164
	ds_read_b128 v[156:159], v164 offset:1024
	ds_read_b128 v[160:163], v164 offset:2048
	ds_read_b128 v[164:167], v164 offset:3072
	ds_read_b128 v[168:171], v180
	ds_read_b128 v[172:175], v180 offset:1024
	ds_read_b128 v[176:179], v180 offset:2048
	ds_read_b128 v[180:183], v180 offset:3072
	ds_read_b128 v[184:187], v153 offset:32768
	ds_read_b128 v[188:191], v153 offset:33792
	ds_read_b128 v[192:195], v153 offset:34816
	ds_read_b128 v[196:199], v153 offset:35840
	ds_read_b128 v[200:203], v153 offset:36864
	ds_read_b128 v[208:211], v153 offset:37888
	ds_read_b128 v[212:215], v153 offset:38912
	ds_read_b128 v[216:219], v153 offset:39936
	s_branch .Lstg_21_2_j
.Lstg_21_2_b:
	s_mov_b32 m0, s38
	s_nop 0
	global_load_lds_dwordx4 v134, s[28:29]
	s_mov_b32 m0, s39
	s_nop 0
	global_load_lds_dwordx4 v130, s[28:29]
	s_add_i32 s56, 0, 0x18000
	s_add_i32 s57, 0, 0x1c000
	v_add_u32_e32 v164, s56, v149
	v_add_u32_e32 v180, s57, v149
	ds_read_b128 v[144:147], v164
	ds_read_b128 v[156:159], v164 offset:1024
	ds_read_b128 v[160:163], v164 offset:2048
	ds_read_b128 v[164:167], v164 offset:3072
	ds_read_b128 v[168:171], v180
	ds_read_b128 v[172:175], v180 offset:1024
	ds_read_b128 v[176:179], v180 offset:2048
	ds_read_b128 v[180:183], v180 offset:3072
	s_add_u32 s28, s28, 0x40000
	s_addc_u32 s29, s29, 0
	s_mov_b32 m0, s40
	ds_read_b128 v[184:187], v153 offset:32768
	ds_read_b128 v[188:191], v153 offset:33792
	ds_read_b128 v[192:195], v153 offset:34816
	ds_read_b128 v[196:199], v153 offset:35840
	ds_read_b128 v[200:203], v153 offset:36864
	ds_read_b128 v[208:211], v153 offset:37888
	ds_read_b128 v[212:215], v153 offset:38912
	ds_read_b128 v[216:219], v153 offset:39936
	global_load_lds_dwordx4 v134, s[28:29]
	s_mov_b32 m0, s41
	s_nop 0
	global_load_lds_dwordx4 v130, s[28:29]
.Lstg_21_2_j:
	s_waitcnt vmcnt(8)
	s_waitcnt lgkmcnt(0)
	s_barrier
	s_waitcnt lgkmcnt(0)
	v_mfma_f32_16x16x32_bf16 v[124:127], v[144:147], v[184:187], v[124:127]
	v_mfma_f32_16x16x32_bf16 v[120:123], v[160:163], v[184:187], v[120:123]
	v_mfma_f32_16x16x32_bf16 v[108:111], v[144:147], v[192:195], v[108:111]
	v_mfma_f32_16x16x32_bf16 v[104:107], v[160:163], v[192:195], v[104:107]
	v_mfma_f32_16x16x32_bf16 v[92:95], v[144:147], v[200:203], v[92:95]
	v_mfma_f32_16x16x32_bf16 v[88:91], v[160:163], v[200:203], v[88:91]
	v_mfma_f32_16x16x32_bf16 v[76:79], v[144:147], v[212:215], v[76:79]
	v_mfma_f32_16x16x32_bf16 v[72:75], v[160:163], v[212:215], v[72:75]
	v_mfma_f32_16x16x32_bf16 v[124:127], v[156:159], v[188:191], v[124:127]
	v_mfma_f32_16x16x32_bf16 v[120:123], v[164:167], v[188:191], v[120:123]
	v_mfma_f32_16x16x32_bf16 v[108:111], v[156:159], v[196:199], v[108:111]
	v_mfma_f32_16x16x32_bf16 v[104:107], v[164:167], v[196:199], v[104:107]
	v_mfma_f32_16x16x32_bf16 v[92:95], v[156:159], v[208:211], v[92:95]
	v_mfma_f32_16x16x32_bf16 v[88:91], v[164:167], v[208:211], v[88:91]
	v_mfma_f32_16x16x32_bf16 v[76:79], v[156:159], v[216:219], v[76:79]
	v_mfma_f32_16x16x32_bf16 v[72:75], v[164:167], v[216:219], v[72:75]
	v_mfma_f32_16x16x32_bf16 v[116:119], v[168:171], v[184:187], v[116:119]
	v_mfma_f32_16x16x32_bf16 v[112:115], v[176:179], v[184:187], v[112:115]
	v_mfma_f32_16x16x32_bf16 v[100:103], v[168:171], v[192:195], v[100:103]
	v_mfma_f32_16x16x32_bf16 v[96:99], v[176:179], v[192:195], v[96:99]
	v_mfma_f32_16x16x32_bf16 v[84:87], v[168:171], v[200:203], v[84:87]
	v_mfma_f32_16x16x32_bf16 v[80:83], v[176:179], v[200:203], v[80:83]
	v_mfma_f32_16x16x32_bf16 v[68:71], v[168:171], v[212:215], v[68:71]
	v_mfma_f32_16x16x32_bf16 v[64:67], v[176:179], v[212:215], v[64:67]
	v_mfma_f32_16x16x32_bf16 v[116:119], v[172:175], v[188:191], v[116:119]
	v_mfma_f32_16x16x32_bf16 v[112:115], v[180:183], v[188:191], v[112:115]
	v_mfma_f32_16x16x32_bf16 v[100:103], v[172:175], v[196:199], v[100:103]
	v_mfma_f32_16x16x32_bf16 v[96:99], v[180:183], v[196:199], v[96:99]
	v_mfma_f32_16x16x32_bf16 v[84:87], v[172:175], v[208:211], v[84:87]
	v_mfma_f32_16x16x32_bf16 v[80:83], v[180:183], v[208:211], v[80:83]
	v_mfma_f32_16x16x32_bf16 v[68:71], v[172:175], v[216:219], v[68:71]
	v_mfma_f32_16x16x32_bf16 v[64:67], v[180:183], v[216:219], v[64:67]
	s_barrier
	s_bitcmp1_b32 s97, 0
	s_cbranch_scc1 .Lstg_21_3_b
	s_add_i32 s28, s56, s35
	s_mov_b32 m0, s28
	s_nop 0
	global_load_lds_dwordx4 v220, s[26:27]
	s_add_i32 m0, s28, 0x2000
	s_add_u32 s26, s26, 0x40080
	s_addc_u32 s27, s27, 0
	s_add_i32 s28, s57, s35
	global_load_lds_dwordx4 v204, s[98:99]
	s_mov_b32 m0, s28
	s_nop 0
	global_load_lds_dwordx4 v132, s[26:27]
	s_add_i32 m0, s28, 0x2000
	s_nop 0
	global_load_lds_dwordx4 v128, s[26:27]
	s_cmp_lg_u32 s55, 12
	s_cbranch_scc1 .Lbal_last_21
	s_mov_b32 m0, s45
	s_nop 0
	global_load_lds_dwordx4 v221, s[100:101]
	s_mov_b32 m0, s46
	s_nop 0
	global_load_lds_dwordx4 v205, s[100:101]
.Lbal_last_21:
	ds_read_b128 v[184:187], v153 offset:49152
	ds_read_b128 v[188:191], v153 offset:50176
	ds_read_b128 v[192:195], v153 offset:51200
	ds_read_b128 v[196:199], v153 offset:52224
	ds_read_b128 v[200:203], v153 offset:53248
	ds_read_b128 v[208:211], v153 offset:54272
	ds_read_b128 v[212:215], v153 offset:55296
	ds_read_b128 v[216:219], v153 offset:56320
	s_branch .Lstg_21_3_j
.Lstg_21_3_b:
	s_add_i32 s28, s56, s35
	s_mov_b32 m0, s28
	ds_read_b128 v[184:187], v153 offset:49152
	ds_read_b128 v[188:191], v153 offset:50176
	ds_read_b128 v[192:195], v153 offset:51200
	ds_read_b128 v[196:199], v153 offset:52224
	ds_read_b128 v[200:203], v153 offset:53248
	ds_read_b128 v[208:211], v153 offset:54272
	ds_read_b128 v[212:215], v153 offset:55296
	ds_read_b128 v[216:219], v153 offset:56320
	global_load_lds_dwordx4 v220, s[26:27]
	s_add_i32 m0, s28, 0x2000
	s_add_u32 s26, s26, 0x40080
	s_addc_u32 s27, s27, 0
	s_add_i32 s28, s57, s35
	global_load_lds_dwordx4 v204, s[98:99]
	s_mov_b32 m0, s28
	s_nop 0
	global_load_lds_dwordx4 v132, s[26:27]
	s_add_i32 m0, s28, 0x2000
	s_nop 0
	global_load_lds_dwordx4 v128, s[26:27]
	s_cmp_lg_u32 s55, 12
	s_cbranch_scc1 .Lbal_last_21_b
	s_mov_b32 m0, s45
	s_nop 0
	global_load_lds_dwordx4 v221, s[100:101]
	s_mov_b32 m0, s46
	s_nop 0
	global_load_lds_dwordx4 v205, s[100:101]
.Lbal_last_21_b:
.Lstg_21_3_j:
	s_waitcnt vmcnt(6)
	s_waitcnt lgkmcnt(0)
	s_barrier
	s_waitcnt lgkmcnt(0)
	v_mfma_f32_16x16x32_bf16 v[60:63], v[144:147], v[184:187], v[60:63]
	v_mfma_f32_16x16x32_bf16 v[56:59], v[160:163], v[184:187], v[56:59]
	v_mfma_f32_16x16x32_bf16 v[44:47], v[144:147], v[192:195], v[44:47]
	v_mfma_f32_16x16x32_bf16 v[40:43], v[160:163], v[192:195], v[40:43]
	v_mfma_f32_16x16x32_bf16 v[28:31], v[144:147], v[200:203], v[28:31]
	v_mfma_f32_16x16x32_bf16 v[24:27], v[160:163], v[200:203], v[24:27]
	v_mfma_f32_16x16x32_bf16 v[12:15], v[144:147], v[212:215], v[12:15]
	v_mfma_f32_16x16x32_bf16 v[8:11], v[160:163], v[212:215], v[8:11]
	v_mfma_f32_16x16x32_bf16 v[60:63], v[156:159], v[188:191], v[60:63]
	v_mfma_f32_16x16x32_bf16 v[56:59], v[164:167], v[188:191], v[56:59]
	v_mfma_f32_16x16x32_bf16 v[44:47], v[156:159], v[196:199], v[44:47]
	v_mfma_f32_16x16x32_bf16 v[40:43], v[164:167], v[196:199], v[40:43]
	v_mfma_f32_16x16x32_bf16 v[28:31], v[156:159], v[208:211], v[28:31]
	v_mfma_f32_16x16x32_bf16 v[24:27], v[164:167], v[208:211], v[24:27]
	v_mfma_f32_16x16x32_bf16 v[12:15], v[156:159], v[216:219], v[12:15]
	v_mfma_f32_16x16x32_bf16 v[8:11], v[164:167], v[216:219], v[8:11]
	v_mfma_f32_16x16x32_bf16 v[52:55], v[168:171], v[184:187], v[52:55]
	v_mfma_f32_16x16x32_bf16 v[48:51], v[176:179], v[184:187], v[48:51]
	v_mfma_f32_16x16x32_bf16 v[36:39], v[168:171], v[192:195], v[36:39]
	v_mfma_f32_16x16x32_bf16 v[32:35], v[176:179], v[192:195], v[32:35]
	v_mfma_f32_16x16x32_bf16 v[20:23], v[168:171], v[200:203], v[20:23]
	v_mfma_f32_16x16x32_bf16 v[16:19], v[176:179], v[200:203], v[16:19]
	v_mfma_f32_16x16x32_bf16 v[4:7], v[168:171], v[212:215], v[4:7]
	v_mfma_f32_16x16x32_bf16 v[0:3], v[176:179], v[212:215], v[0:3]
	v_mfma_f32_16x16x32_bf16 v[52:55], v[172:175], v[188:191], v[52:55]
	v_mfma_f32_16x16x32_bf16 v[48:51], v[180:183], v[188:191], v[48:51]
	v_mfma_f32_16x16x32_bf16 v[36:39], v[172:175], v[196:199], v[36:39]
	v_mfma_f32_16x16x32_bf16 v[32:35], v[180:183], v[196:199], v[32:35]
	v_mfma_f32_16x16x32_bf16 v[20:23], v[172:175], v[208:211], v[20:23]
	v_mfma_f32_16x16x32_bf16 v[16:19], v[180:183], v[208:211], v[16:19]
	v_mfma_f32_16x16x32_bf16 v[4:7], v[172:175], v[216:219], v[4:7]
	v_mfma_f32_16x16x32_bf16 v[0:3], v[180:183], v[216:219], v[0:3]
	s_barrier
	s_add_i32 s55, s55, 2
	s_add_u32 s53, s53, 0x100
	s_addc_u32 s54, s54, 0
	s_add_u32 s24, s24, 0x100
	s_addc_u32 s25, s25, 0
	s_cmp_gt_u32 s55, 13
	s_cbranch_scc0 .LBB0_163
	s_setprio 0
	s_and_b64 vcc, exec, s[14:15]
	s_cbranch_vccz .LBB0_166
	s_barrier

.Lprio_skip_20:
	v_readfirstlane_b32 s101, v206
	s_nop 3
	s_lshr_b32 s101, s101, 6
	.p2align	3
	s_nop 0
.LBB0_606:
	s_bitcmp1_b32 s101, 0
	s_cbranch_scc1 .Lstg_20_0_b
	s_cmp_eq_i32 s58, -2
	s_cbranch_scc1 .Lbal_first_20
	s_mov_b32 m0, s49
	s_nop 0
	global_load_lds_dwordx4 v212, s[36:37]
	s_mov_b32 m0, s50
	s_nop 0
	global_load_lds_dwordx4 v213, s[36:37]
.Lbal_first_20:
	s_add_u32 s30, s28, 0x100
	s_addc_u32 s31, s29, 0
	s_cmp_eq_u32 s58, 12
	s_cselect_b32 s37, s21, s31
	s_cselect_b32 s36, s27, s30
	s_cselect_b32 s35, s19, s57
	s_cselect_b32 s34, s55, s56
	s_add_i32 m0, s44, 0xc000
	s_nop 0
	global_load_lds_dwordx4 v134, s[28:29]
	s_add_i32 m0, s44, 0xe000
	s_nop 0
	global_load_lds_dwordx4 v132, s[28:29]
	ds_read_b128 v[140:143], v147
	ds_read_b128 v[150:153], v147 offset:1024
	ds_read_b128 v[154:157], v147 offset:2048
	ds_read_b128 v[158:161], v147 offset:3072
	ds_read_b128 v[162:165], v148
	ds_read_b128 v[166:169], v148 offset:1024
	ds_read_b128 v[170:173], v148 offset:2048
	ds_read_b128 v[174:177], v148 offset:3072
	ds_read_b128 v[178:181], v149
	ds_read_b128 v[182:185], v149 offset:1024
	ds_read_b128 v[186:189], v149 offset:2048
	ds_read_b128 v[190:193], v149 offset:3072
	ds_read_b128 v[194:197], v149 offset:4096
	ds_read_b128 v[198:201], v149 offset:5120
	ds_read_b128 v[202:205], v149 offset:6144
	ds_read_b128 v[208:211], v149 offset:7168
	s_branch .Lstg_20_0_j

.Lbal_first_20_b:
	ds_read_b128 v[140:143], v147
	ds_read_b128 v[150:153], v147 offset:1024
	ds_read_b128 v[154:157], v147 offset:2048
	ds_read_b128 v[158:161], v147 offset:3072
	ds_read_b128 v[162:165], v148
	ds_read_b128 v[166:169], v148 offset:1024
	ds_read_b128 v[170:173], v148 offset:2048
	ds_read_b128 v[174:177], v148 offset:3072
	s_add_u32 s30, s28, 0x100
	s_addc_u32 s31, s29, 0
	s_cmp_eq_u32 s58, 12
	s_cselect_b32 s37, s21, s31
	s_cselect_b32 s36, s27, s30
	s_cselect_b32 s35, s19, s57
	s_cselect_b32 s34, s55, s56
	s_add_i32 m0, s44, 0xc000
	ds_read_b128 v[178:181], v149
	ds_read_b128 v[182:185], v149 offset:1024
	ds_read_b128 v[186:189], v149 offset:2048
	ds_read_b128 v[190:193], v149 offset:3072
	ds_read_b128 v[194:197], v149 offset:4096
	ds_read_b128 v[198:201], v149 offset:5120
	ds_read_b128 v[202:205], v149 offset:6144
	ds_read_b128 v[208:211], v149 offset:7168
	global_load_lds_dwordx4 v134, s[28:29]
	s_add_i32 m0, s44, 0xe000
	s_nop 0
	global_load_lds_dwordx4 v132, s[28:29]
.Lstg_20_0_j:
	s_waitcnt vmcnt(8)
	s_waitcnt lgkmcnt(0)
	s_barrier
	s_waitcnt lgkmcnt(0)
	v_mfma_f32_16x16x32_bf16 v[124:127], v[140:143], v[178:181], v[124:127]
	v_mfma_f32_16x16x32_bf16 v[120:123], v[154:157], v[178:181], v[120:123]
	v_mfma_f32_16x16x32_bf16 v[108:111], v[140:143], v[186:189], v[108:111]
	v_mfma_f32_16x16x32_bf16 v[104:107], v[154:157], v[186:189], v[104:107]
	v_mfma_f32_16x16x32_bf16 v[92:95], v[140:143], v[194:197], v[92:95]
	v_mfma_f32_16x16x32_bf16 v[88:91], v[154:157], v[194:197], v[88:91]
	v_mfma_f32_16x16x32_bf16 v[76:79], v[140:143], v[202:205], v[76:79]
	v_mfma_f32_16x16x32_bf16 v[72:75], v[154:157], v[202:205], v[72:75]
	v_mfma_f32_16x16x32_bf16 v[124:127], v[150:153], v[182:185], v[124:127]
	v_mfma_f32_16x16x32_bf16 v[120:123], v[158:161], v[182:185], v[120:123]
	v_mfma_f32_16x16x32_bf16 v[108:111], v[150:153], v[190:193], v[108:111]
	v_mfma_f32_16x16x32_bf16 v[104:107], v[158:161], v[190:193], v[104:107]
	v_mfma_f32_16x16x32_bf16 v[92:95], v[150:153], v[198:201], v[92:95]
	v_mfma_f32_16x16x32_bf16 v[88:91], v[158:161], v[198:201], v[88:91]
	v_mfma_f32_16x16x32_bf16 v[76:79], v[150:153], v[208:211], v[76:79]
	v_mfma_f32_16x16x32_bf16 v[72:75], v[158:161], v[208:211], v[72:75]
	v_mfma_f32_16x16x32_bf16 v[116:119], v[162:165], v[178:181], v[116:119]
	v_mfma_f32_16x16x32_bf16 v[112:115], v[170:173], v[178:181], v[112:115]
	v_mfma_f32_16x16x32_bf16 v[100:103], v[162:165], v[186:189], v[100:103]
	v_mfma_f32_16x16x32_bf16 v[96:99], v[170:173], v[186:189], v[96:99]
	v_mfma_f32_16x16x32_bf16 v[84:87], v[162:165], v[194:197], v[84:87]
	v_mfma_f32_16x16x32_bf16 v[80:83], v[170:173], v[194:197], v[80:83]
	v_mfma_f32_16x16x32_bf16 v[68:71], v[162:165], v[202:205], v[68:71]
	v_mfma_f32_16x16x32_bf16 v[64:67], v[170:173], v[202:205], v[64:67]
	v_mfma_f32_16x16x32_bf16 v[116:119], v[166:169], v[182:185], v[116:119]
	v_mfma_f32_16x16x32_bf16 v[112:115], v[174:177], v[182:185], v[112:115]
	v_mfma_f32_16x16x32_bf16 v[100:103], v[166:169], v[190:193], v[100:103]
	v_mfma_f32_16x16x32_bf16 v[96:99], v[174:177], v[190:193], v[96:99]
	v_mfma_f32_16x16x32_bf16 v[84:87], v[166:169], v[198:201], v[84:87]
	v_mfma_f32_16x16x32_bf16 v[80:83], v[174:177], v[198:201], v[80:83]
	v_mfma_f32_16x16x32_bf16 v[68:71], v[166:169], v[208:211], v[68:71]
	v_mfma_f32_16x16x32_bf16 v[64:67], v[174:177], v[208:211], v[64:67]
	s_barrier
	s_bitcmp1_b32 s101, 0
	s_cbranch_scc1 .Lstg_20_1_b
	s_add_i32 s28, s52, s43
	s_mov_b32 m0, s28
	s_nop 0
	global_load_lds_dwordx4 v128, s[34:35]
	s_add_i32 m0, s28, 0x2000
	s_add_u32 s28, s34, 0x40000
	s_mov_b64 s[98:99], s[34:35]
	s_addc_u32 s29, s35, 0
	s_add_i32 s59, s53, s43
	global_load_lds_dwordx4 v130, s[34:35]
	s_mov_b32 m0, s59
	s_nop 0
	global_load_lds_dwordx4 v128, s[28:29]
	s_add_i32 m0, s59, 0x2000
	s_nop 0
	global_load_lds_dwordx4 v130, s[28:29]
	ds_read_b128 v[178:181], v149 offset:16384
	ds_read_b128 v[182:185], v149 offset:17408
	ds_read_b128 v[186:189], v149 offset:18432
	ds_read_b128 v[190:193], v149 offset:19456
	ds_read_b128 v[194:197], v149 offset:20480
	ds_read_b128 v[198:201], v149 offset:21504
	ds_read_b128 v[202:205], v149 offset:22528
	ds_read_b128 v[208:211], v149 offset:23552
	s_branch .Lstg_20_1_j
.Lstg_20_1_b:
	s_add_i32 s28, s52, s43
	s_mov_b32 m0, s28
	ds_read_b128 v[178:181], v149 offset:16384
	ds_read_b128 v[182:185], v149 offset:17408
	ds_read_b128 v[186:189], v149 offset:18432
	ds_read_b128 v[190:193], v149 offset:19456
	ds_read_b128 v[194:197], v149 offset:20480
	ds_read_b128 v[198:201], v149 offset:21504
	ds_read_b128 v[202:205], v149 offset:22528
	ds_read_b128 v[208:211], v149 offset:23552
	global_load_lds_dwordx4 v128, s[34:35]
	s_add_i32 m0, s28, 0x2000
	s_add_u32 s28, s34, 0x40000
	s_mov_b64 s[98:99], s[34:35]
	s_addc_u32 s29, s35, 0
	s_add_i32 s59, s53, s43
	global_load_lds_dwordx4 v130, s[34:35]
	s_mov_b32 m0, s59
	s_nop 0
	global_load_lds_dwordx4 v128, s[28:29]
	s_add_i32 m0, s59, 0x2000
	s_nop 0
	global_load_lds_dwordx4 v130, s[28:29]
.Lstg_20_1_j:
	s_waitcnt vmcnt(6)
	s_waitcnt lgkmcnt(0)
	s_barrier
	s_waitcnt lgkmcnt(0)
	v_mfma_f32_16x16x32_bf16 v[60:63], v[140:143], v[178:181], v[60:63]
	v_mfma_f32_16x16x32_bf16 v[56:59], v[154:157], v[178:181], v[56:59]
	v_mfma_f32_16x16x32_bf16 v[44:47], v[140:143], v[186:189], v[44:47]
	v_mfma_f32_16x16x32_bf16 v[40:43], v[154:157], v[186:189], v[40:43]
	v_mfma_f32_16x16x32_bf16 v[28:31], v[140:143], v[194:197], v[28:31]
	v_mfma_f32_16x16x32_bf16 v[24:27], v[154:157], v[194:197], v[24:27]
	v_mfma_f32_16x16x32_bf16 v[12:15], v[140:143], v[202:205], v[12:15]
	v_mfma_f32_16x16x32_bf16 v[8:11], v[154:157], v[202:205], v[8:11]
	v_mfma_f32_16x16x32_bf16 v[60:63], v[150:153], v[182:185], v[60:63]
	v_mfma_f32_16x16x32_bf16 v[56:59], v[158:161], v[182:185], v[56:59]
	v_mfma_f32_16x16x32_bf16 v[44:47], v[150:153], v[190:193], v[44:47]
	v_mfma_f32_16x16x32_bf16 v[40:43], v[158:161], v[190:193], v[40:43]
	v_mfma_f32_16x16x32_bf16 v[28:31], v[150:153], v[198:201], v[28:31]
	v_mfma_f32_16x16x32_bf16 v[24:27], v[158:161], v[198:201], v[24:27]
	v_mfma_f32_16x16x32_bf16 v[12:15], v[150:153], v[208:211], v[12:15]
	v_mfma_f32_16x16x32_bf16 v[8:11], v[158:161], v[208:211], v[8:11]
	v_mfma_f32_16x16x32_bf16 v[52:55], v[162:165], v[178:181], v[52:55]
	v_mfma_f32_16x16x32_bf16 v[48:51], v[170:173], v[178:181], v[48:51]
	v_mfma_f32_16x16x32_bf16 v[36:39], v[162:165], v[186:189], v[36:39]
	v_mfma_f32_16x16x32_bf16 v[32:35], v[170:173], v[186:189], v[32:35]
	v_mfma_f32_16x16x32_bf16 v[20:23], v[162:165], v[194:197], v[20:23]
	v_mfma_f32_16x16x32_bf16 v[16:19], v[170:173], v[194:197], v[16:19]
	v_mfma_f32_16x16x32_bf16 v[4:7], v[162:165], v[202:205], v[4:7]
	v_mfma_f32_16x16x32_bf16 v[0:3], v[170:173], v[202:205], v[0:3]
	v_mfma_f32_16x16x32_bf16 v[52:55], v[166:169], v[182:185], v[52:55]
	v_mfma_f32_16x16x32_bf16 v[48:51], v[174:177], v[182:185], v[48:51]
	v_mfma_f32_16x16x32_bf16 v[36:39], v[166:169], v[190:193], v[36:39]
	v_mfma_f32_16x16x32_bf16 v[32:35], v[174:177], v[190:193], v[32:35]
	v_mfma_f32_16x16x32_bf16 v[20:23], v[166:169], v[198:201], v[20:23]
	v_mfma_f32_16x16x32_bf16 v[16:19], v[174:177], v[198:201], v[16:19]
	v_mfma_f32_16x16x32_bf16 v[4:7], v[166:169], v[208:211], v[4:7]
	v_mfma_f32_16x16x32_bf16 v[0:3], v[174:177], v[208:211], v[0:3]
	s_barrier
	s_bitcmp1_b32 s101, 0
	s_cbranch_scc1 .Lstg_20_2_b
	s_mov_b32 m0, s44
	s_nop 0
	global_load_lds_dwordx4 v128, s[36:37]
	s_mov_b32 m0, s45
	s_nop 0
	global_load_lds_dwordx4 v130, s[36:37]
	s_add_i32 s59, 0, 0x18000
	s_add_i32 s60, 0, 0x1c000
	s_add_u32 s28, s36, 0x40000
	s_addc_u32 s29, s37, 0
	s_mov_b32 m0, s46
	s_nop 0
	global_load_lds_dwordx4 v128, s[28:29]
	s_mov_b32 m0, s47
	s_nop 0
	global_load_lds_dwordx4 v130, s[28:29]
	v_add_u32_e32 v158, s59, v145
	v_add_u32_e32 v174, s60, v145
	ds_read_b128 v[140:143], v158
	ds_read_b128 v[150:153], v158 offset:1024
	ds_read_b128 v[154:157], v158 offset:2048
	ds_read_b128 v[158:161], v158 offset:3072
	ds_read_b128 v[162:165], v174
	ds_read_b128 v[166:169], v174 offset:1024
	ds_read_b128 v[170:173], v174 offset:2048
	ds_read_b128 v[174:177], v174 offset:3072
	ds_read_b128 v[178:181], v149 offset:32768
	ds_read_b128 v[182:185], v149 offset:33792
	ds_read_b128 v[186:189], v149 offset:34816
	ds_read_b128 v[190:193], v149 offset:35840
	ds_read_b128 v[194:197], v149 offset:36864
	ds_read_b128 v[198:201], v149 offset:37888
	ds_read_b128 v[202:205], v149 offset:38912
	ds_read_b128 v[208:211], v149 offset:39936
	s_branch .Lstg_20_2_j
.Lstg_20_2_b:
	s_mov_b32 m0, s44
	s_nop 0
	global_load_lds_dwordx4 v128, s[36:37]
	s_mov_b32 m0, s45
	s_nop 0
	global_load_lds_dwordx4 v130, s[36:37]
	s_add_i32 s59, 0, 0x18000
	s_add_i32 s60, 0, 0x1c000
	v_add_u32_e32 v158, s59, v145
	v_add_u32_e32 v174, s60, v145
	ds_read_b128 v[140:143], v158
	ds_read_b128 v[150:153], v158 offset:1024
	ds_read_b128 v[154:157], v158 offset:2048
	ds_read_b128 v[158:161], v158 offset:3072
	ds_read_b128 v[162:165], v174
	ds_read_b128 v[166:169], v174 offset:1024
	ds_read_b128 v[170:173], v174 offset:2048
	ds_read_b128 v[174:177], v174 offset:3072
	s_add_u32 s28, s36, 0x40000
	s_addc_u32 s29, s37, 0
	s_mov_b32 m0, s46
	ds_read_b128 v[178:181], v149 offset:32768
	ds_read_b128 v[182:185], v149 offset:33792
	ds_read_b128 v[186:189], v149 offset:34816
	ds_read_b128 v[190:193], v149 offset:35840
	ds_read_b128 v[194:197], v149 offset:36864
	ds_read_b128 v[198:201], v149 offset:37888
	ds_read_b128 v[202:205], v149 offset:38912
	ds_read_b128 v[208:211], v149 offset:39936
	global_load_lds_dwordx4 v128, s[28:29]
	s_mov_b32 m0, s47
	s_nop 0
	global_load_lds_dwordx4 v130, s[28:29]
.Lstg_20_2_j:
	s_waitcnt vmcnt(8)
	s_waitcnt lgkmcnt(0)
	s_barrier
	s_waitcnt lgkmcnt(0)
	v_mfma_f32_16x16x32_bf16 v[124:127], v[140:143], v[178:181], v[124:127]
	v_mfma_f32_16x16x32_bf16 v[120:123], v[154:157], v[178:181], v[120:123]
	v_mfma_f32_16x16x32_bf16 v[108:111], v[140:143], v[186:189], v[108:111]
	v_mfma_f32_16x16x32_bf16 v[104:107], v[154:157], v[186:189], v[104:107]
	v_mfma_f32_16x16x32_bf16 v[92:95], v[140:143], v[194:197], v[92:95]
	v_mfma_f32_16x16x32_bf16 v[88:91], v[154:157], v[194:197], v[88:91]
	v_mfma_f32_16x16x32_bf16 v[76:79], v[140:143], v[202:205], v[76:79]
	v_mfma_f32_16x16x32_bf16 v[72:75], v[154:157], v[202:205], v[72:75]
	v_mfma_f32_16x16x32_bf16 v[124:127], v[150:153], v[182:185], v[124:127]
	v_mfma_f32_16x16x32_bf16 v[120:123], v[158:161], v[182:185], v[120:123]
	v_mfma_f32_16x16x32_bf16 v[108:111], v[150:153], v[190:193], v[108:111]
	v_mfma_f32_16x16x32_bf16 v[104:107], v[158:161], v[190:193], v[104:107]
	v_mfma_f32_16x16x32_bf16 v[92:95], v[150:153], v[198:201], v[92:95]
	v_mfma_f32_16x16x32_bf16 v[88:91], v[158:161], v[198:201], v[88:91]
	v_mfma_f32_16x16x32_bf16 v[76:79], v[150:153], v[208:211], v[76:79]
	v_mfma_f32_16x16x32_bf16 v[72:75], v[158:161], v[208:211], v[72:75]
	v_mfma_f32_16x16x32_bf16 v[116:119], v[162:165], v[178:181], v[116:119]
	v_mfma_f32_16x16x32_bf16 v[112:115], v[170:173], v[178:181], v[112:115]
	v_mfma_f32_16x16x32_bf16 v[100:103], v[162:165], v[186:189], v[100:103]
	v_mfma_f32_16x16x32_bf16 v[96:99], v[170:173], v[186:189], v[96:99]
	v_mfma_f32_16x16x32_bf16 v[84:87], v[162:165], v[194:197], v[84:87]
	v_mfma_f32_16x16x32_bf16 v[80:83], v[170:173], v[194:197], v[80:83]
	v_mfma_f32_16x16x32_bf16 v[68:71], v[162:165], v[202:205], v[68:71]
	v_mfma_f32_16x16x32_bf16 v[64:67], v[170:173], v[202:205], v[64:67]
	v_mfma_f32_16x16x32_bf16 v[116:119], v[166:169], v[182:185], v[116:119]
	v_mfma_f32_16x16x32_bf16 v[112:115], v[174:177], v[182:185], v[112:115]
	v_mfma_f32_16x16x32_bf16 v[100:103], v[166:169], v[190:193], v[100:103]
	v_mfma_f32_16x16x32_bf16 v[96:99], v[174:177], v[190:193], v[96:99]
	v_mfma_f32_16x16x32_bf16 v[84:87], v[166:169], v[198:201], v[84:87]
	v_mfma_f32_16x16x32_bf16 v[80:83], v[174:177], v[198:201], v[80:83]
	v_mfma_f32_16x16x32_bf16 v[68:71], v[166:169], v[208:211], v[68:71]
	v_mfma_f32_16x16x32_bf16 v[64:67], v[174:177], v[208:211], v[64:67]
	s_barrier
	s_bitcmp1_b32 s101, 0
	s_cbranch_scc1 .Lstg_20_3_b
	s_add_i32 s28, s59, s43
	s_mov_b32 m0, s28
	s_nop 0
	global_load_lds_dwordx4 v212, s[34:35]
	s_add_i32 m0, s28, 0x2000
	s_add_u32 s28, s34, 0x40080
	s_addc_u32 s29, s35, 0
	s_add_i32 s34, s60, s43
	global_load_lds_dwordx4 v213, s[98:99]
	s_mov_b32 m0, s34
	s_nop 0
	global_load_lds_dwordx4 v128, s[28:29]
	s_add_i32 m0, s34, 0x2000
	s_nop 0
	global_load_lds_dwordx4 v130, s[28:29]
	s_cmp_lg_u32 s58, 12
	s_cbranch_scc1 .Lbal_last_20
	s_mov_b32 m0, s49
	s_nop 0
	global_load_lds_dwordx4 v212, s[36:37]
	s_mov_b32 m0, s50
	s_nop 0
	global_load_lds_dwordx4 v213, s[36:37]
.Lbal_last_20:
	ds_read_b128 v[178:181], v149 offset:49152
	ds_read_b128 v[182:185], v149 offset:50176
	ds_read_b128 v[186:189], v149 offset:51200
	ds_read_b128 v[190:193], v149 offset:52224
	ds_read_b128 v[194:197], v149 offset:53248
	ds_read_b128 v[198:201], v149 offset:54272
	ds_read_b128 v[202:205], v149 offset:55296
	ds_read_b128 v[208:211], v149 offset:56320
	s_branch .Lstg_20_3_j
.Lstg_20_3_b:
	s_add_i32 s28, s59, s43
	s_mov_b32 m0, s28
	ds_read_b128 v[178:181], v149 offset:49152
	ds_read_b128 v[182:185], v149 offset:50176
	ds_read_b128 v[186:189], v149 offset:51200
	ds_read_b128 v[190:193], v149 offset:52224
	ds_read_b128 v[194:197], v149 offset:53248
	ds_read_b128 v[198:201], v149 offset:54272
	ds_read_b128 v[202:205], v149 offset:55296
	ds_read_b128 v[208:211], v149 offset:56320
	global_load_lds_dwordx4 v212, s[34:35]
	s_add_i32 m0, s28, 0x2000
	s_add_u32 s28, s34, 0x40080
	s_addc_u32 s29, s35, 0
	s_add_i32 s34, s60, s43
	global_load_lds_dwordx4 v213, s[98:99]
	s_mov_b32 m0, s34
	s_nop 0
	global_load_lds_dwordx4 v128, s[28:29]
	s_add_i32 m0, s34, 0x2000
	s_nop 0
	global_load_lds_dwordx4 v130, s[28:29]
	s_cmp_lg_u32 s58, 12
	s_cbranch_scc1 .Lbal_last_20_b
	s_mov_b32 m0, s49
	s_nop 0
	global_load_lds_dwordx4 v212, s[36:37]
	s_mov_b32 m0, s50
	s_nop 0
	global_load_lds_dwordx4 v213, s[36:37]
.Lbal_last_20_b:
.Lstg_20_3_j:
	s_waitcnt vmcnt(6)
	s_waitcnt lgkmcnt(0)
	s_barrier
	s_waitcnt lgkmcnt(0)
	v_mfma_f32_16x16x32_bf16 v[60:63], v[140:143], v[178:181], v[60:63]
	v_mfma_f32_16x16x32_bf16 v[56:59], v[154:157], v[178:181], v[56:59]
	v_mfma_f32_16x16x32_bf16 v[44:47], v[140:143], v[186:189], v[44:47]
	v_mfma_f32_16x16x32_bf16 v[40:43], v[154:157], v[186:189], v[40:43]
	v_mfma_f32_16x16x32_bf16 v[28:31], v[140:143], v[194:197], v[28:31]
	v_mfma_f32_16x16x32_bf16 v[24:27], v[154:157], v[194:197], v[24:27]
	v_mfma_f32_16x16x32_bf16 v[12:15], v[140:143], v[202:205], v[12:15]
	v_mfma_f32_16x16x32_bf16 v[8:11], v[154:157], v[202:205], v[8:11]
	v_mfma_f32_16x16x32_bf16 v[60:63], v[150:153], v[182:185], v[60:63]
	v_mfma_f32_16x16x32_bf16 v[56:59], v[158:161], v[182:185], v[56:59]
	v_mfma_f32_16x16x32_bf16 v[44:47], v[150:153], v[190:193], v[44:47]
	v_mfma_f32_16x16x32_bf16 v[40:43], v[158:161], v[190:193], v[40:43]
	v_mfma_f32_16x16x32_bf16 v[28:31], v[150:153], v[198:201], v[28:31]
	v_mfma_f32_16x16x32_bf16 v[24:27], v[158:161], v[198:201], v[24:27]
	v_mfma_f32_16x16x32_bf16 v[12:15], v[150:153], v[208:211], v[12:15]
	v_mfma_f32_16x16x32_bf16 v[8:11], v[158:161], v[208:211], v[8:11]
	v_mfma_f32_16x16x32_bf16 v[52:55], v[162:165], v[178:181], v[52:55]
	v_mfma_f32_16x16x32_bf16 v[48:51], v[170:173], v[178:181], v[48:51]
	v_mfma_f32_16x16x32_bf16 v[36:39], v[162:165], v[186:189], v[36:39]
	v_mfma_f32_16x16x32_bf16 v[32:35], v[170:173], v[186:189], v[32:35]
	v_mfma_f32_16x16x32_bf16 v[20:23], v[162:165], v[194:197], v[20:23]
	v_mfma_f32_16x16x32_bf16 v[16:19], v[170:173], v[194:197], v[16:19]
	v_mfma_f32_16x16x32_bf16 v[4:7], v[162:165], v[202:205], v[4:7]
	v_mfma_f32_16x16x32_bf16 v[0:3], v[170:173], v[202:205], v[0:3]
	v_mfma_f32_16x16x32_bf16 v[52:55], v[166:169], v[182:185], v[52:55]
	v_mfma_f32_16x16x32_bf16 v[48:51], v[174:177], v[182:185], v[48:51]
	v_mfma_f32_16x16x32_bf16 v[36:39], v[166:169], v[190:193], v[36:39]
	v_mfma_f32_16x16x32_bf16 v[32:35], v[174:177], v[190:193], v[32:35]
	v_mfma_f32_16x16x32_bf16 v[20:23], v[166:169], v[198:201], v[20:23]
	v_mfma_f32_16x16x32_bf16 v[16:19], v[174:177], v[198:201], v[16:19]
	v_mfma_f32_16x16x32_bf16 v[4:7], v[166:169], v[208:211], v[4:7]
	v_mfma_f32_16x16x32_bf16 v[0:3], v[174:177], v[208:211], v[0:3]
	s_barrier
	s_add_i32 s58, s58, 2
	s_add_u32 s56, s56, 0x100
	s_addc_u32 s57, s57, 0
	s_cmp_gt_u32 s58, 13
	s_mov_b64 s[28:29], s[30:31]
	s_cbranch_scc0 .LBB0_606
	s_setprio 0
	s_and_b64 vcc, exec, s[16:17]
	s_cbranch_vccz .LBB0_609
	s_barrier

.LBB0_699:
	s_bitcmp1_b32 s97, 0
	s_cbranch_scc1 .Lstg_19_0_b
	s_cmp_eq_i32 s53, -2
	s_cbranch_scc1 .Lbal_first_19
	s_mov_b32 m0, s44
	s_nop 0
	global_load_lds_dwordx4 v204, s[100:101]
	s_mov_b32 m0, s45
	s_nop 0
	global_load_lds_dwordx4 v220, s[100:101]
.Lbal_first_19:
	s_add_u32 s28, s26, 0xfffc0080
	s_addc_u32 s29, s27, -1
	s_cmp_eq_u32 s53, 12
	s_cselect_b32 s31, s21, s29
	s_cselect_b32 s30, s49, s28
	s_cselect_b32 s29, s19, s52
	s_cselect_b32 s28, s50, s51
	s_add_i32 m0, s39, 0xc000
	s_nop 0
	global_load_lds_dwordx4 v138, s[26:27]
	s_add_i32 m0, s39, 0xe000
	s_nop 0
	global_load_lds_dwordx4 v136, s[26:27]
	ds_read_b128 v[144:147], v151
	ds_read_b128 v[156:159], v151 offset:1024
	ds_read_b128 v[160:163], v151 offset:2048
	ds_read_b128 v[164:167], v151 offset:3072
	ds_read_b128 v[168:171], v152
	ds_read_b128 v[172:175], v152 offset:1024
	ds_read_b128 v[176:179], v152 offset:2048
	ds_read_b128 v[180:183], v152 offset:3072
	ds_read_b128 v[184:187], v153
	ds_read_b128 v[188:191], v153 offset:1024
	ds_read_b128 v[192:195], v153 offset:2048
	ds_read_b128 v[196:199], v153 offset:3072
	ds_read_b128 v[200:203], v153 offset:4096
	ds_read_b128 v[208:211], v153 offset:5120
	ds_read_b128 v[212:215], v153 offset:6144
	ds_read_b128 v[216:219], v153 offset:7168
	s_branch .Lstg_19_0_j

.Lbal_first_19_b:
	ds_read_b128 v[144:147], v151
	ds_read_b128 v[156:159], v151 offset:1024
	ds_read_b128 v[160:163], v151 offset:2048
	ds_read_b128 v[164:167], v151 offset:3072
	ds_read_b128 v[168:171], v152
	ds_read_b128 v[172:175], v152 offset:1024
	ds_read_b128 v[176:179], v152 offset:2048
	ds_read_b128 v[180:183], v152 offset:3072
	s_add_u32 s28, s26, 0xfffc0080
	s_addc_u32 s29, s27, -1
	s_cmp_eq_u32 s53, 12
	s_cselect_b32 s31, s21, s29
	s_cselect_b32 s30, s49, s28
	s_cselect_b32 s29, s19, s52
	s_cselect_b32 s28, s50, s51
	s_add_i32 m0, s39, 0xc000
	ds_read_b128 v[184:187], v153
	ds_read_b128 v[188:191], v153 offset:1024
	ds_read_b128 v[192:195], v153 offset:2048
	ds_read_b128 v[196:199], v153 offset:3072
	ds_read_b128 v[200:203], v153 offset:4096
	ds_read_b128 v[208:211], v153 offset:5120
	ds_read_b128 v[212:215], v153 offset:6144
	ds_read_b128 v[216:219], v153 offset:7168
	global_load_lds_dwordx4 v138, s[26:27]
	s_add_i32 m0, s39, 0xe000
	s_nop 0
	global_load_lds_dwordx4 v136, s[26:27]
.Lstg_19_0_j:
	s_waitcnt vmcnt(8)
	s_waitcnt lgkmcnt(0)
	s_barrier
	s_waitcnt lgkmcnt(0)
	v_mfma_f32_16x16x32_bf16 v[124:127], v[144:147], v[184:187], v[124:127]
	v_mfma_f32_16x16x32_bf16 v[120:123], v[160:163], v[184:187], v[120:123]
	v_mfma_f32_16x16x32_bf16 v[108:111], v[144:147], v[192:195], v[108:111]
	v_mfma_f32_16x16x32_bf16 v[104:107], v[160:163], v[192:195], v[104:107]
	v_mfma_f32_16x16x32_bf16 v[92:95], v[144:147], v[200:203], v[92:95]
	v_mfma_f32_16x16x32_bf16 v[88:91], v[160:163], v[200:203], v[88:91]
	v_mfma_f32_16x16x32_bf16 v[76:79], v[144:147], v[212:215], v[76:79]
	v_mfma_f32_16x16x32_bf16 v[72:75], v[160:163], v[212:215], v[72:75]
	v_mfma_f32_16x16x32_bf16 v[124:127], v[156:159], v[188:191], v[124:127]
	v_mfma_f32_16x16x32_bf16 v[120:123], v[164:167], v[188:191], v[120:123]
	v_mfma_f32_16x16x32_bf16 v[108:111], v[156:159], v[196:199], v[108:111]
	v_mfma_f32_16x16x32_bf16 v[104:107], v[164:167], v[196:199], v[104:107]
	v_mfma_f32_16x16x32_bf16 v[92:95], v[156:159], v[208:211], v[92:95]
	v_mfma_f32_16x16x32_bf16 v[88:91], v[164:167], v[208:211], v[88:91]
	v_mfma_f32_16x16x32_bf16 v[76:79], v[156:159], v[216:219], v[76:79]
	v_mfma_f32_16x16x32_bf16 v[72:75], v[164:167], v[216:219], v[72:75]
	v_mfma_f32_16x16x32_bf16 v[116:119], v[168:171], v[184:187], v[116:119]
	v_mfma_f32_16x16x32_bf16 v[112:115], v[176:179], v[184:187], v[112:115]
	v_mfma_f32_16x16x32_bf16 v[100:103], v[168:171], v[192:195], v[100:103]
	v_mfma_f32_16x16x32_bf16 v[96:99], v[176:179], v[192:195], v[96:99]
	v_mfma_f32_16x16x32_bf16 v[84:87], v[168:171], v[200:203], v[84:87]
	v_mfma_f32_16x16x32_bf16 v[80:83], v[176:179], v[200:203], v[80:83]
	v_mfma_f32_16x16x32_bf16 v[68:71], v[168:171], v[212:215], v[68:71]
	v_mfma_f32_16x16x32_bf16 v[64:67], v[176:179], v[212:215], v[64:67]
	v_mfma_f32_16x16x32_bf16 v[116:119], v[172:175], v[188:191], v[116:119]
	v_mfma_f32_16x16x32_bf16 v[112:115], v[180:183], v[188:191], v[112:115]
	v_mfma_f32_16x16x32_bf16 v[100:103], v[172:175], v[196:199], v[100:103]
	v_mfma_f32_16x16x32_bf16 v[96:99], v[180:183], v[196:199], v[96:99]
	v_mfma_f32_16x16x32_bf16 v[84:87], v[172:175], v[208:211], v[84:87]
	v_mfma_f32_16x16x32_bf16 v[80:83], v[180:183], v[208:211], v[80:83]
	v_mfma_f32_16x16x32_bf16 v[68:71], v[172:175], v[216:219], v[68:71]
	v_mfma_f32_16x16x32_bf16 v[64:67], v[180:183], v[216:219], v[64:67]
	s_barrier
	s_bitcmp1_b32 s97, 0
	s_cbranch_scc1 .Lstg_19_1_b
	s_add_i32 s54, s46, s38
	s_mov_b32 m0, s54
	s_nop 0
	global_load_lds_dwordx4 v130, s[28:29]
	s_add_i32 m0, s54, 0x2000
	s_add_u32 s54, s28, 0x40000
	s_mov_b64 s[98:99], s[28:29]
	s_addc_u32 s55, s29, 0
	s_add_i32 s56, s47, s38
	global_load_lds_dwordx4 v134, s[28:29]
	s_mov_b32 m0, s56
	s_mov_b64 s[100:101], s[30:31]
	global_load_lds_dwordx4 v130, s[54:55]
	s_add_i32 m0, s56, 0x2000
	s_nop 0
	global_load_lds_dwordx4 v134, s[54:55]
	ds_read_b128 v[184:187], v153 offset:16384
	ds_read_b128 v[188:191], v153 offset:17408
	ds_read_b128 v[192:195], v153 offset:18432
	ds_read_b128 v[196:199], v153 offset:19456
	ds_read_b128 v[200:203], v153 offset:20480
	ds_read_b128 v[208:211], v153 offset:21504
	ds_read_b128 v[212:215], v153 offset:22528
	ds_read_b128 v[216:219], v153 offset:23552
	s_branch .Lstg_19_1_j
.Lstg_19_1_b:
	s_add_i32 s54, s46, s38
	s_mov_b32 m0, s54
	ds_read_b128 v[184:187], v153 offset:16384
	ds_read_b128 v[188:191], v153 offset:17408
	ds_read_b128 v[192:195], v153 offset:18432
	ds_read_b128 v[196:199], v153 offset:19456
	ds_read_b128 v[200:203], v153 offset:20480
	ds_read_b128 v[208:211], v153 offset:21504
	ds_read_b128 v[212:215], v153 offset:22528
	ds_read_b128 v[216:219], v153 offset:23552
	global_load_lds_dwordx4 v130, s[28:29]
	s_add_i32 m0, s54, 0x2000
	s_add_u32 s54, s28, 0x40000
	s_mov_b64 s[98:99], s[28:29]
	s_addc_u32 s55, s29, 0
	s_add_i32 s56, s47, s38
	global_load_lds_dwordx4 v134, s[28:29]
	s_mov_b32 m0, s56
	s_mov_b64 s[100:101], s[30:31]
	global_load_lds_dwordx4 v130, s[54:55]
	s_add_i32 m0, s56, 0x2000
	s_nop 0
	global_load_lds_dwordx4 v134, s[54:55]
.Lstg_19_1_j:
	s_waitcnt vmcnt(6)
	s_waitcnt lgkmcnt(0)
	s_barrier
	s_waitcnt lgkmcnt(0)
	v_mfma_f32_16x16x32_bf16 v[60:63], v[144:147], v[184:187], v[60:63]
	v_mfma_f32_16x16x32_bf16 v[56:59], v[160:163], v[184:187], v[56:59]
	v_mfma_f32_16x16x32_bf16 v[44:47], v[144:147], v[192:195], v[44:47]
	v_mfma_f32_16x16x32_bf16 v[40:43], v[160:163], v[192:195], v[40:43]
	v_mfma_f32_16x16x32_bf16 v[28:31], v[144:147], v[200:203], v[28:31]
	v_mfma_f32_16x16x32_bf16 v[24:27], v[160:163], v[200:203], v[24:27]
	v_mfma_f32_16x16x32_bf16 v[12:15], v[144:147], v[212:215], v[12:15]
	v_mfma_f32_16x16x32_bf16 v[8:11], v[160:163], v[212:215], v[8:11]
	v_mfma_f32_16x16x32_bf16 v[60:63], v[156:159], v[188:191], v[60:63]
	v_mfma_f32_16x16x32_bf16 v[56:59], v[164:167], v[188:191], v[56:59]
	v_mfma_f32_16x16x32_bf16 v[44:47], v[156:159], v[196:199], v[44:47]
	v_mfma_f32_16x16x32_bf16 v[40:43], v[164:167], v[196:199], v[40:43]
	v_mfma_f32_16x16x32_bf16 v[28:31], v[156:159], v[208:211], v[28:31]
	v_mfma_f32_16x16x32_bf16 v[24:27], v[164:167], v[208:211], v[24:27]
	v_mfma_f32_16x16x32_bf16 v[12:15], v[156:159], v[216:219], v[12:15]
	v_mfma_f32_16x16x32_bf16 v[8:11], v[164:167], v[216:219], v[8:11]
	v_mfma_f32_16x16x32_bf16 v[52:55], v[168:171], v[184:187], v[52:55]
	v_mfma_f32_16x16x32_bf16 v[48:51], v[176:179], v[184:187], v[48:51]
	v_mfma_f32_16x16x32_bf16 v[36:39], v[168:171], v[192:195], v[36:39]
	v_mfma_f32_16x16x32_bf16 v[32:35], v[176:179], v[192:195], v[32:35]
	v_mfma_f32_16x16x32_bf16 v[20:23], v[168:171], v[200:203], v[20:23]
	v_mfma_f32_16x16x32_bf16 v[16:19], v[176:179], v[200:203], v[16:19]
	v_mfma_f32_16x16x32_bf16 v[4:7], v[168:171], v[212:215], v[4:7]
	v_mfma_f32_16x16x32_bf16 v[0:3], v[176:179], v[212:215], v[0:3]
	v_mfma_f32_16x16x32_bf16 v[52:55], v[172:175], v[188:191], v[52:55]
	v_mfma_f32_16x16x32_bf16 v[48:51], v[180:183], v[188:191], v[48:51]
	v_mfma_f32_16x16x32_bf16 v[36:39], v[172:175], v[196:199], v[36:39]
	v_mfma_f32_16x16x32_bf16 v[32:35], v[180:183], v[196:199], v[32:35]
	v_mfma_f32_16x16x32_bf16 v[20:23], v[172:175], v[208:211], v[20:23]
	v_mfma_f32_16x16x32_bf16 v[16:19], v[180:183], v[208:211], v[16:19]
	v_mfma_f32_16x16x32_bf16 v[4:7], v[172:175], v[216:219], v[4:7]
	v_mfma_f32_16x16x32_bf16 v[0:3], v[180:183], v[216:219], v[0:3]
	s_barrier
	s_bitcmp1_b32 s97, 0
	s_cbranch_scc1 .Lstg_19_2_b
	s_mov_b32 m0, s39
	s_nop 0
	global_load_lds_dwordx4 v128, s[30:31]
	s_mov_b32 m0, s40
	s_nop 0
	global_load_lds_dwordx4 v132, s[30:31]
	s_add_i32 s54, 0, 0x18000
	s_add_i32 s55, 0, 0x1c000
	s_add_u32 s30, s30, 0x40000
	s_addc_u32 s31, s31, 0
	s_mov_b32 m0, s41
	s_nop 0
	global_load_lds_dwordx4 v128, s[30:31]
	s_mov_b32 m0, s42
	s_nop 0
	global_load_lds_dwordx4 v132, s[30:31]
	v_add_u32_e32 v155, s54, v149
	ds_read_b128 v[144:147], v155
	ds_read_b128 v[156:159], v155 offset:1024
	ds_read_b128 v[160:163], v155 offset:2048
	ds_read_b128 v[164:167], v155 offset:3072
	v_add_u32_e32 v155, s55, v149
	ds_read_b128 v[168:171], v155
	ds_read_b128 v[172:175], v155 offset:1024
	ds_read_b128 v[176:179], v155 offset:2048
	ds_read_b128 v[180:183], v155 offset:3072
	ds_read_b128 v[184:187], v153 offset:32768
	ds_read_b128 v[188:191], v153 offset:33792
	ds_read_b128 v[192:195], v153 offset:34816
	ds_read_b128 v[196:199], v153 offset:35840
	ds_read_b128 v[200:203], v153 offset:36864
	ds_read_b128 v[208:211], v153 offset:37888
	ds_read_b128 v[212:215], v153 offset:38912
	ds_read_b128 v[216:219], v153 offset:39936
	s_branch .Lstg_19_2_j
.Lstg_19_2_b:
	s_mov_b32 m0, s39
	s_nop 0
	global_load_lds_dwordx4 v128, s[30:31]
	s_mov_b32 m0, s40
	s_nop 0
	global_load_lds_dwordx4 v132, s[30:31]
	s_add_i32 s54, 0, 0x18000
	v_add_u32_e32 v155, s54, v149
	s_add_i32 s55, 0, 0x1c000
	ds_read_b128 v[144:147], v155
	ds_read_b128 v[156:159], v155 offset:1024
	ds_read_b128 v[160:163], v155 offset:2048
	ds_read_b128 v[164:167], v155 offset:3072
	v_add_u32_e32 v155, s55, v149
	ds_read_b128 v[168:171], v155
	ds_read_b128 v[172:175], v155 offset:1024
	ds_read_b128 v[176:179], v155 offset:2048
	ds_read_b128 v[180:183], v155 offset:3072
	s_add_u32 s30, s30, 0x40000
	s_addc_u32 s31, s31, 0
	s_mov_b32 m0, s41
	ds_read_b128 v[184:187], v153 offset:32768
	ds_read_b128 v[188:191], v153 offset:33792
	ds_read_b128 v[192:195], v153 offset:34816
	ds_read_b128 v[196:199], v153 offset:35840
	ds_read_b128 v[200:203], v153 offset:36864
	ds_read_b128 v[208:211], v153 offset:37888
	ds_read_b128 v[212:215], v153 offset:38912
	ds_read_b128 v[216:219], v153 offset:39936
	global_load_lds_dwordx4 v128, s[30:31]
	s_mov_b32 m0, s42
	s_nop 0
	global_load_lds_dwordx4 v132, s[30:31]
.Lstg_19_2_j:
	s_waitcnt vmcnt(8)
	s_waitcnt lgkmcnt(0)
	s_barrier
	s_waitcnt lgkmcnt(0)
	v_mfma_f32_16x16x32_bf16 v[124:127], v[144:147], v[184:187], v[124:127]
	v_mfma_f32_16x16x32_bf16 v[120:123], v[160:163], v[184:187], v[120:123]
	v_mfma_f32_16x16x32_bf16 v[108:111], v[144:147], v[192:195], v[108:111]
	v_mfma_f32_16x16x32_bf16 v[104:107], v[160:163], v[192:195], v[104:107]
	v_mfma_f32_16x16x32_bf16 v[92:95], v[144:147], v[200:203], v[92:95]
	v_mfma_f32_16x16x32_bf16 v[88:91], v[160:163], v[200:203], v[88:91]
	v_mfma_f32_16x16x32_bf16 v[76:79], v[144:147], v[212:215], v[76:79]
	v_mfma_f32_16x16x32_bf16 v[72:75], v[160:163], v[212:215], v[72:75]
	v_mfma_f32_16x16x32_bf16 v[124:127], v[156:159], v[188:191], v[124:127]
	v_mfma_f32_16x16x32_bf16 v[120:123], v[164:167], v[188:191], v[120:123]
	v_mfma_f32_16x16x32_bf16 v[108:111], v[156:159], v[196:199], v[108:111]
	v_mfma_f32_16x16x32_bf16 v[104:107], v[164:167], v[196:199], v[104:107]
	v_mfma_f32_16x16x32_bf16 v[92:95], v[156:159], v[208:211], v[92:95]
	v_mfma_f32_16x16x32_bf16 v[88:91], v[164:167], v[208:211], v[88:91]
	v_mfma_f32_16x16x32_bf16 v[76:79], v[156:159], v[216:219], v[76:79]
	v_mfma_f32_16x16x32_bf16 v[72:75], v[164:167], v[216:219], v[72:75]
	v_mfma_f32_16x16x32_bf16 v[116:119], v[168:171], v[184:187], v[116:119]
	v_mfma_f32_16x16x32_bf16 v[112:115], v[176:179], v[184:187], v[112:115]
	v_mfma_f32_16x16x32_bf16 v[100:103], v[168:171], v[192:195], v[100:103]
	v_mfma_f32_16x16x32_bf16 v[96:99], v[176:179], v[192:195], v[96:99]
	v_mfma_f32_16x16x32_bf16 v[84:87], v[168:171], v[200:203], v[84:87]
	v_mfma_f32_16x16x32_bf16 v[80:83], v[176:179], v[200:203], v[80:83]
	v_mfma_f32_16x16x32_bf16 v[68:71], v[168:171], v[212:215], v[68:71]
	v_mfma_f32_16x16x32_bf16 v[64:67], v[176:179], v[212:215], v[64:67]
	v_mfma_f32_16x16x32_bf16 v[116:119], v[172:175], v[188:191], v[116:119]
	v_mfma_f32_16x16x32_bf16 v[112:115], v[180:183], v[188:191], v[112:115]
	v_mfma_f32_16x16x32_bf16 v[100:103], v[172:175], v[196:199], v[100:103]
	v_mfma_f32_16x16x32_bf16 v[96:99], v[180:183], v[196:199], v[96:99]
	v_mfma_f32_16x16x32_bf16 v[84:87], v[172:175], v[208:211], v[84:87]
	v_mfma_f32_16x16x32_bf16 v[80:83], v[180:183], v[208:211], v[80:83]
	v_mfma_f32_16x16x32_bf16 v[68:71], v[172:175], v[216:219], v[68:71]
	v_mfma_f32_16x16x32_bf16 v[64:67], v[180:183], v[216:219], v[64:67]
	s_barrier
	s_bitcmp1_b32 s97, 0
	s_cbranch_scc1 .Lstg_19_3_b
	s_add_i32 s30, s54, s38
	s_mov_b32 m0, s30
	s_nop 0
	global_load_lds_dwordx4 v205, s[28:29]
	s_add_i32 m0, s30, 0x2000
	s_add_u32 s28, s28, 0x40080
	s_addc_u32 s29, s29, 0
	s_add_i32 s30, s55, s38
	global_load_lds_dwordx4 v221, s[98:99]
	s_mov_b32 m0, s30
	s_nop 0
	global_load_lds_dwordx4 v130, s[28:29]
	s_add_i32 m0, s30, 0x2000
	s_nop 0
	global_load_lds_dwordx4 v134, s[28:29]
	s_cmp_lg_u32 s53, 12
	s_cbranch_scc1 .Lbal_last_19
	s_mov_b32 m0, s44
	s_nop 0
	global_load_lds_dwordx4 v204, s[100:101]
	s_mov_b32 m0, s45
	s_nop 0
	global_load_lds_dwordx4 v220, s[100:101]

.Lstg_19_3_b:
	s_add_i32 s30, s54, s38
	s_mov_b32 m0, s30
	ds_read_b128 v[184:187], v153 offset:49152
	ds_read_b128 v[188:191], v153 offset:50176
	ds_read_b128 v[192:195], v153 offset:51200
	ds_read_b128 v[196:199], v153 offset:52224
	ds_read_b128 v[200:203], v153 offset:53248
	ds_read_b128 v[208:211], v153 offset:54272
	ds_read_b128 v[212:215], v153 offset:55296
	ds_read_b128 v[216:219], v153 offset:56320
	global_load_lds_dwordx4 v205, s[28:29]
	s_add_i32 m0, s30, 0x2000
	s_add_u32 s28, s28, 0x40080
	s_addc_u32 s29, s29, 0
	s_add_i32 s30, s55, s38
	global_load_lds_dwordx4 v221, s[98:99]
	s_mov_b32 m0, s30
	s_nop 0
	global_load_lds_dwordx4 v130, s[28:29]
	s_add_i32 m0, s30, 0x2000
	s_nop 0
	global_load_lds_dwordx4 v134, s[28:29]
	s_cmp_lg_u32 s53, 12
	s_cbranch_scc1 .Lbal_last_19_b
	s_mov_b32 m0, s44
	s_nop 0
	global_load_lds_dwordx4 v204, s[100:101]
	s_mov_b32 m0, s45
	s_nop 0
	global_load_lds_dwordx4 v220, s[100:101]
.Lbal_last_19_b:
.Lstg_19_3_j:
	s_waitcnt vmcnt(6)
	s_waitcnt lgkmcnt(0)
	s_barrier
	s_waitcnt lgkmcnt(0)
	v_mfma_f32_16x16x32_bf16 v[60:63], v[144:147], v[184:187], v[60:63]
	v_mfma_f32_16x16x32_bf16 v[56:59], v[160:163], v[184:187], v[56:59]
	v_mfma_f32_16x16x32_bf16 v[44:47], v[144:147], v[192:195], v[44:47]
	v_mfma_f32_16x16x32_bf16 v[40:43], v[160:163], v[192:195], v[40:43]
	v_mfma_f32_16x16x32_bf16 v[28:31], v[144:147], v[200:203], v[28:31]
	v_mfma_f32_16x16x32_bf16 v[24:27], v[160:163], v[200:203], v[24:27]
	v_mfma_f32_16x16x32_bf16 v[12:15], v[144:147], v[212:215], v[12:15]
	v_mfma_f32_16x16x32_bf16 v[8:11], v[160:163], v[212:215], v[8:11]
	v_mfma_f32_16x16x32_bf16 v[60:63], v[156:159], v[188:191], v[60:63]
	v_mfma_f32_16x16x32_bf16 v[56:59], v[164:167], v[188:191], v[56:59]
	v_mfma_f32_16x16x32_bf16 v[44:47], v[156:159], v[196:199], v[44:47]
	v_mfma_f32_16x16x32_bf16 v[40:43], v[164:167], v[196:199], v[40:43]
	v_mfma_f32_16x16x32_bf16 v[28:31], v[156:159], v[208:211], v[28:31]
	v_mfma_f32_16x16x32_bf16 v[24:27], v[164:167], v[208:211], v[24:27]
	v_mfma_f32_16x16x32_bf16 v[12:15], v[156:159], v[216:219], v[12:15]
	v_mfma_f32_16x16x32_bf16 v[8:11], v[164:167], v[216:219], v[8:11]
	v_mfma_f32_16x16x32_bf16 v[52:55], v[168:171], v[184:187], v[52:55]
	v_mfma_f32_16x16x32_bf16 v[48:51], v[176:179], v[184:187], v[48:51]
	v_mfma_f32_16x16x32_bf16 v[36:39], v[168:171], v[192:195], v[36:39]
	v_mfma_f32_16x16x32_bf16 v[32:35], v[176:179], v[192:195], v[32:35]
	v_mfma_f32_16x16x32_bf16 v[20:23], v[168:171], v[200:203], v[20:23]
	v_mfma_f32_16x16x32_bf16 v[16:19], v[176:179], v[200:203], v[16:19]
	v_mfma_f32_16x16x32_bf16 v[4:7], v[168:171], v[212:215], v[4:7]
	v_mfma_f32_16x16x32_bf16 v[0:3], v[176:179], v[212:215], v[0:3]
	v_mfma_f32_16x16x32_bf16 v[52:55], v[172:175], v[188:191], v[52:55]
	v_mfma_f32_16x16x32_bf16 v[48:51], v[180:183], v[188:191], v[48:51]
	v_mfma_f32_16x16x32_bf16 v[36:39], v[172:175], v[196:199], v[36:39]
	v_mfma_f32_16x16x32_bf16 v[32:35], v[180:183], v[196:199], v[32:35]
	v_mfma_f32_16x16x32_bf16 v[20:23], v[172:175], v[208:211], v[20:23]
	v_mfma_f32_16x16x32_bf16 v[16:19], v[180:183], v[208:211], v[16:19]
	v_mfma_f32_16x16x32_bf16 v[4:7], v[172:175], v[216:219], v[4:7]
	v_mfma_f32_16x16x32_bf16 v[0:3], v[180:183], v[216:219], v[0:3]
	s_barrier
	s_add_i32 s53, s53, 2
	s_add_u32 s51, s51, 0x100
	s_addc_u32 s52, s52, 0
	s_add_u32 s26, s26, 0x100
	s_addc_u32 s27, s27, 0
	s_cmp_gt_u32 s53, 13
	s_cbranch_scc0 .LBB0_699
	s_setprio 0
	s_and_b64 vcc, exec, s[16:17]
	s_cbranch_vccz .LBB0_702
	s_barrier

.Lbal_first_18:
	s_add_u32 s30, s28, 0x100
	s_addc_u32 s31, s29, 0
	s_cmp_eq_u32 s58, 60
	s_cselect_b32 s37, s21, s31
	s_cselect_b32 s36, s27, s30
	s_cselect_b32 s35, s19, s57
	s_cselect_b32 s34, s55, s56
	s_add_i32 m0, s44, 0xc000
	s_nop 0
	global_load_lds_dwordx4 v134, s[28:29]
	s_add_i32 m0, s44, 0xe000
	s_nop 0
	global_load_lds_dwordx4 v132, s[28:29]
	ds_read_b128 v[140:143], v147
	ds_read_b128 v[150:153], v147 offset:1024
	ds_read_b128 v[154:157], v147 offset:2048
	ds_read_b128 v[158:161], v147 offset:3072
	ds_read_b128 v[162:165], v148
	ds_read_b128 v[166:169], v148 offset:1024
	ds_read_b128 v[170:173], v148 offset:2048
	ds_read_b128 v[174:177], v148 offset:3072
	ds_read_b128 v[178:181], v149
	ds_read_b128 v[182:185], v149 offset:1024
	ds_read_b128 v[186:189], v149 offset:2048
	ds_read_b128 v[190:193], v149 offset:3072
	ds_read_b128 v[194:197], v149 offset:4096
	ds_read_b128 v[198:201], v149 offset:5120
	ds_read_b128 v[202:205], v149 offset:6144
	ds_read_b128 v[208:211], v149 offset:7168
	s_branch .Lstg_18_0_j

.Lbal_first_18_b:
	ds_read_b128 v[140:143], v147
	ds_read_b128 v[150:153], v147 offset:1024
	ds_read_b128 v[154:157], v147 offset:2048
	ds_read_b128 v[158:161], v147 offset:3072
	ds_read_b128 v[162:165], v148
	ds_read_b128 v[166:169], v148 offset:1024
	ds_read_b128 v[170:173], v148 offset:2048
	ds_read_b128 v[174:177], v148 offset:3072
	s_add_u32 s30, s28, 0x100
	s_addc_u32 s31, s29, 0
	s_cmp_eq_u32 s58, 60
	s_cselect_b32 s37, s21, s31
	s_cselect_b32 s36, s27, s30
	s_cselect_b32 s35, s19, s57
	s_cselect_b32 s34, s55, s56
	s_add_i32 m0, s44, 0xc000
	ds_read_b128 v[178:181], v149
	ds_read_b128 v[182:185], v149 offset:1024
	ds_read_b128 v[186:189], v149 offset:2048
	ds_read_b128 v[190:193], v149 offset:3072
	ds_read_b128 v[194:197], v149 offset:4096
	ds_read_b128 v[198:201], v149 offset:5120
	ds_read_b128 v[202:205], v149 offset:6144
	ds_read_b128 v[208:211], v149 offset:7168
	global_load_lds_dwordx4 v134, s[28:29]
	s_add_i32 m0, s44, 0xe000
	s_nop 0
	global_load_lds_dwordx4 v132, s[28:29]
.Lstg_18_0_j:
	s_waitcnt vmcnt(8)
	s_waitcnt lgkmcnt(0)
	s_barrier
	s_waitcnt lgkmcnt(0)
	v_mfma_f32_16x16x32_bf16 v[124:127], v[140:143], v[178:181], v[124:127]
	v_mfma_f32_16x16x32_bf16 v[120:123], v[154:157], v[178:181], v[120:123]
	v_mfma_f32_16x16x32_bf16 v[108:111], v[140:143], v[186:189], v[108:111]
	v_mfma_f32_16x16x32_bf16 v[104:107], v[154:157], v[186:189], v[104:107]
	v_mfma_f32_16x16x32_bf16 v[92:95], v[140:143], v[194:197], v[92:95]
	v_mfma_f32_16x16x32_bf16 v[88:91], v[154:157], v[194:197], v[88:91]
	v_mfma_f32_16x16x32_bf16 v[76:79], v[140:143], v[202:205], v[76:79]
	v_mfma_f32_16x16x32_bf16 v[72:75], v[154:157], v[202:205], v[72:75]
	v_mfma_f32_16x16x32_bf16 v[124:127], v[150:153], v[182:185], v[124:127]
	v_mfma_f32_16x16x32_bf16 v[120:123], v[158:161], v[182:185], v[120:123]
	v_mfma_f32_16x16x32_bf16 v[108:111], v[150:153], v[190:193], v[108:111]
	v_mfma_f32_16x16x32_bf16 v[104:107], v[158:161], v[190:193], v[104:107]
	v_mfma_f32_16x16x32_bf16 v[92:95], v[150:153], v[198:201], v[92:95]
	v_mfma_f32_16x16x32_bf16 v[88:91], v[158:161], v[198:201], v[88:91]
	v_mfma_f32_16x16x32_bf16 v[76:79], v[150:153], v[208:211], v[76:79]
	v_mfma_f32_16x16x32_bf16 v[72:75], v[158:161], v[208:211], v[72:75]
	v_mfma_f32_16x16x32_bf16 v[116:119], v[162:165], v[178:181], v[116:119]
	v_mfma_f32_16x16x32_bf16 v[112:115], v[170:173], v[178:181], v[112:115]
	v_mfma_f32_16x16x32_bf16 v[100:103], v[162:165], v[186:189], v[100:103]
	v_mfma_f32_16x16x32_bf16 v[96:99], v[170:173], v[186:189], v[96:99]
	v_mfma_f32_16x16x32_bf16 v[84:87], v[162:165], v[194:197], v[84:87]
	v_mfma_f32_16x16x32_bf16 v[80:83], v[170:173], v[194:197], v[80:83]
	v_mfma_f32_16x16x32_bf16 v[68:71], v[162:165], v[202:205], v[68:71]
	v_mfma_f32_16x16x32_bf16 v[64:67], v[170:173], v[202:205], v[64:67]
	v_mfma_f32_16x16x32_bf16 v[116:119], v[166:169], v[182:185], v[116:119]
	v_mfma_f32_16x16x32_bf16 v[112:115], v[174:177], v[182:185], v[112:115]
	v_mfma_f32_16x16x32_bf16 v[100:103], v[166:169], v[190:193], v[100:103]
	v_mfma_f32_16x16x32_bf16 v[96:99], v[174:177], v[190:193], v[96:99]
	v_mfma_f32_16x16x32_bf16 v[84:87], v[166:169], v[198:201], v[84:87]
	v_mfma_f32_16x16x32_bf16 v[80:83], v[174:177], v[198:201], v[80:83]
	v_mfma_f32_16x16x32_bf16 v[68:71], v[166:169], v[208:211], v[68:71]
	v_mfma_f32_16x16x32_bf16 v[64:67], v[174:177], v[208:211], v[64:67]
	s_barrier
	s_bitcmp1_b32 s101, 0
	s_cbranch_scc1 .Lstg_18_1_b
	s_add_i32 s28, s52, s43
	s_mov_b32 m0, s28
	s_nop 0
	global_load_lds_dwordx4 v128, s[34:35]
	s_add_i32 m0, s28, 0x2000
	s_add_u32 s28, s34, 0x100000
	s_mov_b64 s[98:99], s[34:35]
	s_addc_u32 s29, s35, 0
	s_add_i32 s59, s53, s43
	global_load_lds_dwordx4 v130, s[34:35]
	s_mov_b32 m0, s59
	s_nop 0
	global_load_lds_dwordx4 v128, s[28:29]
	s_add_i32 m0, s59, 0x2000
	s_nop 0
	global_load_lds_dwordx4 v130, s[28:29]
	ds_read_b128 v[178:181], v149 offset:16384
	ds_read_b128 v[182:185], v149 offset:17408
	ds_read_b128 v[186:189], v149 offset:18432
	ds_read_b128 v[190:193], v149 offset:19456
	ds_read_b128 v[194:197], v149 offset:20480
	ds_read_b128 v[198:201], v149 offset:21504
	ds_read_b128 v[202:205], v149 offset:22528
	ds_read_b128 v[208:211], v149 offset:23552
	s_branch .Lstg_18_1_j
.Lstg_18_1_b:
	s_add_i32 s28, s52, s43
	s_mov_b32 m0, s28
	ds_read_b128 v[178:181], v149 offset:16384
	ds_read_b128 v[182:185], v149 offset:17408
	ds_read_b128 v[186:189], v149 offset:18432
	ds_read_b128 v[190:193], v149 offset:19456
	ds_read_b128 v[194:197], v149 offset:20480
	ds_read_b128 v[198:201], v149 offset:21504
	ds_read_b128 v[202:205], v149 offset:22528
	ds_read_b128 v[208:211], v149 offset:23552
	global_load_lds_dwordx4 v128, s[34:35]
	s_add_i32 m0, s28, 0x2000
	s_add_u32 s28, s34, 0x100000
	s_mov_b64 s[98:99], s[34:35]
	s_addc_u32 s29, s35, 0
	s_add_i32 s59, s53, s43
	global_load_lds_dwordx4 v130, s[34:35]
	s_mov_b32 m0, s59
	s_nop 0
	global_load_lds_dwordx4 v128, s[28:29]
	s_add_i32 m0, s59, 0x2000
	s_nop 0
	global_load_lds_dwordx4 v130, s[28:29]
.Lstg_18_1_j:
	s_waitcnt vmcnt(6)
	s_waitcnt lgkmcnt(0)
	s_barrier
	s_waitcnt lgkmcnt(0)
	v_mfma_f32_16x16x32_bf16 v[60:63], v[140:143], v[178:181], v[60:63]
	v_mfma_f32_16x16x32_bf16 v[56:59], v[154:157], v[178:181], v[56:59]
	v_mfma_f32_16x16x32_bf16 v[44:47], v[140:143], v[186:189], v[44:47]
	v_mfma_f32_16x16x32_bf16 v[40:43], v[154:157], v[186:189], v[40:43]
	v_mfma_f32_16x16x32_bf16 v[28:31], v[140:143], v[194:197], v[28:31]
	v_mfma_f32_16x16x32_bf16 v[24:27], v[154:157], v[194:197], v[24:27]
	v_mfma_f32_16x16x32_bf16 v[12:15], v[140:143], v[202:205], v[12:15]
	v_mfma_f32_16x16x32_bf16 v[8:11], v[154:157], v[202:205], v[8:11]
	v_mfma_f32_16x16x32_bf16 v[60:63], v[150:153], v[182:185], v[60:63]
	v_mfma_f32_16x16x32_bf16 v[56:59], v[158:161], v[182:185], v[56:59]
	v_mfma_f32_16x16x32_bf16 v[44:47], v[150:153], v[190:193], v[44:47]
	v_mfma_f32_16x16x32_bf16 v[40:43], v[158:161], v[190:193], v[40:43]
	v_mfma_f32_16x16x32_bf16 v[28:31], v[150:153], v[198:201], v[28:31]
	v_mfma_f32_16x16x32_bf16 v[24:27], v[158:161], v[198:201], v[24:27]
	v_mfma_f32_16x16x32_bf16 v[12:15], v[150:153], v[208:211], v[12:15]
	v_mfma_f32_16x16x32_bf16 v[8:11], v[158:161], v[208:211], v[8:11]
	v_mfma_f32_16x16x32_bf16 v[52:55], v[162:165], v[178:181], v[52:55]
	v_mfma_f32_16x16x32_bf16 v[48:51], v[170:173], v[178:181], v[48:51]
	v_mfma_f32_16x16x32_bf16 v[36:39], v[162:165], v[186:189], v[36:39]
	v_mfma_f32_16x16x32_bf16 v[32:35], v[170:173], v[186:189], v[32:35]
	v_mfma_f32_16x16x32_bf16 v[20:23], v[162:165], v[194:197], v[20:23]
	v_mfma_f32_16x16x32_bf16 v[16:19], v[170:173], v[194:197], v[16:19]
	v_mfma_f32_16x16x32_bf16 v[4:7], v[162:165], v[202:205], v[4:7]
	v_mfma_f32_16x16x32_bf16 v[0:3], v[170:173], v[202:205], v[0:3]
	v_mfma_f32_16x16x32_bf16 v[52:55], v[166:169], v[182:185], v[52:55]
	v_mfma_f32_16x16x32_bf16 v[48:51], v[174:177], v[182:185], v[48:51]
	v_mfma_f32_16x16x32_bf16 v[36:39], v[166:169], v[190:193], v[36:39]
	v_mfma_f32_16x16x32_bf16 v[32:35], v[174:177], v[190:193], v[32:35]
	v_mfma_f32_16x16x32_bf16 v[20:23], v[166:169], v[198:201], v[20:23]
	v_mfma_f32_16x16x32_bf16 v[16:19], v[174:177], v[198:201], v[16:19]
	v_mfma_f32_16x16x32_bf16 v[4:7], v[166:169], v[208:211], v[4:7]
	v_mfma_f32_16x16x32_bf16 v[0:3], v[174:177], v[208:211], v[0:3]
	s_barrier
	s_bitcmp1_b32 s101, 0
	s_cbranch_scc1 .Lstg_18_2_b
	s_mov_b32 m0, s44
	s_nop 0
	global_load_lds_dwordx4 v128, s[36:37]
	s_mov_b32 m0, s45
	s_nop 0
	global_load_lds_dwordx4 v130, s[36:37]
	s_add_i32 s59, 0, 0x18000
	s_add_i32 s60, 0, 0x1c000
	s_add_u32 s28, s36, 0x100000
	s_addc_u32 s29, s37, 0
	s_mov_b32 m0, s46
	s_nop 0
	global_load_lds_dwordx4 v128, s[28:29]
	s_mov_b32 m0, s47
	s_nop 0
	global_load_lds_dwordx4 v130, s[28:29]
	v_add_u32_e32 v158, s59, v145
	v_add_u32_e32 v174, s60, v145
	ds_read_b128 v[140:143], v158
	ds_read_b128 v[150:153], v158 offset:1024
	ds_read_b128 v[154:157], v158 offset:2048
	ds_read_b128 v[158:161], v158 offset:3072
	ds_read_b128 v[162:165], v174
	ds_read_b128 v[166:169], v174 offset:1024
	ds_read_b128 v[170:173], v174 offset:2048
	ds_read_b128 v[174:177], v174 offset:3072
	ds_read_b128 v[178:181], v149 offset:32768
	ds_read_b128 v[182:185], v149 offset:33792
	ds_read_b128 v[186:189], v149 offset:34816
	ds_read_b128 v[190:193], v149 offset:35840
	ds_read_b128 v[194:197], v149 offset:36864
	ds_read_b128 v[198:201], v149 offset:37888
	ds_read_b128 v[202:205], v149 offset:38912
	ds_read_b128 v[208:211], v149 offset:39936
	s_branch .Lstg_18_2_j
.Lstg_18_2_b:
	s_mov_b32 m0, s44
	s_nop 0
	global_load_lds_dwordx4 v128, s[36:37]
	s_mov_b32 m0, s45
	s_nop 0
	global_load_lds_dwordx4 v130, s[36:37]
	s_add_i32 s59, 0, 0x18000
	s_add_i32 s60, 0, 0x1c000
	v_add_u32_e32 v158, s59, v145
	v_add_u32_e32 v174, s60, v145
	ds_read_b128 v[140:143], v158
	ds_read_b128 v[150:153], v158 offset:1024
	ds_read_b128 v[154:157], v158 offset:2048
	ds_read_b128 v[158:161], v158 offset:3072
	ds_read_b128 v[162:165], v174
	ds_read_b128 v[166:169], v174 offset:1024
	ds_read_b128 v[170:173], v174 offset:2048
	ds_read_b128 v[174:177], v174 offset:3072
	s_add_u32 s28, s36, 0x100000
	s_addc_u32 s29, s37, 0
	s_mov_b32 m0, s46
	ds_read_b128 v[178:181], v149 offset:32768
	ds_read_b128 v[182:185], v149 offset:33792
	ds_read_b128 v[186:189], v149 offset:34816
	ds_read_b128 v[190:193], v149 offset:35840
	ds_read_b128 v[194:197], v149 offset:36864
	ds_read_b128 v[198:201], v149 offset:37888
	ds_read_b128 v[202:205], v149 offset:38912
	ds_read_b128 v[208:211], v149 offset:39936
	global_load_lds_dwordx4 v128, s[28:29]
	s_mov_b32 m0, s47
	s_nop 0
	global_load_lds_dwordx4 v130, s[28:29]
.Lstg_18_2_j:
	s_waitcnt vmcnt(8)
	s_waitcnt lgkmcnt(0)
	s_barrier
	s_waitcnt lgkmcnt(0)
	v_mfma_f32_16x16x32_bf16 v[124:127], v[140:143], v[178:181], v[124:127]
	v_mfma_f32_16x16x32_bf16 v[120:123], v[154:157], v[178:181], v[120:123]
	v_mfma_f32_16x16x32_bf16 v[108:111], v[140:143], v[186:189], v[108:111]
	v_mfma_f32_16x16x32_bf16 v[104:107], v[154:157], v[186:189], v[104:107]
	v_mfma_f32_16x16x32_bf16 v[92:95], v[140:143], v[194:197], v[92:95]
	v_mfma_f32_16x16x32_bf16 v[88:91], v[154:157], v[194:197], v[88:91]
	v_mfma_f32_16x16x32_bf16 v[76:79], v[140:143], v[202:205], v[76:79]
	v_mfma_f32_16x16x32_bf16 v[72:75], v[154:157], v[202:205], v[72:75]
	v_mfma_f32_16x16x32_bf16 v[124:127], v[150:153], v[182:185], v[124:127]
	v_mfma_f32_16x16x32_bf16 v[120:123], v[158:161], v[182:185], v[120:123]
	v_mfma_f32_16x16x32_bf16 v[108:111], v[150:153], v[190:193], v[108:111]
	v_mfma_f32_16x16x32_bf16 v[104:107], v[158:161], v[190:193], v[104:107]
	v_mfma_f32_16x16x32_bf16 v[92:95], v[150:153], v[198:201], v[92:95]
	v_mfma_f32_16x16x32_bf16 v[88:91], v[158:161], v[198:201], v[88:91]
	v_mfma_f32_16x16x32_bf16 v[76:79], v[150:153], v[208:211], v[76:79]
	v_mfma_f32_16x16x32_bf16 v[72:75], v[158:161], v[208:211], v[72:75]
	v_mfma_f32_16x16x32_bf16 v[116:119], v[162:165], v[178:181], v[116:119]
	v_mfma_f32_16x16x32_bf16 v[112:115], v[170:173], v[178:181], v[112:115]
	v_mfma_f32_16x16x32_bf16 v[100:103], v[162:165], v[186:189], v[100:103]
	v_mfma_f32_16x16x32_bf16 v[96:99], v[170:173], v[186:189], v[96:99]
	v_mfma_f32_16x16x32_bf16 v[84:87], v[162:165], v[194:197], v[84:87]
	v_mfma_f32_16x16x32_bf16 v[80:83], v[170:173], v[194:197], v[80:83]
	v_mfma_f32_16x16x32_bf16 v[68:71], v[162:165], v[202:205], v[68:71]
	v_mfma_f32_16x16x32_bf16 v[64:67], v[170:173], v[202:205], v[64:67]
	v_mfma_f32_16x16x32_bf16 v[116:119], v[166:169], v[182:185], v[116:119]
	v_mfma_f32_16x16x32_bf16 v[112:115], v[174:177], v[182:185], v[112:115]
	v_mfma_f32_16x16x32_bf16 v[100:103], v[166:169], v[190:193], v[100:103]
	v_mfma_f32_16x16x32_bf16 v[96:99], v[174:177], v[190:193], v[96:99]
	v_mfma_f32_16x16x32_bf16 v[84:87], v[166:169], v[198:201], v[84:87]
	v_mfma_f32_16x16x32_bf16 v[80:83], v[174:177], v[198:201], v[80:83]
	v_mfma_f32_16x16x32_bf16 v[68:71], v[166:169], v[208:211], v[68:71]
	v_mfma_f32_16x16x32_bf16 v[64:67], v[174:177], v[208:211], v[64:67]
	s_barrier
	s_bitcmp1_b32 s101, 0
	s_cbranch_scc1 .Lstg_18_3_b
	s_add_i32 s28, s59, s43
	s_mov_b32 m0, s28
	s_nop 0
	global_load_lds_dwordx4 v212, s[34:35]
	s_add_i32 m0, s28, 0x2000
	s_add_u32 s28, s34, 0x100080
	s_addc_u32 s29, s35, 0
	s_add_i32 s34, s60, s43
	global_load_lds_dwordx4 v213, s[98:99]
	s_mov_b32 m0, s34
	s_nop 0
	global_load_lds_dwordx4 v128, s[28:29]
	s_add_i32 m0, s34, 0x2000
	s_nop 0
	global_load_lds_dwordx4 v130, s[28:29]
	s_cmp_lg_u32 s58, 60
	s_cbranch_scc1 .Lbal_last_18
	s_mov_b32 m0, s49
	s_nop 0
	global_load_lds_dwordx4 v212, s[36:37]
	s_mov_b32 m0, s50
	s_nop 0
	global_load_lds_dwordx4 v213, s[36:37]

.Lstg_18_3_b:
	s_add_i32 s28, s59, s43
	s_mov_b32 m0, s28
	ds_read_b128 v[178:181], v149 offset:49152
	ds_read_b128 v[182:185], v149 offset:50176
	ds_read_b128 v[186:189], v149 offset:51200
	ds_read_b128 v[190:193], v149 offset:52224
	ds_read_b128 v[194:197], v149 offset:53248
	ds_read_b128 v[198:201], v149 offset:54272
	ds_read_b128 v[202:205], v149 offset:55296
	ds_read_b128 v[208:211], v149 offset:56320
	global_load_lds_dwordx4 v212, s[34:35]
	s_add_i32 m0, s28, 0x2000
	s_add_u32 s28, s34, 0x100080
	s_addc_u32 s29, s35, 0
	s_add_i32 s34, s60, s43
	global_load_lds_dwordx4 v213, s[98:99]
	s_mov_b32 m0, s34
	s_nop 0
	global_load_lds_dwordx4 v128, s[28:29]
	s_add_i32 m0, s34, 0x2000
	s_nop 0
	global_load_lds_dwordx4 v130, s[28:29]
	s_cmp_lg_u32 s58, 60
	s_cbranch_scc1 .Lbal_last_18_b
	s_mov_b32 m0, s49
	s_nop 0
	global_load_lds_dwordx4 v212, s[36:37]
	s_mov_b32 m0, s50
	s_nop 0
	global_load_lds_dwordx4 v213, s[36:37]
.Lbal_last_18_b:
.Lstg_18_3_j:
	s_waitcnt vmcnt(6)
	s_waitcnt lgkmcnt(0)
	s_barrier
	s_waitcnt lgkmcnt(0)
	v_mfma_f32_16x16x32_bf16 v[60:63], v[140:143], v[178:181], v[60:63]
	v_mfma_f32_16x16x32_bf16 v[56:59], v[154:157], v[178:181], v[56:59]
	v_mfma_f32_16x16x32_bf16 v[44:47], v[140:143], v[186:189], v[44:47]
	v_mfma_f32_16x16x32_bf16 v[40:43], v[154:157], v[186:189], v[40:43]
	v_mfma_f32_16x16x32_bf16 v[28:31], v[140:143], v[194:197], v[28:31]
	v_mfma_f32_16x16x32_bf16 v[24:27], v[154:157], v[194:197], v[24:27]
	v_mfma_f32_16x16x32_bf16 v[12:15], v[140:143], v[202:205], v[12:15]
	v_mfma_f32_16x16x32_bf16 v[8:11], v[154:157], v[202:205], v[8:11]
	v_mfma_f32_16x16x32_bf16 v[60:63], v[150:153], v[182:185], v[60:63]
	v_mfma_f32_16x16x32_bf16 v[56:59], v[158:161], v[182:185], v[56:59]
	v_mfma_f32_16x16x32_bf16 v[44:47], v[150:153], v[190:193], v[44:47]
	v_mfma_f32_16x16x32_bf16 v[40:43], v[158:161], v[190:193], v[40:43]
	v_mfma_f32_16x16x32_bf16 v[28:31], v[150:153], v[198:201], v[28:31]
	v_mfma_f32_16x16x32_bf16 v[24:27], v[158:161], v[198:201], v[24:27]
	v_mfma_f32_16x16x32_bf16 v[12:15], v[150:153], v[208:211], v[12:15]
	v_mfma_f32_16x16x32_bf16 v[8:11], v[158:161], v[208:211], v[8:11]
	v_mfma_f32_16x16x32_bf16 v[52:55], v[162:165], v[178:181], v[52:55]
	v_mfma_f32_16x16x32_bf16 v[48:51], v[170:173], v[178:181], v[48:51]
	v_mfma_f32_16x16x32_bf16 v[36:39], v[162:165], v[186:189], v[36:39]
	v_mfma_f32_16x16x32_bf16 v[32:35], v[170:173], v[186:189], v[32:35]
	v_mfma_f32_16x16x32_bf16 v[20:23], v[162:165], v[194:197], v[20:23]
	v_mfma_f32_16x16x32_bf16 v[16:19], v[170:173], v[194:197], v[16:19]
	v_mfma_f32_16x16x32_bf16 v[4:7], v[162:165], v[202:205], v[4:7]
	v_mfma_f32_16x16x32_bf16 v[0:3], v[170:173], v[202:205], v[0:3]
	v_mfma_f32_16x16x32_bf16 v[52:55], v[166:169], v[182:185], v[52:55]
	v_mfma_f32_16x16x32_bf16 v[48:51], v[174:177], v[182:185], v[48:51]
	v_mfma_f32_16x16x32_bf16 v[36:39], v[166:169], v[190:193], v[36:39]
	v_mfma_f32_16x16x32_bf16 v[32:35], v[174:177], v[190:193], v[32:35]
	v_mfma_f32_16x16x32_bf16 v[20:23], v[166:169], v[198:201], v[20:23]
	v_mfma_f32_16x16x32_bf16 v[16:19], v[174:177], v[198:201], v[16:19]
	v_mfma_f32_16x16x32_bf16 v[4:7], v[166:169], v[208:211], v[4:7]
	v_mfma_f32_16x16x32_bf16 v[0:3], v[174:177], v[208:211], v[0:3]
	s_barrier
	s_add_i32 s58, s58, 2
	s_add_u32 s56, s56, 0x100
	s_addc_u32 s57, s57, 0
	s_cmp_gt_u32 s58, 61
	s_mov_b64 s[28:29], s[30:31]
	s_cbranch_scc0 .LBB0_778
	s_setprio 0
	s_and_b64 vcc, exec, s[16:17]
	s_cbranch_vccz .LBB0_781
	s_barrier

.LBB0_895:
	s_bitcmp1_b32 s97, 0
	s_cbranch_scc1 .Lstg_17_0_b
	s_cmp_eq_i32 s61, -2
	s_cbranch_scc1 .Lbal_first_17
	s_mov_b32 m0, s51
	s_nop 0
	global_load_lds_dwordx4 v148, s[100:101]
	s_mov_b32 m0, s52
	s_nop 0
	global_load_lds_dwordx4 v149, s[100:101]
.Lbal_first_17:
	s_add_u32 s38, s36, 0xfffc0080
	s_addc_u32 s39, s37, -1
	s_cmp_eq_u32 s61, 12
	s_cselect_b32 s41, s3, s39
	s_cselect_b32 s40, s29, s38
	s_cselect_b32 s39, s27, s60
	s_cselect_b32 s38, s58, s59
	s_add_i32 m0, s46, 0xc000
	s_nop 0
	global_load_lds_dwordx4 v134, s[36:37]
	s_add_i32 m0, s46, 0xe000
	s_nop 0
	global_load_lds_dwordx4 v132, s[36:37]
	ds_read_b128 v[140:143], v153
	ds_read_b128 v[144:147], v153 offset:1024
	ds_read_b128 v[158:161], v153 offset:2048
	ds_read_b128 v[162:165], v153 offset:3072
	ds_read_b128 v[166:169], v154
	ds_read_b128 v[170:173], v154 offset:1024
	ds_read_b128 v[174:177], v154 offset:2048
	ds_read_b128 v[178:181], v154 offset:3072
	ds_read_b128 v[182:185], v155
	ds_read_b128 v[186:189], v155 offset:1024
	ds_read_b128 v[190:193], v155 offset:2048
	ds_read_b128 v[194:197], v155 offset:3072
	ds_read_b128 v[198:201], v155 offset:4096
	ds_read_b128 v[202:205], v155 offset:5120
	ds_read_b128 v[208:211], v155 offset:6144
	ds_read_b128 v[212:215], v155 offset:7168
	s_branch .Lstg_17_0_j

.Lbal_first_17_b:
	ds_read_b128 v[140:143], v153
	ds_read_b128 v[144:147], v153 offset:1024
	ds_read_b128 v[158:161], v153 offset:2048
	ds_read_b128 v[162:165], v153 offset:3072
	ds_read_b128 v[166:169], v154
	ds_read_b128 v[170:173], v154 offset:1024
	ds_read_b128 v[174:177], v154 offset:2048
	ds_read_b128 v[178:181], v154 offset:3072
	s_add_u32 s38, s36, 0xfffc0080
	s_addc_u32 s39, s37, -1
	s_cmp_eq_u32 s61, 12
	s_cselect_b32 s41, s3, s39
	s_cselect_b32 s40, s29, s38
	s_cselect_b32 s39, s27, s60
	s_cselect_b32 s38, s58, s59
	s_add_i32 m0, s46, 0xc000
	ds_read_b128 v[182:185], v155
	ds_read_b128 v[186:189], v155 offset:1024
	ds_read_b128 v[190:193], v155 offset:2048
	ds_read_b128 v[194:197], v155 offset:3072
	ds_read_b128 v[198:201], v155 offset:4096
	ds_read_b128 v[202:205], v155 offset:5120
	ds_read_b128 v[208:211], v155 offset:6144
	ds_read_b128 v[212:215], v155 offset:7168
	global_load_lds_dwordx4 v134, s[36:37]
	s_add_i32 m0, s46, 0xe000
	s_nop 0
	global_load_lds_dwordx4 v132, s[36:37]
.Lstg_17_0_j:
	s_waitcnt vmcnt(8)
	s_waitcnt lgkmcnt(0)
	s_barrier
	s_waitcnt lgkmcnt(0)
	v_mfma_f32_16x16x32_bf16 v[124:127], v[140:143], v[182:185], v[124:127]
	v_mfma_f32_16x16x32_bf16 v[120:123], v[158:161], v[182:185], v[120:123]
	v_mfma_f32_16x16x32_bf16 v[108:111], v[140:143], v[190:193], v[108:111]
	v_mfma_f32_16x16x32_bf16 v[104:107], v[158:161], v[190:193], v[104:107]
	v_mfma_f32_16x16x32_bf16 v[92:95], v[140:143], v[198:201], v[92:95]
	v_mfma_f32_16x16x32_bf16 v[88:91], v[158:161], v[198:201], v[88:91]
	v_mfma_f32_16x16x32_bf16 v[76:79], v[140:143], v[208:211], v[76:79]
	v_mfma_f32_16x16x32_bf16 v[72:75], v[158:161], v[208:211], v[72:75]
	v_mfma_f32_16x16x32_bf16 v[124:127], v[144:147], v[186:189], v[124:127]
	v_mfma_f32_16x16x32_bf16 v[120:123], v[162:165], v[186:189], v[120:123]
	v_mfma_f32_16x16x32_bf16 v[108:111], v[144:147], v[194:197], v[108:111]
	v_mfma_f32_16x16x32_bf16 v[104:107], v[162:165], v[194:197], v[104:107]
	v_mfma_f32_16x16x32_bf16 v[92:95], v[144:147], v[202:205], v[92:95]
	v_mfma_f32_16x16x32_bf16 v[88:91], v[162:165], v[202:205], v[88:91]
	v_mfma_f32_16x16x32_bf16 v[76:79], v[144:147], v[212:215], v[76:79]
	v_mfma_f32_16x16x32_bf16 v[72:75], v[162:165], v[212:215], v[72:75]
	v_mfma_f32_16x16x32_bf16 v[116:119], v[166:169], v[182:185], v[116:119]
	v_mfma_f32_16x16x32_bf16 v[112:115], v[174:177], v[182:185], v[112:115]
	v_mfma_f32_16x16x32_bf16 v[100:103], v[166:169], v[190:193], v[100:103]
	v_mfma_f32_16x16x32_bf16 v[96:99], v[174:177], v[190:193], v[96:99]
	v_mfma_f32_16x16x32_bf16 v[84:87], v[166:169], v[198:201], v[84:87]
	v_mfma_f32_16x16x32_bf16 v[80:83], v[174:177], v[198:201], v[80:83]
	v_mfma_f32_16x16x32_bf16 v[68:71], v[166:169], v[208:211], v[68:71]
	v_mfma_f32_16x16x32_bf16 v[64:67], v[174:177], v[208:211], v[64:67]
	v_mfma_f32_16x16x32_bf16 v[116:119], v[170:173], v[186:189], v[116:119]
	v_mfma_f32_16x16x32_bf16 v[112:115], v[178:181], v[186:189], v[112:115]
	v_mfma_f32_16x16x32_bf16 v[100:103], v[170:173], v[194:197], v[100:103]
	v_mfma_f32_16x16x32_bf16 v[96:99], v[178:181], v[194:197], v[96:99]
	v_mfma_f32_16x16x32_bf16 v[84:87], v[170:173], v[202:205], v[84:87]
	v_mfma_f32_16x16x32_bf16 v[80:83], v[178:181], v[202:205], v[80:83]
	v_mfma_f32_16x16x32_bf16 v[68:71], v[170:173], v[212:215], v[68:71]
	v_mfma_f32_16x16x32_bf16 v[64:67], v[178:181], v[212:215], v[64:67]
	s_barrier
	s_bitcmp1_b32 s97, 0
	s_cbranch_scc1 .Lstg_17_1_b
	s_add_i32 s62, s54, s45
	s_mov_b32 m0, s62
	s_nop 0
	global_load_lds_dwordx4 v128, s[38:39]
	s_add_i32 m0, s62, 0x2000
	s_add_u32 s62, s38, 0x40000
	s_mov_b64 s[98:99], s[38:39]
	s_addc_u32 s63, s39, 0
	s_add_i32 s64, s55, s45
	global_load_lds_dwordx4 v130, s[38:39]
	s_mov_b32 m0, s64
	s_mov_b64 s[100:101], s[40:41]
	global_load_lds_dwordx4 v128, s[62:63]
	s_add_i32 m0, s64, 0x2000
	s_nop 0
	global_load_lds_dwordx4 v130, s[62:63]
	ds_read_b128 v[182:185], v155 offset:16384
	ds_read_b128 v[186:189], v155 offset:17408
	ds_read_b128 v[190:193], v155 offset:18432
	ds_read_b128 v[194:197], v155 offset:19456
	ds_read_b128 v[198:201], v155 offset:20480
	ds_read_b128 v[202:205], v155 offset:21504
	ds_read_b128 v[208:211], v155 offset:22528
	ds_read_b128 v[212:215], v155 offset:23552
	s_branch .Lstg_17_1_j
.Lstg_17_1_b:
	s_add_i32 s62, s54, s45
	s_mov_b32 m0, s62
	ds_read_b128 v[182:185], v155 offset:16384
	ds_read_b128 v[186:189], v155 offset:17408
	ds_read_b128 v[190:193], v155 offset:18432
	ds_read_b128 v[194:197], v155 offset:19456
	ds_read_b128 v[198:201], v155 offset:20480
	ds_read_b128 v[202:205], v155 offset:21504
	ds_read_b128 v[208:211], v155 offset:22528
	ds_read_b128 v[212:215], v155 offset:23552
	global_load_lds_dwordx4 v128, s[38:39]
	s_add_i32 m0, s62, 0x2000
	s_add_u32 s62, s38, 0x40000
	s_mov_b64 s[98:99], s[38:39]
	s_addc_u32 s63, s39, 0
	s_add_i32 s64, s55, s45
	global_load_lds_dwordx4 v130, s[38:39]
	s_mov_b32 m0, s64
	s_mov_b64 s[100:101], s[40:41]
	global_load_lds_dwordx4 v128, s[62:63]
	s_add_i32 m0, s64, 0x2000
	s_nop 0
	global_load_lds_dwordx4 v130, s[62:63]
.Lstg_17_1_j:
	s_waitcnt vmcnt(6)
	s_waitcnt lgkmcnt(0)
	s_barrier
	s_waitcnt lgkmcnt(0)
	v_mfma_f32_16x16x32_bf16 v[60:63], v[140:143], v[182:185], v[60:63]
	v_mfma_f32_16x16x32_bf16 v[56:59], v[158:161], v[182:185], v[56:59]
	v_mfma_f32_16x16x32_bf16 v[44:47], v[140:143], v[190:193], v[44:47]
	v_mfma_f32_16x16x32_bf16 v[40:43], v[158:161], v[190:193], v[40:43]
	v_mfma_f32_16x16x32_bf16 v[28:31], v[140:143], v[198:201], v[28:31]
	v_mfma_f32_16x16x32_bf16 v[24:27], v[158:161], v[198:201], v[24:27]
	v_mfma_f32_16x16x32_bf16 v[12:15], v[140:143], v[208:211], v[12:15]
	v_mfma_f32_16x16x32_bf16 v[8:11], v[158:161], v[208:211], v[8:11]
	v_mfma_f32_16x16x32_bf16 v[60:63], v[144:147], v[186:189], v[60:63]
	v_mfma_f32_16x16x32_bf16 v[56:59], v[162:165], v[186:189], v[56:59]
	v_mfma_f32_16x16x32_bf16 v[44:47], v[144:147], v[194:197], v[44:47]
	v_mfma_f32_16x16x32_bf16 v[40:43], v[162:165], v[194:197], v[40:43]
	v_mfma_f32_16x16x32_bf16 v[28:31], v[144:147], v[202:205], v[28:31]
	v_mfma_f32_16x16x32_bf16 v[24:27], v[162:165], v[202:205], v[24:27]
	v_mfma_f32_16x16x32_bf16 v[12:15], v[144:147], v[212:215], v[12:15]
	v_mfma_f32_16x16x32_bf16 v[8:11], v[162:165], v[212:215], v[8:11]
	v_mfma_f32_16x16x32_bf16 v[52:55], v[166:169], v[182:185], v[52:55]
	v_mfma_f32_16x16x32_bf16 v[48:51], v[174:177], v[182:185], v[48:51]
	v_mfma_f32_16x16x32_bf16 v[36:39], v[166:169], v[190:193], v[36:39]
	v_mfma_f32_16x16x32_bf16 v[32:35], v[174:177], v[190:193], v[32:35]
	v_mfma_f32_16x16x32_bf16 v[20:23], v[166:169], v[198:201], v[20:23]
	v_mfma_f32_16x16x32_bf16 v[16:19], v[174:177], v[198:201], v[16:19]
	v_mfma_f32_16x16x32_bf16 v[4:7], v[166:169], v[208:211], v[4:7]
	v_mfma_f32_16x16x32_bf16 v[0:3], v[174:177], v[208:211], v[0:3]
	v_mfma_f32_16x16x32_bf16 v[52:55], v[170:173], v[186:189], v[52:55]
	v_mfma_f32_16x16x32_bf16 v[48:51], v[178:181], v[186:189], v[48:51]
	v_mfma_f32_16x16x32_bf16 v[36:39], v[170:173], v[194:197], v[36:39]
	v_mfma_f32_16x16x32_bf16 v[32:35], v[178:181], v[194:197], v[32:35]
	v_mfma_f32_16x16x32_bf16 v[20:23], v[170:173], v[202:205], v[20:23]
	v_mfma_f32_16x16x32_bf16 v[16:19], v[178:181], v[202:205], v[16:19]
	v_mfma_f32_16x16x32_bf16 v[4:7], v[170:173], v[212:215], v[4:7]
	v_mfma_f32_16x16x32_bf16 v[0:3], v[178:181], v[212:215], v[0:3]
	s_barrier
	s_bitcmp1_b32 s97, 0
	s_cbranch_scc1 .Lstg_17_2_b
	s_mov_b32 m0, s46
	s_nop 0
	global_load_lds_dwordx4 v128, s[40:41]
	s_mov_b32 m0, s47
	s_nop 0
	global_load_lds_dwordx4 v130, s[40:41]
	s_add_i32 s62, 0, 0x18000
	s_add_i32 s63, 0, 0x1c000
	s_add_u32 s40, s40, 0x40000
	s_addc_u32 s41, s41, 0
	s_mov_b32 m0, s48
	s_nop 0
	global_load_lds_dwordx4 v128, s[40:41]
	s_mov_b32 m0, s49
	s_nop 0
	global_load_lds_dwordx4 v130, s[40:41]
	v_add_u32_e32 v157, s62, v151
	ds_read_b128 v[140:143], v157
	ds_read_b128 v[144:147], v157 offset:1024
	ds_read_b128 v[158:161], v157 offset:2048
	ds_read_b128 v[162:165], v157 offset:3072
	v_add_u32_e32 v157, s63, v151
	ds_read_b128 v[166:169], v157
	ds_read_b128 v[170:173], v157 offset:1024
	ds_read_b128 v[174:177], v157 offset:2048
	ds_read_b128 v[178:181], v157 offset:3072
	ds_read_b128 v[182:185], v155 offset:32768
	ds_read_b128 v[186:189], v155 offset:33792
	ds_read_b128 v[190:193], v155 offset:34816
	ds_read_b128 v[194:197], v155 offset:35840
	ds_read_b128 v[198:201], v155 offset:36864
	ds_read_b128 v[202:205], v155 offset:37888
	ds_read_b128 v[208:211], v155 offset:38912
	ds_read_b128 v[212:215], v155 offset:39936
	s_branch .Lstg_17_2_j
.Lstg_17_2_b:
	s_mov_b32 m0, s46
	s_nop 0
	global_load_lds_dwordx4 v128, s[40:41]
	s_mov_b32 m0, s47
	s_nop 0
	global_load_lds_dwordx4 v130, s[40:41]
	s_add_i32 s62, 0, 0x18000
	v_add_u32_e32 v157, s62, v151
	s_add_i32 s63, 0, 0x1c000
	ds_read_b128 v[140:143], v157
	ds_read_b128 v[144:147], v157 offset:1024
	ds_read_b128 v[158:161], v157 offset:2048
	ds_read_b128 v[162:165], v157 offset:3072
	v_add_u32_e32 v157, s63, v151
	ds_read_b128 v[166:169], v157
	ds_read_b128 v[170:173], v157 offset:1024
	ds_read_b128 v[174:177], v157 offset:2048
	ds_read_b128 v[178:181], v157 offset:3072
	s_add_u32 s40, s40, 0x40000
	s_addc_u32 s41, s41, 0
	s_mov_b32 m0, s48
	ds_read_b128 v[182:185], v155 offset:32768
	ds_read_b128 v[186:189], v155 offset:33792
	ds_read_b128 v[190:193], v155 offset:34816
	ds_read_b128 v[194:197], v155 offset:35840
	ds_read_b128 v[198:201], v155 offset:36864
	ds_read_b128 v[202:205], v155 offset:37888
	ds_read_b128 v[208:211], v155 offset:38912
	ds_read_b128 v[212:215], v155 offset:39936
	global_load_lds_dwordx4 v128, s[40:41]
	s_mov_b32 m0, s49
	s_nop 0
	global_load_lds_dwordx4 v130, s[40:41]
.Lstg_17_2_j:
	s_waitcnt vmcnt(8)
	s_waitcnt lgkmcnt(0)
	s_barrier
	s_waitcnt lgkmcnt(0)
	v_mfma_f32_16x16x32_bf16 v[124:127], v[140:143], v[182:185], v[124:127]
	v_mfma_f32_16x16x32_bf16 v[120:123], v[158:161], v[182:185], v[120:123]
	v_mfma_f32_16x16x32_bf16 v[108:111], v[140:143], v[190:193], v[108:111]
	v_mfma_f32_16x16x32_bf16 v[104:107], v[158:161], v[190:193], v[104:107]
	v_mfma_f32_16x16x32_bf16 v[92:95], v[140:143], v[198:201], v[92:95]
	v_mfma_f32_16x16x32_bf16 v[88:91], v[158:161], v[198:201], v[88:91]
	v_mfma_f32_16x16x32_bf16 v[76:79], v[140:143], v[208:211], v[76:79]
	v_mfma_f32_16x16x32_bf16 v[72:75], v[158:161], v[208:211], v[72:75]
	v_mfma_f32_16x16x32_bf16 v[124:127], v[144:147], v[186:189], v[124:127]
	v_mfma_f32_16x16x32_bf16 v[120:123], v[162:165], v[186:189], v[120:123]
	v_mfma_f32_16x16x32_bf16 v[108:111], v[144:147], v[194:197], v[108:111]
	v_mfma_f32_16x16x32_bf16 v[104:107], v[162:165], v[194:197], v[104:107]
	v_mfma_f32_16x16x32_bf16 v[92:95], v[144:147], v[202:205], v[92:95]
	v_mfma_f32_16x16x32_bf16 v[88:91], v[162:165], v[202:205], v[88:91]
	v_mfma_f32_16x16x32_bf16 v[76:79], v[144:147], v[212:215], v[76:79]
	v_mfma_f32_16x16x32_bf16 v[72:75], v[162:165], v[212:215], v[72:75]
	v_mfma_f32_16x16x32_bf16 v[116:119], v[166:169], v[182:185], v[116:119]
	v_mfma_f32_16x16x32_bf16 v[112:115], v[174:177], v[182:185], v[112:115]
	v_mfma_f32_16x16x32_bf16 v[100:103], v[166:169], v[190:193], v[100:103]
	v_mfma_f32_16x16x32_bf16 v[96:99], v[174:177], v[190:193], v[96:99]
	v_mfma_f32_16x16x32_bf16 v[84:87], v[166:169], v[198:201], v[84:87]
	v_mfma_f32_16x16x32_bf16 v[80:83], v[174:177], v[198:201], v[80:83]
	v_mfma_f32_16x16x32_bf16 v[68:71], v[166:169], v[208:211], v[68:71]
	v_mfma_f32_16x16x32_bf16 v[64:67], v[174:177], v[208:211], v[64:67]
	v_mfma_f32_16x16x32_bf16 v[116:119], v[170:173], v[186:189], v[116:119]
	v_mfma_f32_16x16x32_bf16 v[112:115], v[178:181], v[186:189], v[112:115]
	v_mfma_f32_16x16x32_bf16 v[100:103], v[170:173], v[194:197], v[100:103]
	v_mfma_f32_16x16x32_bf16 v[96:99], v[178:181], v[194:197], v[96:99]
	v_mfma_f32_16x16x32_bf16 v[84:87], v[170:173], v[202:205], v[84:87]
	v_mfma_f32_16x16x32_bf16 v[80:83], v[178:181], v[202:205], v[80:83]
	v_mfma_f32_16x16x32_bf16 v[68:71], v[170:173], v[212:215], v[68:71]
	v_mfma_f32_16x16x32_bf16 v[64:67], v[178:181], v[212:215], v[64:67]
	s_barrier
	s_bitcmp1_b32 s97, 0
	s_cbranch_scc1 .Lstg_17_3_b
	s_add_i32 s40, s62, s45
	s_mov_b32 m0, s40
	s_nop 0
	global_load_lds_dwordx4 v148, s[38:39]
	s_add_i32 m0, s40, 0x2000
	s_add_u32 s38, s38, 0x40080
	s_addc_u32 s39, s39, 0
	s_add_i32 s40, s63, s45
	global_load_lds_dwordx4 v149, s[98:99]
	s_mov_b32 m0, s40
	s_nop 0
	global_load_lds_dwordx4 v128, s[38:39]
	s_add_i32 m0, s40, 0x2000
	s_nop 0
	global_load_lds_dwordx4 v130, s[38:39]
	s_cmp_lg_u32 s61, 12
	s_cbranch_scc1 .Lbal_last_17
	s_mov_b32 m0, s51
	s_nop 0
	global_load_lds_dwordx4 v148, s[100:101]
	s_mov_b32 m0, s52
	s_nop 0
	global_load_lds_dwordx4 v149, s[100:101]
.Lbal_last_17:
	ds_read_b128 v[182:185], v155 offset:49152
	ds_read_b128 v[186:189], v155 offset:50176
	ds_read_b128 v[190:193], v155 offset:51200
	ds_read_b128 v[194:197], v155 offset:52224
	ds_read_b128 v[198:201], v155 offset:53248
	ds_read_b128 v[202:205], v155 offset:54272
	ds_read_b128 v[208:211], v155 offset:55296
	ds_read_b128 v[212:215], v155 offset:56320
	s_branch .Lstg_17_3_j
.Lstg_17_3_b:
	s_add_i32 s40, s62, s45
	s_mov_b32 m0, s40
	ds_read_b128 v[182:185], v155 offset:49152
	ds_read_b128 v[186:189], v155 offset:50176
	ds_read_b128 v[190:193], v155 offset:51200
	ds_read_b128 v[194:197], v155 offset:52224
	ds_read_b128 v[198:201], v155 offset:53248
	ds_read_b128 v[202:205], v155 offset:54272
	ds_read_b128 v[208:211], v155 offset:55296
	ds_read_b128 v[212:215], v155 offset:56320
	global_load_lds_dwordx4 v148, s[38:39]
	s_add_i32 m0, s40, 0x2000
	s_add_u32 s38, s38, 0x40080
	s_addc_u32 s39, s39, 0
	s_add_i32 s40, s63, s45
	global_load_lds_dwordx4 v149, s[98:99]
	s_mov_b32 m0, s40
	s_nop 0
	global_load_lds_dwordx4 v128, s[38:39]
	s_add_i32 m0, s40, 0x2000
	s_nop 0
	global_load_lds_dwordx4 v130, s[38:39]
	s_cmp_lg_u32 s61, 12
	s_cbranch_scc1 .Lbal_last_17_b
	s_mov_b32 m0, s51
	s_nop 0
	global_load_lds_dwordx4 v148, s[100:101]
	s_mov_b32 m0, s52
	s_nop 0
	global_load_lds_dwordx4 v149, s[100:101]
.Lbal_last_17_b:
.Lstg_17_3_j:
	s_waitcnt vmcnt(6)
	s_waitcnt lgkmcnt(0)
	s_barrier
	s_waitcnt lgkmcnt(0)
	v_mfma_f32_16x16x32_bf16 v[60:63], v[140:143], v[182:185], v[60:63]
	v_mfma_f32_16x16x32_bf16 v[56:59], v[158:161], v[182:185], v[56:59]
	v_mfma_f32_16x16x32_bf16 v[44:47], v[140:143], v[190:193], v[44:47]
	v_mfma_f32_16x16x32_bf16 v[40:43], v[158:161], v[190:193], v[40:43]
	v_mfma_f32_16x16x32_bf16 v[28:31], v[140:143], v[198:201], v[28:31]
	v_mfma_f32_16x16x32_bf16 v[24:27], v[158:161], v[198:201], v[24:27]
	v_mfma_f32_16x16x32_bf16 v[12:15], v[140:143], v[208:211], v[12:15]
	v_mfma_f32_16x16x32_bf16 v[8:11], v[158:161], v[208:211], v[8:11]
	v_mfma_f32_16x16x32_bf16 v[60:63], v[144:147], v[186:189], v[60:63]
	v_mfma_f32_16x16x32_bf16 v[56:59], v[162:165], v[186:189], v[56:59]
	v_mfma_f32_16x16x32_bf16 v[44:47], v[144:147], v[194:197], v[44:47]
	v_mfma_f32_16x16x32_bf16 v[40:43], v[162:165], v[194:197], v[40:43]
	v_mfma_f32_16x16x32_bf16 v[28:31], v[144:147], v[202:205], v[28:31]
	v_mfma_f32_16x16x32_bf16 v[24:27], v[162:165], v[202:205], v[24:27]
	v_mfma_f32_16x16x32_bf16 v[12:15], v[144:147], v[212:215], v[12:15]
	v_mfma_f32_16x16x32_bf16 v[8:11], v[162:165], v[212:215], v[8:11]
	v_mfma_f32_16x16x32_bf16 v[52:55], v[166:169], v[182:185], v[52:55]
	v_mfma_f32_16x16x32_bf16 v[48:51], v[174:177], v[182:185], v[48:51]
	v_mfma_f32_16x16x32_bf16 v[36:39], v[166:169], v[190:193], v[36:39]
	v_mfma_f32_16x16x32_bf16 v[32:35], v[174:177], v[190:193], v[32:35]
	v_mfma_f32_16x16x32_bf16 v[20:23], v[166:169], v[198:201], v[20:23]
	v_mfma_f32_16x16x32_bf16 v[16:19], v[174:177], v[198:201], v[16:19]
	v_mfma_f32_16x16x32_bf16 v[4:7], v[166:169], v[208:211], v[4:7]
	v_mfma_f32_16x16x32_bf16 v[0:3], v[174:177], v[208:211], v[0:3]
	v_mfma_f32_16x16x32_bf16 v[52:55], v[170:173], v[186:189], v[52:55]
	v_mfma_f32_16x16x32_bf16 v[48:51], v[178:181], v[186:189], v[48:51]
	v_mfma_f32_16x16x32_bf16 v[36:39], v[170:173], v[194:197], v[36:39]
	v_mfma_f32_16x16x32_bf16 v[32:35], v[178:181], v[194:197], v[32:35]
	v_mfma_f32_16x16x32_bf16 v[20:23], v[170:173], v[202:205], v[20:23]
	v_mfma_f32_16x16x32_bf16 v[16:19], v[178:181], v[202:205], v[16:19]
	v_mfma_f32_16x16x32_bf16 v[4:7], v[170:173], v[212:215], v[4:7]
	v_mfma_f32_16x16x32_bf16 v[0:3], v[178:181], v[212:215], v[0:3]
	s_barrier
	s_add_i32 s61, s61, 2
	s_add_u32 s59, s59, 0x100
	s_addc_u32 s60, s60, 0
	s_add_u32 s36, s36, 0x100
	s_addc_u32 s37, s37, 0
	s_cmp_gt_u32 s61, 13
	s_cbranch_scc0 .LBB0_895
	s_setprio 0
	s_and_b64 vcc, exec, s[24:25]
	s_cbranch_vccz .LBB0_898
	s_barrier

.LBB0_988:
	s_bitcmp1_b32 s97, 0
	s_cbranch_scc1 .Lstg_16_0_b
	s_cmp_eq_i32 s53, -2
	s_cbranch_scc1 .Lbal_first_16
	s_mov_b32 m0, s43
	s_nop 0
	global_load_lds_dwordx4 v204, s[100:101]
	s_mov_b32 m0, s44
	s_nop 0
	global_load_lds_dwordx4 v220, s[100:101]
.Lbal_first_16:
	s_add_u32 s26, s6, 0xfffc0080
	s_addc_u32 s27, s7, -1
	s_cmp_eq_u32 s53, 12
	s_cselect_b32 s29, s19, s27
	s_cselect_b32 s28, s49, s26
	s_cselect_b32 s27, s17, s52
	s_cselect_b32 s26, s50, s51
	s_add_i32 m0, s25, 0xc000
	s_nop 0
	global_load_lds_dwordx4 v138, s[6:7]
	s_add_i32 m0, s25, 0xe000
	s_nop 0
	global_load_lds_dwordx4 v136, s[6:7]
	ds_read_b128 v[144:147], v151
	ds_read_b128 v[156:159], v151 offset:1024
	ds_read_b128 v[160:163], v151 offset:2048
	ds_read_b128 v[164:167], v151 offset:3072
	ds_read_b128 v[168:171], v152
	ds_read_b128 v[172:175], v152 offset:1024
	ds_read_b128 v[176:179], v152 offset:2048
	ds_read_b128 v[180:183], v152 offset:3072
	ds_read_b128 v[184:187], v153
	ds_read_b128 v[188:191], v153 offset:1024
	ds_read_b128 v[192:195], v153 offset:2048
	ds_read_b128 v[196:199], v153 offset:3072
	ds_read_b128 v[200:203], v153 offset:4096
	ds_read_b128 v[208:211], v153 offset:5120
	ds_read_b128 v[212:215], v153 offset:6144
	ds_read_b128 v[216:219], v153 offset:7168
	s_branch .Lstg_16_0_j

.Lbal_first_16_b:
	ds_read_b128 v[144:147], v151
	ds_read_b128 v[156:159], v151 offset:1024
	ds_read_b128 v[160:163], v151 offset:2048
	ds_read_b128 v[164:167], v151 offset:3072
	ds_read_b128 v[168:171], v152
	ds_read_b128 v[172:175], v152 offset:1024
	ds_read_b128 v[176:179], v152 offset:2048
	ds_read_b128 v[180:183], v152 offset:3072
	s_add_u32 s26, s6, 0xfffc0080
	s_addc_u32 s27, s7, -1
	s_cmp_eq_u32 s53, 12
	s_cselect_b32 s29, s19, s27
	s_cselect_b32 s28, s49, s26
	s_cselect_b32 s27, s17, s52
	s_cselect_b32 s26, s50, s51
	s_add_i32 m0, s25, 0xc000
	ds_read_b128 v[184:187], v153
	ds_read_b128 v[188:191], v153 offset:1024
	ds_read_b128 v[192:195], v153 offset:2048
	ds_read_b128 v[196:199], v153 offset:3072
	ds_read_b128 v[200:203], v153 offset:4096
	ds_read_b128 v[208:211], v153 offset:5120
	ds_read_b128 v[212:215], v153 offset:6144
	ds_read_b128 v[216:219], v153 offset:7168
	global_load_lds_dwordx4 v138, s[6:7]
	s_add_i32 m0, s25, 0xe000
	s_nop 0
	global_load_lds_dwordx4 v136, s[6:7]
.Lstg_16_0_j:
	s_waitcnt vmcnt(8)
	s_waitcnt lgkmcnt(0)
	s_barrier
	s_waitcnt lgkmcnt(0)
	v_mfma_f32_16x16x32_bf16 v[124:127], v[144:147], v[184:187], v[124:127]
	v_mfma_f32_16x16x32_bf16 v[120:123], v[160:163], v[184:187], v[120:123]
	v_mfma_f32_16x16x32_bf16 v[108:111], v[144:147], v[192:195], v[108:111]
	v_mfma_f32_16x16x32_bf16 v[104:107], v[160:163], v[192:195], v[104:107]
	v_mfma_f32_16x16x32_bf16 v[92:95], v[144:147], v[200:203], v[92:95]
	v_mfma_f32_16x16x32_bf16 v[88:91], v[160:163], v[200:203], v[88:91]
	v_mfma_f32_16x16x32_bf16 v[76:79], v[144:147], v[212:215], v[76:79]
	v_mfma_f32_16x16x32_bf16 v[72:75], v[160:163], v[212:215], v[72:75]
	v_mfma_f32_16x16x32_bf16 v[124:127], v[156:159], v[188:191], v[124:127]
	v_mfma_f32_16x16x32_bf16 v[120:123], v[164:167], v[188:191], v[120:123]
	v_mfma_f32_16x16x32_bf16 v[108:111], v[156:159], v[196:199], v[108:111]
	v_mfma_f32_16x16x32_bf16 v[104:107], v[164:167], v[196:199], v[104:107]
	v_mfma_f32_16x16x32_bf16 v[92:95], v[156:159], v[208:211], v[92:95]
	v_mfma_f32_16x16x32_bf16 v[88:91], v[164:167], v[208:211], v[88:91]
	v_mfma_f32_16x16x32_bf16 v[76:79], v[156:159], v[216:219], v[76:79]
	v_mfma_f32_16x16x32_bf16 v[72:75], v[164:167], v[216:219], v[72:75]
	v_mfma_f32_16x16x32_bf16 v[116:119], v[168:171], v[184:187], v[116:119]
	v_mfma_f32_16x16x32_bf16 v[112:115], v[176:179], v[184:187], v[112:115]
	v_mfma_f32_16x16x32_bf16 v[100:103], v[168:171], v[192:195], v[100:103]
	v_mfma_f32_16x16x32_bf16 v[96:99], v[176:179], v[192:195], v[96:99]
	v_mfma_f32_16x16x32_bf16 v[84:87], v[168:171], v[200:203], v[84:87]
	v_mfma_f32_16x16x32_bf16 v[80:83], v[176:179], v[200:203], v[80:83]
	v_mfma_f32_16x16x32_bf16 v[68:71], v[168:171], v[212:215], v[68:71]
	v_mfma_f32_16x16x32_bf16 v[64:67], v[176:179], v[212:215], v[64:67]
	v_mfma_f32_16x16x32_bf16 v[116:119], v[172:175], v[188:191], v[116:119]
	v_mfma_f32_16x16x32_bf16 v[112:115], v[180:183], v[188:191], v[112:115]
	v_mfma_f32_16x16x32_bf16 v[100:103], v[172:175], v[196:199], v[100:103]
	v_mfma_f32_16x16x32_bf16 v[96:99], v[180:183], v[196:199], v[96:99]
	v_mfma_f32_16x16x32_bf16 v[84:87], v[172:175], v[208:211], v[84:87]
	v_mfma_f32_16x16x32_bf16 v[80:83], v[180:183], v[208:211], v[80:83]
	v_mfma_f32_16x16x32_bf16 v[68:71], v[172:175], v[216:219], v[68:71]
	v_mfma_f32_16x16x32_bf16 v[64:67], v[180:183], v[216:219], v[64:67]
	s_barrier
	s_bitcmp1_b32 s97, 0
	s_cbranch_scc1 .Lstg_16_1_b
	s_add_i32 s54, s45, s38
	s_mov_b32 m0, s54
	s_nop 0
	global_load_lds_dwordx4 v130, s[26:27]
	s_add_i32 m0, s54, 0x2000
	s_add_u32 s54, s26, 0x40000
	s_mov_b64 s[98:99], s[26:27]
	s_addc_u32 s55, s27, 0
	s_add_i32 s56, s46, s38
	global_load_lds_dwordx4 v134, s[26:27]
	s_mov_b32 m0, s56
	s_mov_b64 s[100:101], s[28:29]
	global_load_lds_dwordx4 v130, s[54:55]
	s_add_i32 m0, s56, 0x2000
	s_nop 0
	global_load_lds_dwordx4 v134, s[54:55]
	ds_read_b128 v[184:187], v153 offset:16384
	ds_read_b128 v[188:191], v153 offset:17408
	ds_read_b128 v[192:195], v153 offset:18432
	ds_read_b128 v[196:199], v153 offset:19456
	ds_read_b128 v[200:203], v153 offset:20480
	ds_read_b128 v[208:211], v153 offset:21504
	ds_read_b128 v[212:215], v153 offset:22528
	ds_read_b128 v[216:219], v153 offset:23552
	s_branch .Lstg_16_1_j
.Lstg_16_1_b:
	s_add_i32 s54, s45, s38
	s_mov_b32 m0, s54
	ds_read_b128 v[184:187], v153 offset:16384
	ds_read_b128 v[188:191], v153 offset:17408
	ds_read_b128 v[192:195], v153 offset:18432
	ds_read_b128 v[196:199], v153 offset:19456
	ds_read_b128 v[200:203], v153 offset:20480
	ds_read_b128 v[208:211], v153 offset:21504
	ds_read_b128 v[212:215], v153 offset:22528
	ds_read_b128 v[216:219], v153 offset:23552
	global_load_lds_dwordx4 v130, s[26:27]
	s_add_i32 m0, s54, 0x2000
	s_add_u32 s54, s26, 0x40000
	s_mov_b64 s[98:99], s[26:27]
	s_addc_u32 s55, s27, 0
	s_add_i32 s56, s46, s38
	global_load_lds_dwordx4 v134, s[26:27]
	s_mov_b32 m0, s56
	s_mov_b64 s[100:101], s[28:29]
	global_load_lds_dwordx4 v130, s[54:55]
	s_add_i32 m0, s56, 0x2000
	s_nop 0
	global_load_lds_dwordx4 v134, s[54:55]
.Lstg_16_1_j:
	s_waitcnt vmcnt(6)
	s_waitcnt lgkmcnt(0)
	s_barrier
	s_waitcnt lgkmcnt(0)
	v_mfma_f32_16x16x32_bf16 v[60:63], v[144:147], v[184:187], v[60:63]
	v_mfma_f32_16x16x32_bf16 v[56:59], v[160:163], v[184:187], v[56:59]
	v_mfma_f32_16x16x32_bf16 v[44:47], v[144:147], v[192:195], v[44:47]
	v_mfma_f32_16x16x32_bf16 v[40:43], v[160:163], v[192:195], v[40:43]
	v_mfma_f32_16x16x32_bf16 v[28:31], v[144:147], v[200:203], v[28:31]
	v_mfma_f32_16x16x32_bf16 v[24:27], v[160:163], v[200:203], v[24:27]
	v_mfma_f32_16x16x32_bf16 v[12:15], v[144:147], v[212:215], v[12:15]
	v_mfma_f32_16x16x32_bf16 v[8:11], v[160:163], v[212:215], v[8:11]
	v_mfma_f32_16x16x32_bf16 v[60:63], v[156:159], v[188:191], v[60:63]
	v_mfma_f32_16x16x32_bf16 v[56:59], v[164:167], v[188:191], v[56:59]
	v_mfma_f32_16x16x32_bf16 v[44:47], v[156:159], v[196:199], v[44:47]
	v_mfma_f32_16x16x32_bf16 v[40:43], v[164:167], v[196:199], v[40:43]
	v_mfma_f32_16x16x32_bf16 v[28:31], v[156:159], v[208:211], v[28:31]
	v_mfma_f32_16x16x32_bf16 v[24:27], v[164:167], v[208:211], v[24:27]
	v_mfma_f32_16x16x32_bf16 v[12:15], v[156:159], v[216:219], v[12:15]
	v_mfma_f32_16x16x32_bf16 v[8:11], v[164:167], v[216:219], v[8:11]
	v_mfma_f32_16x16x32_bf16 v[52:55], v[168:171], v[184:187], v[52:55]
	v_mfma_f32_16x16x32_bf16 v[48:51], v[176:179], v[184:187], v[48:51]
	v_mfma_f32_16x16x32_bf16 v[36:39], v[168:171], v[192:195], v[36:39]
	v_mfma_f32_16x16x32_bf16 v[32:35], v[176:179], v[192:195], v[32:35]
	v_mfma_f32_16x16x32_bf16 v[20:23], v[168:171], v[200:203], v[20:23]
	v_mfma_f32_16x16x32_bf16 v[16:19], v[176:179], v[200:203], v[16:19]
	v_mfma_f32_16x16x32_bf16 v[4:7], v[168:171], v[212:215], v[4:7]
	v_mfma_f32_16x16x32_bf16 v[0:3], v[176:179], v[212:215], v[0:3]
	v_mfma_f32_16x16x32_bf16 v[52:55], v[172:175], v[188:191], v[52:55]
	v_mfma_f32_16x16x32_bf16 v[48:51], v[180:183], v[188:191], v[48:51]
	v_mfma_f32_16x16x32_bf16 v[36:39], v[172:175], v[196:199], v[36:39]
	v_mfma_f32_16x16x32_bf16 v[32:35], v[180:183], v[196:199], v[32:35]
	v_mfma_f32_16x16x32_bf16 v[20:23], v[172:175], v[208:211], v[20:23]
	v_mfma_f32_16x16x32_bf16 v[16:19], v[180:183], v[208:211], v[16:19]
	v_mfma_f32_16x16x32_bf16 v[4:7], v[172:175], v[216:219], v[4:7]
	v_mfma_f32_16x16x32_bf16 v[0:3], v[180:183], v[216:219], v[0:3]
	s_barrier
	s_bitcmp1_b32 s97, 0
	s_cbranch_scc1 .Lstg_16_2_b
	s_mov_b32 m0, s25
	s_nop 0
	global_load_lds_dwordx4 v128, s[28:29]
	s_mov_b32 m0, s39
	s_nop 0
	global_load_lds_dwordx4 v132, s[28:29]
	s_add_i32 s54, 0, 0x18000
	s_add_i32 s55, 0, 0x1c000
	s_add_u32 s28, s28, 0x40000
	s_addc_u32 s29, s29, 0
	s_mov_b32 m0, s40
	s_nop 0
	global_load_lds_dwordx4 v128, s[28:29]
	s_mov_b32 m0, s41
	s_nop 0
	global_load_lds_dwordx4 v132, s[28:29]
	v_add_u32_e32 v155, s54, v149
	ds_read_b128 v[144:147], v155
	ds_read_b128 v[156:159], v155 offset:1024
	ds_read_b128 v[160:163], v155 offset:2048
	ds_read_b128 v[164:167], v155 offset:3072
	v_add_u32_e32 v155, s55, v149
	ds_read_b128 v[168:171], v155
	ds_read_b128 v[172:175], v155 offset:1024
	ds_read_b128 v[176:179], v155 offset:2048
	ds_read_b128 v[180:183], v155 offset:3072
	ds_read_b128 v[184:187], v153 offset:32768
	ds_read_b128 v[188:191], v153 offset:33792
	ds_read_b128 v[192:195], v153 offset:34816
	ds_read_b128 v[196:199], v153 offset:35840
	ds_read_b128 v[200:203], v153 offset:36864
	ds_read_b128 v[208:211], v153 offset:37888
	ds_read_b128 v[212:215], v153 offset:38912
	ds_read_b128 v[216:219], v153 offset:39936
	s_branch .Lstg_16_2_j
.Lstg_16_2_b:
	s_mov_b32 m0, s25
	s_nop 0
	global_load_lds_dwordx4 v128, s[28:29]
	s_mov_b32 m0, s39
	s_nop 0
	global_load_lds_dwordx4 v132, s[28:29]
	s_add_i32 s54, 0, 0x18000
	v_add_u32_e32 v155, s54, v149
	s_add_i32 s55, 0, 0x1c000
	ds_read_b128 v[144:147], v155
	ds_read_b128 v[156:159], v155 offset:1024
	ds_read_b128 v[160:163], v155 offset:2048
	ds_read_b128 v[164:167], v155 offset:3072
	v_add_u32_e32 v155, s55, v149
	ds_read_b128 v[168:171], v155
	ds_read_b128 v[172:175], v155 offset:1024
	ds_read_b128 v[176:179], v155 offset:2048
	ds_read_b128 v[180:183], v155 offset:3072
	s_add_u32 s28, s28, 0x40000
	s_addc_u32 s29, s29, 0
	s_mov_b32 m0, s40
	ds_read_b128 v[184:187], v153 offset:32768
	ds_read_b128 v[188:191], v153 offset:33792
	ds_read_b128 v[192:195], v153 offset:34816
	ds_read_b128 v[196:199], v153 offset:35840
	ds_read_b128 v[200:203], v153 offset:36864
	ds_read_b128 v[208:211], v153 offset:37888
	ds_read_b128 v[212:215], v153 offset:38912
	ds_read_b128 v[216:219], v153 offset:39936
	global_load_lds_dwordx4 v128, s[28:29]
	s_mov_b32 m0, s41
	s_nop 0
	global_load_lds_dwordx4 v132, s[28:29]
.Lstg_16_2_j:
	s_waitcnt vmcnt(8)
	s_waitcnt lgkmcnt(0)
	s_barrier
	s_waitcnt lgkmcnt(0)
	v_mfma_f32_16x16x32_bf16 v[124:127], v[144:147], v[184:187], v[124:127]
	v_mfma_f32_16x16x32_bf16 v[120:123], v[160:163], v[184:187], v[120:123]
	v_mfma_f32_16x16x32_bf16 v[108:111], v[144:147], v[192:195], v[108:111]
	v_mfma_f32_16x16x32_bf16 v[104:107], v[160:163], v[192:195], v[104:107]
	v_mfma_f32_16x16x32_bf16 v[92:95], v[144:147], v[200:203], v[92:95]
	v_mfma_f32_16x16x32_bf16 v[88:91], v[160:163], v[200:203], v[88:91]
	v_mfma_f32_16x16x32_bf16 v[76:79], v[144:147], v[212:215], v[76:79]
	v_mfma_f32_16x16x32_bf16 v[72:75], v[160:163], v[212:215], v[72:75]
	v_mfma_f32_16x16x32_bf16 v[124:127], v[156:159], v[188:191], v[124:127]
	v_mfma_f32_16x16x32_bf16 v[120:123], v[164:167], v[188:191], v[120:123]
	v_mfma_f32_16x16x32_bf16 v[108:111], v[156:159], v[196:199], v[108:111]
	v_mfma_f32_16x16x32_bf16 v[104:107], v[164:167], v[196:199], v[104:107]
	v_mfma_f32_16x16x32_bf16 v[92:95], v[156:159], v[208:211], v[92:95]
	v_mfma_f32_16x16x32_bf16 v[88:91], v[164:167], v[208:211], v[88:91]
	v_mfma_f32_16x16x32_bf16 v[76:79], v[156:159], v[216:219], v[76:79]
	v_mfma_f32_16x16x32_bf16 v[72:75], v[164:167], v[216:219], v[72:75]
	v_mfma_f32_16x16x32_bf16 v[116:119], v[168:171], v[184:187], v[116:119]
	v_mfma_f32_16x16x32_bf16 v[112:115], v[176:179], v[184:187], v[112:115]
	v_mfma_f32_16x16x32_bf16 v[100:103], v[168:171], v[192:195], v[100:103]
	v_mfma_f32_16x16x32_bf16 v[96:99], v[176:179], v[192:195], v[96:99]
	v_mfma_f32_16x16x32_bf16 v[84:87], v[168:171], v[200:203], v[84:87]
	v_mfma_f32_16x16x32_bf16 v[80:83], v[176:179], v[200:203], v[80:83]
	v_mfma_f32_16x16x32_bf16 v[68:71], v[168:171], v[212:215], v[68:71]
	v_mfma_f32_16x16x32_bf16 v[64:67], v[176:179], v[212:215], v[64:67]
	v_mfma_f32_16x16x32_bf16 v[116:119], v[172:175], v[188:191], v[116:119]
	v_mfma_f32_16x16x32_bf16 v[112:115], v[180:183], v[188:191], v[112:115]
	v_mfma_f32_16x16x32_bf16 v[100:103], v[172:175], v[196:199], v[100:103]
	v_mfma_f32_16x16x32_bf16 v[96:99], v[180:183], v[196:199], v[96:99]
	v_mfma_f32_16x16x32_bf16 v[84:87], v[172:175], v[208:211], v[84:87]
	v_mfma_f32_16x16x32_bf16 v[80:83], v[180:183], v[208:211], v[80:83]
	v_mfma_f32_16x16x32_bf16 v[68:71], v[172:175], v[216:219], v[68:71]
	v_mfma_f32_16x16x32_bf16 v[64:67], v[180:183], v[216:219], v[64:67]
	s_barrier
	s_bitcmp1_b32 s97, 0
	s_cbranch_scc1 .Lstg_16_3_b
	s_add_i32 s28, s54, s38
	s_mov_b32 m0, s28
	s_nop 0
	global_load_lds_dwordx4 v205, s[26:27]
	s_add_i32 m0, s28, 0x2000
	s_add_u32 s26, s26, 0x40080
	s_addc_u32 s27, s27, 0
	s_add_i32 s28, s55, s38
	global_load_lds_dwordx4 v221, s[98:99]
	s_mov_b32 m0, s28
	s_nop 0
	global_load_lds_dwordx4 v130, s[26:27]
	s_add_i32 m0, s28, 0x2000
	s_nop 0
	global_load_lds_dwordx4 v134, s[26:27]
	s_cmp_lg_u32 s53, 12
	s_cbranch_scc1 .Lbal_last_16
	s_mov_b32 m0, s43
	s_nop 0
	global_load_lds_dwordx4 v204, s[100:101]
	s_mov_b32 m0, s44
	s_nop 0
	global_load_lds_dwordx4 v220, s[100:101]

.Lstg_16_3_b:
	s_add_i32 s28, s54, s38
	s_mov_b32 m0, s28
	ds_read_b128 v[184:187], v153 offset:49152
	ds_read_b128 v[188:191], v153 offset:50176
	ds_read_b128 v[192:195], v153 offset:51200
	ds_read_b128 v[196:199], v153 offset:52224
	ds_read_b128 v[200:203], v153 offset:53248
	ds_read_b128 v[208:211], v153 offset:54272
	ds_read_b128 v[212:215], v153 offset:55296
	ds_read_b128 v[216:219], v153 offset:56320
	global_load_lds_dwordx4 v205, s[26:27]
	s_add_i32 m0, s28, 0x2000
	s_add_u32 s26, s26, 0x40080
	s_addc_u32 s27, s27, 0
	s_add_i32 s28, s55, s38
	global_load_lds_dwordx4 v221, s[98:99]
	s_mov_b32 m0, s28
	s_nop 0
	global_load_lds_dwordx4 v130, s[26:27]
	s_add_i32 m0, s28, 0x2000
	s_nop 0
	global_load_lds_dwordx4 v134, s[26:27]
	s_cmp_lg_u32 s53, 12
	s_cbranch_scc1 .Lbal_last_16_b
	s_mov_b32 m0, s43
	s_nop 0
	global_load_lds_dwordx4 v204, s[100:101]
	s_mov_b32 m0, s44
	s_nop 0
	global_load_lds_dwordx4 v220, s[100:101]
.Lbal_last_16_b:
.Lstg_16_3_j:
	s_waitcnt vmcnt(6)
	s_waitcnt lgkmcnt(0)
	s_barrier
	s_waitcnt lgkmcnt(0)
	v_mfma_f32_16x16x32_bf16 v[60:63], v[144:147], v[184:187], v[60:63]
	v_mfma_f32_16x16x32_bf16 v[56:59], v[160:163], v[184:187], v[56:59]
	v_mfma_f32_16x16x32_bf16 v[44:47], v[144:147], v[192:195], v[44:47]
	v_mfma_f32_16x16x32_bf16 v[40:43], v[160:163], v[192:195], v[40:43]
	v_mfma_f32_16x16x32_bf16 v[28:31], v[144:147], v[200:203], v[28:31]
	v_mfma_f32_16x16x32_bf16 v[24:27], v[160:163], v[200:203], v[24:27]
	v_mfma_f32_16x16x32_bf16 v[12:15], v[144:147], v[212:215], v[12:15]
	v_mfma_f32_16x16x32_bf16 v[8:11], v[160:163], v[212:215], v[8:11]
	v_mfma_f32_16x16x32_bf16 v[60:63], v[156:159], v[188:191], v[60:63]
	v_mfma_f32_16x16x32_bf16 v[56:59], v[164:167], v[188:191], v[56:59]
	v_mfma_f32_16x16x32_bf16 v[44:47], v[156:159], v[196:199], v[44:47]
	v_mfma_f32_16x16x32_bf16 v[40:43], v[164:167], v[196:199], v[40:43]
	v_mfma_f32_16x16x32_bf16 v[28:31], v[156:159], v[208:211], v[28:31]
	v_mfma_f32_16x16x32_bf16 v[24:27], v[164:167], v[208:211], v[24:27]
	v_mfma_f32_16x16x32_bf16 v[12:15], v[156:159], v[216:219], v[12:15]
	v_mfma_f32_16x16x32_bf16 v[8:11], v[164:167], v[216:219], v[8:11]
	v_mfma_f32_16x16x32_bf16 v[52:55], v[168:171], v[184:187], v[52:55]
	v_mfma_f32_16x16x32_bf16 v[48:51], v[176:179], v[184:187], v[48:51]
	v_mfma_f32_16x16x32_bf16 v[36:39], v[168:171], v[192:195], v[36:39]
	v_mfma_f32_16x16x32_bf16 v[32:35], v[176:179], v[192:195], v[32:35]
	v_mfma_f32_16x16x32_bf16 v[20:23], v[168:171], v[200:203], v[20:23]
	v_mfma_f32_16x16x32_bf16 v[16:19], v[176:179], v[200:203], v[16:19]
	v_mfma_f32_16x16x32_bf16 v[4:7], v[168:171], v[212:215], v[4:7]
	v_mfma_f32_16x16x32_bf16 v[0:3], v[176:179], v[212:215], v[0:3]
	v_mfma_f32_16x16x32_bf16 v[52:55], v[172:175], v[188:191], v[52:55]
	v_mfma_f32_16x16x32_bf16 v[48:51], v[180:183], v[188:191], v[48:51]
	v_mfma_f32_16x16x32_bf16 v[36:39], v[172:175], v[196:199], v[36:39]
	v_mfma_f32_16x16x32_bf16 v[32:35], v[180:183], v[196:199], v[32:35]
	v_mfma_f32_16x16x32_bf16 v[20:23], v[172:175], v[208:211], v[20:23]
	v_mfma_f32_16x16x32_bf16 v[16:19], v[180:183], v[208:211], v[16:19]
	v_mfma_f32_16x16x32_bf16 v[4:7], v[172:175], v[216:219], v[4:7]
	v_mfma_f32_16x16x32_bf16 v[0:3], v[180:183], v[216:219], v[0:3]
	s_barrier
	s_add_i32 s53, s53, 2
	s_add_u32 s51, s51, 0x100
	s_addc_u32 s52, s52, 0
	s_add_u32 s6, s6, 0x100
	s_addc_u32 s7, s7, 0
	s_cmp_gt_u32 s53, 13
	s_cbranch_scc0 .LBB0_988
	s_setprio 0
	s_and_b64 vcc, exec, s[14:15]
	s_cbranch_vccz .LBB0_991
	s_barrier

.LBB0_1193:
	s_bitcmp1_b32 s97, 0
	s_cbranch_scc1 .Lstg_15_0_b
	s_cmp_eq_i32 s50, -2
	s_cbranch_scc1 .Lbal_first_15
	s_mov_b32 m0, s41
	s_nop 0
	global_load_lds_dwordx4 v216, s[100:101]
	s_mov_b32 m0, s42
	s_nop 0
	global_load_lds_dwordx4 v218, s[100:101]
.Lbal_first_15:
	s_add_u32 s26, s24, 0xfffe0080
	s_addc_u32 s27, s25, -1
	s_cmp_eq_u32 s50, 4
	s_cselect_b32 s29, s17, s27
	s_cselect_b32 s28, s46, s26
	s_cselect_b32 s27, s15, s49
	s_cselect_b32 s26, s47, s48
	s_add_i32 m0, s23, 0xc000
	s_nop 0
	global_load_lds_dwordx4 v138, s[24:25]
	s_add_i32 m0, s23, 0xe000
	s_nop 0
	global_load_lds_dwordx4 v136, s[24:25]
	ds_read_b128 v[144:147], v151
	ds_read_b128 v[154:157], v151 offset:1024
	ds_read_b128 v[158:161], v151 offset:2048
	ds_read_b128 v[162:165], v151 offset:3072
	ds_read_b128 v[166:169], v152
	ds_read_b128 v[170:173], v152 offset:1024
	ds_read_b128 v[174:177], v152 offset:2048
	ds_read_b128 v[178:181], v152 offset:3072
	ds_read_b128 v[182:185], v153
	ds_read_b128 v[186:189], v153 offset:1024
	ds_read_b128 v[190:193], v153 offset:2048
	ds_read_b128 v[194:197], v153 offset:3072
	ds_read_b128 v[198:201], v153 offset:4096
	ds_read_b128 v[202:205], v153 offset:5120
	ds_read_b128 v[208:211], v153 offset:6144
	ds_read_b128 v[212:215], v153 offset:7168
	s_branch .Lstg_15_0_j

.Lbal_first_15_b:
	ds_read_b128 v[144:147], v151
	ds_read_b128 v[154:157], v151 offset:1024
	ds_read_b128 v[158:161], v151 offset:2048
	ds_read_b128 v[162:165], v151 offset:3072
	ds_read_b128 v[166:169], v152
	ds_read_b128 v[170:173], v152 offset:1024
	ds_read_b128 v[174:177], v152 offset:2048
	ds_read_b128 v[178:181], v152 offset:3072
	s_add_u32 s26, s24, 0xfffe0080
	s_addc_u32 s27, s25, -1
	s_cmp_eq_u32 s50, 4
	s_cselect_b32 s29, s17, s27
	s_cselect_b32 s28, s46, s26
	s_cselect_b32 s27, s15, s49
	s_cselect_b32 s26, s47, s48
	s_add_i32 m0, s23, 0xc000
	ds_read_b128 v[182:185], v153
	ds_read_b128 v[186:189], v153 offset:1024
	ds_read_b128 v[190:193], v153 offset:2048
	ds_read_b128 v[194:197], v153 offset:3072
	ds_read_b128 v[198:201], v153 offset:4096
	ds_read_b128 v[202:205], v153 offset:5120
	ds_read_b128 v[208:211], v153 offset:6144
	ds_read_b128 v[212:215], v153 offset:7168
	global_load_lds_dwordx4 v138, s[24:25]
	s_add_i32 m0, s23, 0xe000
	s_nop 0
	global_load_lds_dwordx4 v136, s[24:25]
.Lstg_15_0_j:
	s_waitcnt vmcnt(8)
	s_waitcnt lgkmcnt(0)
	s_barrier
	s_waitcnt lgkmcnt(0)
	v_mfma_f32_16x16x32_bf16 v[124:127], v[144:147], v[182:185], v[124:127]
	v_mfma_f32_16x16x32_bf16 v[120:123], v[158:161], v[182:185], v[120:123]
	v_mfma_f32_16x16x32_bf16 v[108:111], v[144:147], v[190:193], v[108:111]
	v_mfma_f32_16x16x32_bf16 v[104:107], v[158:161], v[190:193], v[104:107]
	v_mfma_f32_16x16x32_bf16 v[92:95], v[144:147], v[198:201], v[92:95]
	v_mfma_f32_16x16x32_bf16 v[88:91], v[158:161], v[198:201], v[88:91]
	v_mfma_f32_16x16x32_bf16 v[76:79], v[144:147], v[208:211], v[76:79]
	v_mfma_f32_16x16x32_bf16 v[72:75], v[158:161], v[208:211], v[72:75]
	v_mfma_f32_16x16x32_bf16 v[124:127], v[154:157], v[186:189], v[124:127]
	v_mfma_f32_16x16x32_bf16 v[120:123], v[162:165], v[186:189], v[120:123]
	v_mfma_f32_16x16x32_bf16 v[108:111], v[154:157], v[194:197], v[108:111]
	v_mfma_f32_16x16x32_bf16 v[104:107], v[162:165], v[194:197], v[104:107]
	v_mfma_f32_16x16x32_bf16 v[92:95], v[154:157], v[202:205], v[92:95]
	v_mfma_f32_16x16x32_bf16 v[88:91], v[162:165], v[202:205], v[88:91]
	v_mfma_f32_16x16x32_bf16 v[76:79], v[154:157], v[212:215], v[76:79]
	v_mfma_f32_16x16x32_bf16 v[72:75], v[162:165], v[212:215], v[72:75]
	v_mfma_f32_16x16x32_bf16 v[116:119], v[166:169], v[182:185], v[116:119]
	v_mfma_f32_16x16x32_bf16 v[112:115], v[174:177], v[182:185], v[112:115]
	v_mfma_f32_16x16x32_bf16 v[100:103], v[166:169], v[190:193], v[100:103]
	v_mfma_f32_16x16x32_bf16 v[96:99], v[174:177], v[190:193], v[96:99]
	v_mfma_f32_16x16x32_bf16 v[84:87], v[166:169], v[198:201], v[84:87]
	v_mfma_f32_16x16x32_bf16 v[80:83], v[174:177], v[198:201], v[80:83]
	v_mfma_f32_16x16x32_bf16 v[68:71], v[166:169], v[208:211], v[68:71]
	v_mfma_f32_16x16x32_bf16 v[64:67], v[174:177], v[208:211], v[64:67]
	v_mfma_f32_16x16x32_bf16 v[116:119], v[170:173], v[186:189], v[116:119]
	v_mfma_f32_16x16x32_bf16 v[112:115], v[178:181], v[186:189], v[112:115]
	v_mfma_f32_16x16x32_bf16 v[100:103], v[170:173], v[194:197], v[100:103]
	v_mfma_f32_16x16x32_bf16 v[96:99], v[178:181], v[194:197], v[96:99]
	v_mfma_f32_16x16x32_bf16 v[84:87], v[170:173], v[202:205], v[84:87]
	v_mfma_f32_16x16x32_bf16 v[80:83], v[178:181], v[202:205], v[80:83]
	v_mfma_f32_16x16x32_bf16 v[68:71], v[170:173], v[212:215], v[68:71]
	v_mfma_f32_16x16x32_bf16 v[64:67], v[178:181], v[212:215], v[64:67]
	s_barrier
	s_bitcmp1_b32 s97, 0
	s_cbranch_scc1 .Lstg_15_1_b
	s_add_i32 s51, s43, s36
	s_mov_b32 m0, s51
	s_nop 0
	global_load_lds_dwordx4 v130, s[26:27]
	s_add_i32 m0, s51, 0x2000
	s_add_u32 s52, s26, 0x20000
	s_mov_b64 s[98:99], s[26:27]
	s_addc_u32 s53, s27, 0
	s_add_i32 s51, s44, s36
	global_load_lds_dwordx4 v134, s[26:27]
	s_mov_b32 m0, s51
	s_mov_b64 s[100:101], s[28:29]
	global_load_lds_dwordx4 v130, s[52:53]
	s_add_i32 m0, s51, 0x2000
	s_nop 0
	global_load_lds_dwordx4 v134, s[52:53]
	ds_read_b128 v[182:185], v153 offset:16384
	ds_read_b128 v[186:189], v153 offset:17408
	ds_read_b128 v[190:193], v153 offset:18432
	ds_read_b128 v[194:197], v153 offset:19456
	ds_read_b128 v[198:201], v153 offset:20480
	ds_read_b128 v[202:205], v153 offset:21504
	ds_read_b128 v[208:211], v153 offset:22528
	ds_read_b128 v[212:215], v153 offset:23552
	s_branch .Lstg_15_1_j
.Lstg_15_1_b:
	s_add_i32 s51, s43, s36
	s_mov_b32 m0, s51
	ds_read_b128 v[182:185], v153 offset:16384
	ds_read_b128 v[186:189], v153 offset:17408
	ds_read_b128 v[190:193], v153 offset:18432
	ds_read_b128 v[194:197], v153 offset:19456
	ds_read_b128 v[198:201], v153 offset:20480
	ds_read_b128 v[202:205], v153 offset:21504
	ds_read_b128 v[208:211], v153 offset:22528
	ds_read_b128 v[212:215], v153 offset:23552
	global_load_lds_dwordx4 v130, s[26:27]
	s_add_i32 m0, s51, 0x2000
	s_add_u32 s52, s26, 0x20000
	s_mov_b64 s[98:99], s[26:27]
	s_addc_u32 s53, s27, 0
	s_add_i32 s51, s44, s36
	global_load_lds_dwordx4 v134, s[26:27]
	s_mov_b32 m0, s51
	s_mov_b64 s[100:101], s[28:29]
	global_load_lds_dwordx4 v130, s[52:53]
	s_add_i32 m0, s51, 0x2000
	s_nop 0
	global_load_lds_dwordx4 v134, s[52:53]
.Lstg_15_1_j:
	s_waitcnt vmcnt(6)
	s_waitcnt lgkmcnt(0)
	s_barrier
	s_waitcnt lgkmcnt(0)
	v_mfma_f32_16x16x32_bf16 v[60:63], v[144:147], v[182:185], v[60:63]
	v_mfma_f32_16x16x32_bf16 v[56:59], v[158:161], v[182:185], v[56:59]
	v_mfma_f32_16x16x32_bf16 v[44:47], v[144:147], v[190:193], v[44:47]
	v_mfma_f32_16x16x32_bf16 v[40:43], v[158:161], v[190:193], v[40:43]
	v_mfma_f32_16x16x32_bf16 v[28:31], v[144:147], v[198:201], v[28:31]
	v_mfma_f32_16x16x32_bf16 v[24:27], v[158:161], v[198:201], v[24:27]
	v_mfma_f32_16x16x32_bf16 v[12:15], v[144:147], v[208:211], v[12:15]
	v_mfma_f32_16x16x32_bf16 v[8:11], v[158:161], v[208:211], v[8:11]
	v_mfma_f32_16x16x32_bf16 v[60:63], v[154:157], v[186:189], v[60:63]
	v_mfma_f32_16x16x32_bf16 v[56:59], v[162:165], v[186:189], v[56:59]
	v_mfma_f32_16x16x32_bf16 v[44:47], v[154:157], v[194:197], v[44:47]
	v_mfma_f32_16x16x32_bf16 v[40:43], v[162:165], v[194:197], v[40:43]
	v_mfma_f32_16x16x32_bf16 v[28:31], v[154:157], v[202:205], v[28:31]
	v_mfma_f32_16x16x32_bf16 v[24:27], v[162:165], v[202:205], v[24:27]
	v_mfma_f32_16x16x32_bf16 v[12:15], v[154:157], v[212:215], v[12:15]
	v_mfma_f32_16x16x32_bf16 v[8:11], v[162:165], v[212:215], v[8:11]
	v_mfma_f32_16x16x32_bf16 v[52:55], v[166:169], v[182:185], v[52:55]
	v_mfma_f32_16x16x32_bf16 v[48:51], v[174:177], v[182:185], v[48:51]
	v_mfma_f32_16x16x32_bf16 v[36:39], v[166:169], v[190:193], v[36:39]
	v_mfma_f32_16x16x32_bf16 v[32:35], v[174:177], v[190:193], v[32:35]
	v_mfma_f32_16x16x32_bf16 v[20:23], v[166:169], v[198:201], v[20:23]
	v_mfma_f32_16x16x32_bf16 v[16:19], v[174:177], v[198:201], v[16:19]
	v_mfma_f32_16x16x32_bf16 v[4:7], v[166:169], v[208:211], v[4:7]
	v_mfma_f32_16x16x32_bf16 v[0:3], v[174:177], v[208:211], v[0:3]
	v_mfma_f32_16x16x32_bf16 v[52:55], v[170:173], v[186:189], v[52:55]
	v_mfma_f32_16x16x32_bf16 v[48:51], v[178:181], v[186:189], v[48:51]
	v_mfma_f32_16x16x32_bf16 v[36:39], v[170:173], v[194:197], v[36:39]
	v_mfma_f32_16x16x32_bf16 v[32:35], v[178:181], v[194:197], v[32:35]
	v_mfma_f32_16x16x32_bf16 v[20:23], v[170:173], v[202:205], v[20:23]
	v_mfma_f32_16x16x32_bf16 v[16:19], v[178:181], v[202:205], v[16:19]
	v_mfma_f32_16x16x32_bf16 v[4:7], v[170:173], v[212:215], v[4:7]
	v_mfma_f32_16x16x32_bf16 v[0:3], v[178:181], v[212:215], v[0:3]
	s_barrier
	s_bitcmp1_b32 s97, 0
	s_cbranch_scc1 .Lstg_15_2_b
	s_mov_b32 m0, s23
	s_nop 0
	global_load_lds_dwordx4 v128, s[28:29]
	s_mov_b32 m0, s37
	s_nop 0
	global_load_lds_dwordx4 v132, s[28:29]
	s_add_i32 s51, 0, 0x18000
	s_add_i32 s52, 0, 0x1c000
	s_add_u32 s28, s28, 0x20000
	s_addc_u32 s29, s29, 0
	s_mov_b32 m0, s38
	s_nop 0
	global_load_lds_dwordx4 v128, s[28:29]
	s_mov_b32 m0, s39
	s_nop 0
	global_load_lds_dwordx4 v132, s[28:29]
	v_add_u32_e32 v162, s51, v149
	v_add_u32_e32 v178, s52, v149
	ds_read_b128 v[144:147], v162
	ds_read_b128 v[154:157], v162 offset:1024
	ds_read_b128 v[158:161], v162 offset:2048
	ds_read_b128 v[162:165], v162 offset:3072
	ds_read_b128 v[166:169], v178
	ds_read_b128 v[170:173], v178 offset:1024
	ds_read_b128 v[174:177], v178 offset:2048
	ds_read_b128 v[178:181], v178 offset:3072
	ds_read_b128 v[182:185], v153 offset:32768
	ds_read_b128 v[186:189], v153 offset:33792
	ds_read_b128 v[190:193], v153 offset:34816
	ds_read_b128 v[194:197], v153 offset:35840
	ds_read_b128 v[198:201], v153 offset:36864
	ds_read_b128 v[202:205], v153 offset:37888
	ds_read_b128 v[208:211], v153 offset:38912
	ds_read_b128 v[212:215], v153 offset:39936
	s_branch .Lstg_15_2_j
.Lstg_15_2_b:
	s_mov_b32 m0, s23
	s_nop 0
	global_load_lds_dwordx4 v128, s[28:29]
	s_mov_b32 m0, s37
	s_nop 0
	global_load_lds_dwordx4 v132, s[28:29]
	s_add_i32 s51, 0, 0x18000
	s_add_i32 s52, 0, 0x1c000
	v_add_u32_e32 v162, s51, v149
	v_add_u32_e32 v178, s52, v149
	ds_read_b128 v[144:147], v162
	ds_read_b128 v[154:157], v162 offset:1024
	ds_read_b128 v[158:161], v162 offset:2048
	ds_read_b128 v[162:165], v162 offset:3072
	ds_read_b128 v[166:169], v178
	ds_read_b128 v[170:173], v178 offset:1024
	ds_read_b128 v[174:177], v178 offset:2048
	ds_read_b128 v[178:181], v178 offset:3072
	s_add_u32 s28, s28, 0x20000
	s_addc_u32 s29, s29, 0
	s_mov_b32 m0, s38
	ds_read_b128 v[182:185], v153 offset:32768
	ds_read_b128 v[186:189], v153 offset:33792
	ds_read_b128 v[190:193], v153 offset:34816
	ds_read_b128 v[194:197], v153 offset:35840
	ds_read_b128 v[198:201], v153 offset:36864
	ds_read_b128 v[202:205], v153 offset:37888
	ds_read_b128 v[208:211], v153 offset:38912
	ds_read_b128 v[212:215], v153 offset:39936
	global_load_lds_dwordx4 v128, s[28:29]
	s_mov_b32 m0, s39
	s_nop 0
	global_load_lds_dwordx4 v132, s[28:29]
.Lstg_15_2_j:
	s_waitcnt vmcnt(8)
	s_waitcnt lgkmcnt(0)
	s_barrier
	s_waitcnt lgkmcnt(0)
	v_mfma_f32_16x16x32_bf16 v[124:127], v[144:147], v[182:185], v[124:127]
	v_mfma_f32_16x16x32_bf16 v[120:123], v[158:161], v[182:185], v[120:123]
	v_mfma_f32_16x16x32_bf16 v[108:111], v[144:147], v[190:193], v[108:111]
	v_mfma_f32_16x16x32_bf16 v[104:107], v[158:161], v[190:193], v[104:107]
	v_mfma_f32_16x16x32_bf16 v[92:95], v[144:147], v[198:201], v[92:95]
	v_mfma_f32_16x16x32_bf16 v[88:91], v[158:161], v[198:201], v[88:91]
	v_mfma_f32_16x16x32_bf16 v[76:79], v[144:147], v[208:211], v[76:79]
	v_mfma_f32_16x16x32_bf16 v[72:75], v[158:161], v[208:211], v[72:75]
	v_mfma_f32_16x16x32_bf16 v[124:127], v[154:157], v[186:189], v[124:127]
	v_mfma_f32_16x16x32_bf16 v[120:123], v[162:165], v[186:189], v[120:123]
	v_mfma_f32_16x16x32_bf16 v[108:111], v[154:157], v[194:197], v[108:111]
	v_mfma_f32_16x16x32_bf16 v[104:107], v[162:165], v[194:197], v[104:107]
	v_mfma_f32_16x16x32_bf16 v[92:95], v[154:157], v[202:205], v[92:95]
	v_mfma_f32_16x16x32_bf16 v[88:91], v[162:165], v[202:205], v[88:91]
	v_mfma_f32_16x16x32_bf16 v[76:79], v[154:157], v[212:215], v[76:79]
	v_mfma_f32_16x16x32_bf16 v[72:75], v[162:165], v[212:215], v[72:75]
	v_mfma_f32_16x16x32_bf16 v[116:119], v[166:169], v[182:185], v[116:119]
	v_mfma_f32_16x16x32_bf16 v[112:115], v[174:177], v[182:185], v[112:115]
	v_mfma_f32_16x16x32_bf16 v[100:103], v[166:169], v[190:193], v[100:103]
	v_mfma_f32_16x16x32_bf16 v[96:99], v[174:177], v[190:193], v[96:99]
	v_mfma_f32_16x16x32_bf16 v[84:87], v[166:169], v[198:201], v[84:87]
	v_mfma_f32_16x16x32_bf16 v[80:83], v[174:177], v[198:201], v[80:83]
	v_mfma_f32_16x16x32_bf16 v[68:71], v[166:169], v[208:211], v[68:71]
	v_mfma_f32_16x16x32_bf16 v[64:67], v[174:177], v[208:211], v[64:67]
	v_mfma_f32_16x16x32_bf16 v[116:119], v[170:173], v[186:189], v[116:119]
	v_mfma_f32_16x16x32_bf16 v[112:115], v[178:181], v[186:189], v[112:115]
	v_mfma_f32_16x16x32_bf16 v[100:103], v[170:173], v[194:197], v[100:103]
	v_mfma_f32_16x16x32_bf16 v[96:99], v[178:181], v[194:197], v[96:99]
	v_mfma_f32_16x16x32_bf16 v[84:87], v[170:173], v[202:205], v[84:87]
	v_mfma_f32_16x16x32_bf16 v[80:83], v[178:181], v[202:205], v[80:83]
	v_mfma_f32_16x16x32_bf16 v[68:71], v[170:173], v[212:215], v[68:71]
	v_mfma_f32_16x16x32_bf16 v[64:67], v[178:181], v[212:215], v[64:67]
	s_barrier
	s_bitcmp1_b32 s97, 0
	s_cbranch_scc1 .Lstg_15_3_b
	s_add_i32 s28, s51, s36
	s_mov_b32 m0, s28
	s_nop 0
	global_load_lds_dwordx4 v217, s[26:27]
	s_add_i32 m0, s28, 0x2000
	s_add_u32 s26, s26, 0x20080
	s_addc_u32 s27, s27, 0
	s_add_i32 s28, s52, s36
	global_load_lds_dwordx4 v219, s[98:99]
	s_mov_b32 m0, s28
	s_nop 0
	global_load_lds_dwordx4 v130, s[26:27]
	s_add_i32 m0, s28, 0x2000
	s_nop 0
	global_load_lds_dwordx4 v134, s[26:27]
	s_cmp_lg_u32 s50, 4
	s_cbranch_scc1 .Lbal_last_15
	s_mov_b32 m0, s41
	s_nop 0
	global_load_lds_dwordx4 v216, s[100:101]
	s_mov_b32 m0, s42
	s_nop 0
	global_load_lds_dwordx4 v218, s[100:101]
.Lbal_last_15:
	ds_read_b128 v[182:185], v153 offset:49152
	ds_read_b128 v[186:189], v153 offset:50176
	ds_read_b128 v[190:193], v153 offset:51200
	ds_read_b128 v[194:197], v153 offset:52224
	ds_read_b128 v[198:201], v153 offset:53248
	ds_read_b128 v[202:205], v153 offset:54272
	ds_read_b128 v[208:211], v153 offset:55296
	ds_read_b128 v[212:215], v153 offset:56320
	s_branch .Lstg_15_3_j
.Lstg_15_3_b:
	s_add_i32 s28, s51, s36
	s_mov_b32 m0, s28
	ds_read_b128 v[182:185], v153 offset:49152
	ds_read_b128 v[186:189], v153 offset:50176
	ds_read_b128 v[190:193], v153 offset:51200
	ds_read_b128 v[194:197], v153 offset:52224
	ds_read_b128 v[198:201], v153 offset:53248
	ds_read_b128 v[202:205], v153 offset:54272
	ds_read_b128 v[208:211], v153 offset:55296
	ds_read_b128 v[212:215], v153 offset:56320
	global_load_lds_dwordx4 v217, s[26:27]
	s_add_i32 m0, s28, 0x2000
	s_add_u32 s26, s26, 0x20080
	s_addc_u32 s27, s27, 0
	s_add_i32 s28, s52, s36
	global_load_lds_dwordx4 v219, s[98:99]
	s_mov_b32 m0, s28
	s_nop 0
	global_load_lds_dwordx4 v130, s[26:27]
	s_add_i32 m0, s28, 0x2000
	s_nop 0
	global_load_lds_dwordx4 v134, s[26:27]
	s_cmp_lg_u32 s50, 4
	s_cbranch_scc1 .Lbal_last_15_b
	s_mov_b32 m0, s41
	s_nop 0
	global_load_lds_dwordx4 v216, s[100:101]
	s_mov_b32 m0, s42
	s_nop 0
	global_load_lds_dwordx4 v218, s[100:101]
.Lbal_last_15_b:
.Lstg_15_3_j:
	s_waitcnt vmcnt(6)
	s_waitcnt lgkmcnt(0)
	s_barrier
	s_waitcnt lgkmcnt(0)
	v_mfma_f32_16x16x32_bf16 v[60:63], v[144:147], v[182:185], v[60:63]
	v_mfma_f32_16x16x32_bf16 v[56:59], v[158:161], v[182:185], v[56:59]
	v_mfma_f32_16x16x32_bf16 v[44:47], v[144:147], v[190:193], v[44:47]
	v_mfma_f32_16x16x32_bf16 v[40:43], v[158:161], v[190:193], v[40:43]
	v_mfma_f32_16x16x32_bf16 v[28:31], v[144:147], v[198:201], v[28:31]
	v_mfma_f32_16x16x32_bf16 v[24:27], v[158:161], v[198:201], v[24:27]
	v_mfma_f32_16x16x32_bf16 v[12:15], v[144:147], v[208:211], v[12:15]
	v_mfma_f32_16x16x32_bf16 v[8:11], v[158:161], v[208:211], v[8:11]
	v_mfma_f32_16x16x32_bf16 v[60:63], v[154:157], v[186:189], v[60:63]
	v_mfma_f32_16x16x32_bf16 v[56:59], v[162:165], v[186:189], v[56:59]
	v_mfma_f32_16x16x32_bf16 v[44:47], v[154:157], v[194:197], v[44:47]
	v_mfma_f32_16x16x32_bf16 v[40:43], v[162:165], v[194:197], v[40:43]
	v_mfma_f32_16x16x32_bf16 v[28:31], v[154:157], v[202:205], v[28:31]
	v_mfma_f32_16x16x32_bf16 v[24:27], v[162:165], v[202:205], v[24:27]
	v_mfma_f32_16x16x32_bf16 v[12:15], v[154:157], v[212:215], v[12:15]
	v_mfma_f32_16x16x32_bf16 v[8:11], v[162:165], v[212:215], v[8:11]
	v_mfma_f32_16x16x32_bf16 v[52:55], v[166:169], v[182:185], v[52:55]
	v_mfma_f32_16x16x32_bf16 v[48:51], v[174:177], v[182:185], v[48:51]
	v_mfma_f32_16x16x32_bf16 v[36:39], v[166:169], v[190:193], v[36:39]
	v_mfma_f32_16x16x32_bf16 v[32:35], v[174:177], v[190:193], v[32:35]
	v_mfma_f32_16x16x32_bf16 v[20:23], v[166:169], v[198:201], v[20:23]
	v_mfma_f32_16x16x32_bf16 v[16:19], v[174:177], v[198:201], v[16:19]
	v_mfma_f32_16x16x32_bf16 v[4:7], v[166:169], v[208:211], v[4:7]
	v_mfma_f32_16x16x32_bf16 v[0:3], v[174:177], v[208:211], v[0:3]
	v_mfma_f32_16x16x32_bf16 v[52:55], v[170:173], v[186:189], v[52:55]
	v_mfma_f32_16x16x32_bf16 v[48:51], v[178:181], v[186:189], v[48:51]
	v_mfma_f32_16x16x32_bf16 v[36:39], v[170:173], v[194:197], v[36:39]
	v_mfma_f32_16x16x32_bf16 v[32:35], v[178:181], v[194:197], v[32:35]
	v_mfma_f32_16x16x32_bf16 v[20:23], v[170:173], v[202:205], v[20:23]
	v_mfma_f32_16x16x32_bf16 v[16:19], v[178:181], v[202:205], v[16:19]
	v_mfma_f32_16x16x32_bf16 v[4:7], v[170:173], v[212:215], v[4:7]
	v_mfma_f32_16x16x32_bf16 v[0:3], v[178:181], v[212:215], v[0:3]
	s_barrier
	s_add_i32 s50, s50, 2
	s_add_u32 s48, s48, 0x100
	s_addc_u32 s49, s49, 0
	s_add_u32 s24, s24, 0x100
	s_addc_u32 s25, s25, 0
	s_cmp_gt_u32 s50, 5
	s_cbranch_scc0 .LBB0_1193
	s_setprio 0
	s_and_b64 vcc, exec, s[12:13]
	s_cbranch_vccz .LBB0_1196
	s_barrier

.Lbal_first_13:
	s_add_u32 s26, s24, 0xfffc0080
	s_addc_u32 s27, s25, -1
	s_cmp_eq_u32 s53, 12
	s_cselect_b32 s29, s19, s27
	s_cselect_b32 s28, s49, s26
	s_cselect_b32 s27, s17, s52
	s_cselect_b32 s26, s50, s51
	s_add_i32 m0, s39, 0xc000
	s_nop 0
	global_load_lds_dwordx4 v138, s[24:25]
	s_add_i32 m0, s39, 0xe000
	s_nop 0
	global_load_lds_dwordx4 v136, s[24:25]
	ds_read_b128 v[144:147], v151
	ds_read_b128 v[156:159], v151 offset:1024
	ds_read_b128 v[160:163], v151 offset:2048
	ds_read_b128 v[164:167], v151 offset:3072
	ds_read_b128 v[168:171], v152
	ds_read_b128 v[172:175], v152 offset:1024
	ds_read_b128 v[176:179], v152 offset:2048
	ds_read_b128 v[180:183], v152 offset:3072
	ds_read_b128 v[184:187], v153
	ds_read_b128 v[188:191], v153 offset:1024
	ds_read_b128 v[192:195], v153 offset:2048
	ds_read_b128 v[196:199], v153 offset:3072
	ds_read_b128 v[200:203], v153 offset:4096
	ds_read_b128 v[208:211], v153 offset:5120
	ds_read_b128 v[212:215], v153 offset:6144
	ds_read_b128 v[216:219], v153 offset:7168
	s_branch .Lstg_13_0_j

.Lbal_first_13_b:
	ds_read_b128 v[144:147], v151
	ds_read_b128 v[156:159], v151 offset:1024
	ds_read_b128 v[160:163], v151 offset:2048
	ds_read_b128 v[164:167], v151 offset:3072
	ds_read_b128 v[168:171], v152
	ds_read_b128 v[172:175], v152 offset:1024
	ds_read_b128 v[176:179], v152 offset:2048
	ds_read_b128 v[180:183], v152 offset:3072
	s_add_u32 s26, s24, 0xfffc0080
	s_addc_u32 s27, s25, -1
	s_cmp_eq_u32 s53, 12
	s_cselect_b32 s29, s19, s27
	s_cselect_b32 s28, s49, s26
	s_cselect_b32 s27, s17, s52
	s_cselect_b32 s26, s50, s51
	s_add_i32 m0, s39, 0xc000
	ds_read_b128 v[184:187], v153
	ds_read_b128 v[188:191], v153 offset:1024
	ds_read_b128 v[192:195], v153 offset:2048
	ds_read_b128 v[196:199], v153 offset:3072
	ds_read_b128 v[200:203], v153 offset:4096
	ds_read_b128 v[208:211], v153 offset:5120
	ds_read_b128 v[212:215], v153 offset:6144
	ds_read_b128 v[216:219], v153 offset:7168
	global_load_lds_dwordx4 v138, s[24:25]
	s_add_i32 m0, s39, 0xe000
	s_nop 0
	global_load_lds_dwordx4 v136, s[24:25]
.Lstg_13_0_j:
	s_waitcnt vmcnt(8)
	s_waitcnt lgkmcnt(0)
	s_barrier
	s_waitcnt lgkmcnt(0)
	v_mfma_f32_16x16x32_bf16 v[124:127], v[144:147], v[184:187], v[124:127]
	v_mfma_f32_16x16x32_bf16 v[120:123], v[160:163], v[184:187], v[120:123]
	v_mfma_f32_16x16x32_bf16 v[108:111], v[144:147], v[192:195], v[108:111]
	v_mfma_f32_16x16x32_bf16 v[104:107], v[160:163], v[192:195], v[104:107]
	v_mfma_f32_16x16x32_bf16 v[92:95], v[144:147], v[200:203], v[92:95]
	v_mfma_f32_16x16x32_bf16 v[88:91], v[160:163], v[200:203], v[88:91]
	v_mfma_f32_16x16x32_bf16 v[76:79], v[144:147], v[212:215], v[76:79]
	v_mfma_f32_16x16x32_bf16 v[72:75], v[160:163], v[212:215], v[72:75]
	v_mfma_f32_16x16x32_bf16 v[124:127], v[156:159], v[188:191], v[124:127]
	v_mfma_f32_16x16x32_bf16 v[120:123], v[164:167], v[188:191], v[120:123]
	v_mfma_f32_16x16x32_bf16 v[108:111], v[156:159], v[196:199], v[108:111]
	v_mfma_f32_16x16x32_bf16 v[104:107], v[164:167], v[196:199], v[104:107]
	v_mfma_f32_16x16x32_bf16 v[92:95], v[156:159], v[208:211], v[92:95]
	v_mfma_f32_16x16x32_bf16 v[88:91], v[164:167], v[208:211], v[88:91]
	v_mfma_f32_16x16x32_bf16 v[76:79], v[156:159], v[216:219], v[76:79]
	v_mfma_f32_16x16x32_bf16 v[72:75], v[164:167], v[216:219], v[72:75]
	v_mfma_f32_16x16x32_bf16 v[116:119], v[168:171], v[184:187], v[116:119]
	v_mfma_f32_16x16x32_bf16 v[112:115], v[176:179], v[184:187], v[112:115]
	v_mfma_f32_16x16x32_bf16 v[100:103], v[168:171], v[192:195], v[100:103]
	v_mfma_f32_16x16x32_bf16 v[96:99], v[176:179], v[192:195], v[96:99]
	v_mfma_f32_16x16x32_bf16 v[84:87], v[168:171], v[200:203], v[84:87]
	v_mfma_f32_16x16x32_bf16 v[80:83], v[176:179], v[200:203], v[80:83]
	v_mfma_f32_16x16x32_bf16 v[68:71], v[168:171], v[212:215], v[68:71]
	v_mfma_f32_16x16x32_bf16 v[64:67], v[176:179], v[212:215], v[64:67]
	v_mfma_f32_16x16x32_bf16 v[116:119], v[172:175], v[188:191], v[116:119]
	v_mfma_f32_16x16x32_bf16 v[112:115], v[180:183], v[188:191], v[112:115]
	v_mfma_f32_16x16x32_bf16 v[100:103], v[172:175], v[196:199], v[100:103]
	v_mfma_f32_16x16x32_bf16 v[96:99], v[180:183], v[196:199], v[96:99]
	v_mfma_f32_16x16x32_bf16 v[84:87], v[172:175], v[208:211], v[84:87]
	v_mfma_f32_16x16x32_bf16 v[80:83], v[180:183], v[208:211], v[80:83]
	v_mfma_f32_16x16x32_bf16 v[68:71], v[172:175], v[216:219], v[68:71]
	v_mfma_f32_16x16x32_bf16 v[64:67], v[180:183], v[216:219], v[64:67]
	s_barrier
	s_bitcmp1_b32 s97, 0
	s_cbranch_scc1 .Lstg_13_1_b
	s_add_i32 s54, s46, s38
	s_mov_b32 m0, s54
	s_nop 0
	global_load_lds_dwordx4 v130, s[26:27]
	s_add_i32 m0, s54, 0x2000
	s_add_u32 s54, s26, 0x40000
	s_mov_b64 s[98:99], s[26:27]
	s_addc_u32 s55, s27, 0
	s_add_i32 s56, s47, s38
	global_load_lds_dwordx4 v134, s[26:27]
	s_mov_b32 m0, s56
	s_mov_b64 s[100:101], s[28:29]
	global_load_lds_dwordx4 v130, s[54:55]
	s_add_i32 m0, s56, 0x2000
	s_nop 0
	global_load_lds_dwordx4 v134, s[54:55]
	ds_read_b128 v[184:187], v153 offset:16384
	ds_read_b128 v[188:191], v153 offset:17408
	ds_read_b128 v[192:195], v153 offset:18432
	ds_read_b128 v[196:199], v153 offset:19456
	ds_read_b128 v[200:203], v153 offset:20480
	ds_read_b128 v[208:211], v153 offset:21504
	ds_read_b128 v[212:215], v153 offset:22528
	ds_read_b128 v[216:219], v153 offset:23552
	s_branch .Lstg_13_1_j
.Lstg_13_1_b:
	s_add_i32 s54, s46, s38
	s_mov_b32 m0, s54
	ds_read_b128 v[184:187], v153 offset:16384
	ds_read_b128 v[188:191], v153 offset:17408
	ds_read_b128 v[192:195], v153 offset:18432
	ds_read_b128 v[196:199], v153 offset:19456
	ds_read_b128 v[200:203], v153 offset:20480
	ds_read_b128 v[208:211], v153 offset:21504
	ds_read_b128 v[212:215], v153 offset:22528
	ds_read_b128 v[216:219], v153 offset:23552
	global_load_lds_dwordx4 v130, s[26:27]
	s_add_i32 m0, s54, 0x2000
	s_add_u32 s54, s26, 0x40000
	s_mov_b64 s[98:99], s[26:27]
	s_addc_u32 s55, s27, 0
	s_add_i32 s56, s47, s38
	global_load_lds_dwordx4 v134, s[26:27]
	s_mov_b32 m0, s56
	s_mov_b64 s[100:101], s[28:29]
	global_load_lds_dwordx4 v130, s[54:55]
	s_add_i32 m0, s56, 0x2000
	s_nop 0
	global_load_lds_dwordx4 v134, s[54:55]
.Lstg_13_1_j:
	s_waitcnt vmcnt(6)
	s_waitcnt lgkmcnt(0)
	s_barrier
	s_waitcnt lgkmcnt(0)
	v_mfma_f32_16x16x32_bf16 v[60:63], v[144:147], v[184:187], v[60:63]
	v_mfma_f32_16x16x32_bf16 v[56:59], v[160:163], v[184:187], v[56:59]
	v_mfma_f32_16x16x32_bf16 v[44:47], v[144:147], v[192:195], v[44:47]
	v_mfma_f32_16x16x32_bf16 v[40:43], v[160:163], v[192:195], v[40:43]
	v_mfma_f32_16x16x32_bf16 v[28:31], v[144:147], v[200:203], v[28:31]
	v_mfma_f32_16x16x32_bf16 v[24:27], v[160:163], v[200:203], v[24:27]
	v_mfma_f32_16x16x32_bf16 v[12:15], v[144:147], v[212:215], v[12:15]
	v_mfma_f32_16x16x32_bf16 v[8:11], v[160:163], v[212:215], v[8:11]
	v_mfma_f32_16x16x32_bf16 v[60:63], v[156:159], v[188:191], v[60:63]
	v_mfma_f32_16x16x32_bf16 v[56:59], v[164:167], v[188:191], v[56:59]
	v_mfma_f32_16x16x32_bf16 v[44:47], v[156:159], v[196:199], v[44:47]
	v_mfma_f32_16x16x32_bf16 v[40:43], v[164:167], v[196:199], v[40:43]
	v_mfma_f32_16x16x32_bf16 v[28:31], v[156:159], v[208:211], v[28:31]
	v_mfma_f32_16x16x32_bf16 v[24:27], v[164:167], v[208:211], v[24:27]
	v_mfma_f32_16x16x32_bf16 v[12:15], v[156:159], v[216:219], v[12:15]
	v_mfma_f32_16x16x32_bf16 v[8:11], v[164:167], v[216:219], v[8:11]
	v_mfma_f32_16x16x32_bf16 v[52:55], v[168:171], v[184:187], v[52:55]
	v_mfma_f32_16x16x32_bf16 v[48:51], v[176:179], v[184:187], v[48:51]
	v_mfma_f32_16x16x32_bf16 v[36:39], v[168:171], v[192:195], v[36:39]
	v_mfma_f32_16x16x32_bf16 v[32:35], v[176:179], v[192:195], v[32:35]
	v_mfma_f32_16x16x32_bf16 v[20:23], v[168:171], v[200:203], v[20:23]
	v_mfma_f32_16x16x32_bf16 v[16:19], v[176:179], v[200:203], v[16:19]
	v_mfma_f32_16x16x32_bf16 v[4:7], v[168:171], v[212:215], v[4:7]
	v_mfma_f32_16x16x32_bf16 v[0:3], v[176:179], v[212:215], v[0:3]
	v_mfma_f32_16x16x32_bf16 v[52:55], v[172:175], v[188:191], v[52:55]
	v_mfma_f32_16x16x32_bf16 v[48:51], v[180:183], v[188:191], v[48:51]
	v_mfma_f32_16x16x32_bf16 v[36:39], v[172:175], v[196:199], v[36:39]
	v_mfma_f32_16x16x32_bf16 v[32:35], v[180:183], v[196:199], v[32:35]
	v_mfma_f32_16x16x32_bf16 v[20:23], v[172:175], v[208:211], v[20:23]
	v_mfma_f32_16x16x32_bf16 v[16:19], v[180:183], v[208:211], v[16:19]
	v_mfma_f32_16x16x32_bf16 v[4:7], v[172:175], v[216:219], v[4:7]
	v_mfma_f32_16x16x32_bf16 v[0:3], v[180:183], v[216:219], v[0:3]
	s_barrier
	s_bitcmp1_b32 s97, 0
	s_cbranch_scc1 .Lstg_13_2_b
	s_mov_b32 m0, s39
	s_nop 0
	global_load_lds_dwordx4 v128, s[28:29]
	s_mov_b32 m0, s40
	s_nop 0
	global_load_lds_dwordx4 v132, s[28:29]
	s_add_i32 s54, 0, 0x18000
	s_add_i32 s55, 0, 0x1c000
	s_add_u32 s28, s28, 0x40000
	s_addc_u32 s29, s29, 0
	s_mov_b32 m0, s41
	s_nop 0
	global_load_lds_dwordx4 v128, s[28:29]
	s_mov_b32 m0, s42
	s_nop 0
	global_load_lds_dwordx4 v132, s[28:29]
	v_add_u32_e32 v155, s54, v149
	ds_read_b128 v[144:147], v155
	ds_read_b128 v[156:159], v155 offset:1024
	ds_read_b128 v[160:163], v155 offset:2048
	ds_read_b128 v[164:167], v155 offset:3072
	v_add_u32_e32 v155, s55, v149
	ds_read_b128 v[168:171], v155
	ds_read_b128 v[172:175], v155 offset:1024
	ds_read_b128 v[176:179], v155 offset:2048
	ds_read_b128 v[180:183], v155 offset:3072
	ds_read_b128 v[184:187], v153 offset:32768
	ds_read_b128 v[188:191], v153 offset:33792
	ds_read_b128 v[192:195], v153 offset:34816
	ds_read_b128 v[196:199], v153 offset:35840
	ds_read_b128 v[200:203], v153 offset:36864
	ds_read_b128 v[208:211], v153 offset:37888
	ds_read_b128 v[212:215], v153 offset:38912
	ds_read_b128 v[216:219], v153 offset:39936
	s_branch .Lstg_13_2_j
.Lstg_13_2_b:
	s_mov_b32 m0, s39
	s_nop 0
	global_load_lds_dwordx4 v128, s[28:29]
	s_mov_b32 m0, s40
	s_nop 0
	global_load_lds_dwordx4 v132, s[28:29]
	s_add_i32 s54, 0, 0x18000
	v_add_u32_e32 v155, s54, v149
	s_add_i32 s55, 0, 0x1c000
	ds_read_b128 v[144:147], v155
	ds_read_b128 v[156:159], v155 offset:1024
	ds_read_b128 v[160:163], v155 offset:2048
	ds_read_b128 v[164:167], v155 offset:3072
	v_add_u32_e32 v155, s55, v149
	ds_read_b128 v[168:171], v155
	ds_read_b128 v[172:175], v155 offset:1024
	ds_read_b128 v[176:179], v155 offset:2048
	ds_read_b128 v[180:183], v155 offset:3072
	s_add_u32 s28, s28, 0x40000
	s_addc_u32 s29, s29, 0
	s_mov_b32 m0, s41
	ds_read_b128 v[184:187], v153 offset:32768
	ds_read_b128 v[188:191], v153 offset:33792
	ds_read_b128 v[192:195], v153 offset:34816
	ds_read_b128 v[196:199], v153 offset:35840
	ds_read_b128 v[200:203], v153 offset:36864
	ds_read_b128 v[208:211], v153 offset:37888
	ds_read_b128 v[212:215], v153 offset:38912
	ds_read_b128 v[216:219], v153 offset:39936
	global_load_lds_dwordx4 v128, s[28:29]
	s_mov_b32 m0, s42
	s_nop 0
	global_load_lds_dwordx4 v132, s[28:29]
.Lstg_13_2_j:
	s_waitcnt vmcnt(8)
	s_waitcnt lgkmcnt(0)
	s_barrier
	s_waitcnt lgkmcnt(0)
	v_mfma_f32_16x16x32_bf16 v[124:127], v[144:147], v[184:187], v[124:127]
	v_mfma_f32_16x16x32_bf16 v[120:123], v[160:163], v[184:187], v[120:123]
	v_mfma_f32_16x16x32_bf16 v[108:111], v[144:147], v[192:195], v[108:111]
	v_mfma_f32_16x16x32_bf16 v[104:107], v[160:163], v[192:195], v[104:107]
	v_mfma_f32_16x16x32_bf16 v[92:95], v[144:147], v[200:203], v[92:95]
	v_mfma_f32_16x16x32_bf16 v[88:91], v[160:163], v[200:203], v[88:91]
	v_mfma_f32_16x16x32_bf16 v[76:79], v[144:147], v[212:215], v[76:79]
	v_mfma_f32_16x16x32_bf16 v[72:75], v[160:163], v[212:215], v[72:75]
	v_mfma_f32_16x16x32_bf16 v[124:127], v[156:159], v[188:191], v[124:127]
	v_mfma_f32_16x16x32_bf16 v[120:123], v[164:167], v[188:191], v[120:123]
	v_mfma_f32_16x16x32_bf16 v[108:111], v[156:159], v[196:199], v[108:111]
	v_mfma_f32_16x16x32_bf16 v[104:107], v[164:167], v[196:199], v[104:107]
	v_mfma_f32_16x16x32_bf16 v[92:95], v[156:159], v[208:211], v[92:95]
	v_mfma_f32_16x16x32_bf16 v[88:91], v[164:167], v[208:211], v[88:91]
	v_mfma_f32_16x16x32_bf16 v[76:79], v[156:159], v[216:219], v[76:79]
	v_mfma_f32_16x16x32_bf16 v[72:75], v[164:167], v[216:219], v[72:75]
	v_mfma_f32_16x16x32_bf16 v[116:119], v[168:171], v[184:187], v[116:119]
	v_mfma_f32_16x16x32_bf16 v[112:115], v[176:179], v[184:187], v[112:115]
	v_mfma_f32_16x16x32_bf16 v[100:103], v[168:171], v[192:195], v[100:103]
	v_mfma_f32_16x16x32_bf16 v[96:99], v[176:179], v[192:195], v[96:99]
	v_mfma_f32_16x16x32_bf16 v[84:87], v[168:171], v[200:203], v[84:87]
	v_mfma_f32_16x16x32_bf16 v[80:83], v[176:179], v[200:203], v[80:83]
	v_mfma_f32_16x16x32_bf16 v[68:71], v[168:171], v[212:215], v[68:71]
	v_mfma_f32_16x16x32_bf16 v[64:67], v[176:179], v[212:215], v[64:67]
	v_mfma_f32_16x16x32_bf16 v[116:119], v[172:175], v[188:191], v[116:119]
	v_mfma_f32_16x16x32_bf16 v[112:115], v[180:183], v[188:191], v[112:115]
	v_mfma_f32_16x16x32_bf16 v[100:103], v[172:175], v[196:199], v[100:103]
	v_mfma_f32_16x16x32_bf16 v[96:99], v[180:183], v[196:199], v[96:99]
	v_mfma_f32_16x16x32_bf16 v[84:87], v[172:175], v[208:211], v[84:87]
	v_mfma_f32_16x16x32_bf16 v[80:83], v[180:183], v[208:211], v[80:83]
	v_mfma_f32_16x16x32_bf16 v[68:71], v[172:175], v[216:219], v[68:71]
	v_mfma_f32_16x16x32_bf16 v[64:67], v[180:183], v[216:219], v[64:67]
	s_barrier
	s_bitcmp1_b32 s97, 0
	s_cbranch_scc1 .Lstg_13_3_b
	s_add_i32 s28, s54, s38
	s_mov_b32 m0, s28
	s_nop 0
	global_load_lds_dwordx4 v205, s[26:27]
	s_add_i32 m0, s28, 0x2000
	s_add_u32 s26, s26, 0x40080
	s_addc_u32 s27, s27, 0
	s_add_i32 s28, s55, s38
	global_load_lds_dwordx4 v221, s[98:99]
	s_mov_b32 m0, s28
	s_nop 0
	global_load_lds_dwordx4 v130, s[26:27]
	s_add_i32 m0, s28, 0x2000
	s_nop 0
	global_load_lds_dwordx4 v134, s[26:27]
	s_cmp_lg_u32 s53, 12
	s_cbranch_scc1 .Lbal_last_13
	s_mov_b32 m0, s44
	s_nop 0
	global_load_lds_dwordx4 v204, s[100:101]
	s_mov_b32 m0, s45
	s_nop 0
	global_load_lds_dwordx4 v220, s[100:101]

.Lstg_13_3_b:
	s_add_i32 s28, s54, s38
	s_mov_b32 m0, s28
	ds_read_b128 v[184:187], v153 offset:49152
	ds_read_b128 v[188:191], v153 offset:50176
	ds_read_b128 v[192:195], v153 offset:51200
	ds_read_b128 v[196:199], v153 offset:52224
	ds_read_b128 v[200:203], v153 offset:53248
	ds_read_b128 v[208:211], v153 offset:54272
	ds_read_b128 v[212:215], v153 offset:55296
	ds_read_b128 v[216:219], v153 offset:56320
	global_load_lds_dwordx4 v205, s[26:27]
	s_add_i32 m0, s28, 0x2000
	s_add_u32 s26, s26, 0x40080
	s_addc_u32 s27, s27, 0
	s_add_i32 s28, s55, s38
	global_load_lds_dwordx4 v221, s[98:99]
	s_mov_b32 m0, s28
	s_nop 0
	global_load_lds_dwordx4 v130, s[26:27]
	s_add_i32 m0, s28, 0x2000
	s_nop 0
	global_load_lds_dwordx4 v134, s[26:27]
	s_cmp_lg_u32 s53, 12
	s_cbranch_scc1 .Lbal_last_13_b
	s_mov_b32 m0, s44
	s_nop 0
	global_load_lds_dwordx4 v204, s[100:101]
	s_mov_b32 m0, s45
	s_nop 0
	global_load_lds_dwordx4 v220, s[100:101]
.Lbal_last_13_b:
.Lstg_13_3_j:
	s_waitcnt vmcnt(6)
	s_waitcnt lgkmcnt(0)
	s_barrier
	s_waitcnt lgkmcnt(0)
	v_mfma_f32_16x16x32_bf16 v[60:63], v[144:147], v[184:187], v[60:63]
	v_mfma_f32_16x16x32_bf16 v[56:59], v[160:163], v[184:187], v[56:59]
	v_mfma_f32_16x16x32_bf16 v[44:47], v[144:147], v[192:195], v[44:47]
	v_mfma_f32_16x16x32_bf16 v[40:43], v[160:163], v[192:195], v[40:43]
	v_mfma_f32_16x16x32_bf16 v[28:31], v[144:147], v[200:203], v[28:31]
	v_mfma_f32_16x16x32_bf16 v[24:27], v[160:163], v[200:203], v[24:27]
	v_mfma_f32_16x16x32_bf16 v[12:15], v[144:147], v[212:215], v[12:15]
	v_mfma_f32_16x16x32_bf16 v[8:11], v[160:163], v[212:215], v[8:11]
	v_mfma_f32_16x16x32_bf16 v[60:63], v[156:159], v[188:191], v[60:63]
	v_mfma_f32_16x16x32_bf16 v[56:59], v[164:167], v[188:191], v[56:59]
	v_mfma_f32_16x16x32_bf16 v[44:47], v[156:159], v[196:199], v[44:47]
	v_mfma_f32_16x16x32_bf16 v[40:43], v[164:167], v[196:199], v[40:43]
	v_mfma_f32_16x16x32_bf16 v[28:31], v[156:159], v[208:211], v[28:31]
	v_mfma_f32_16x16x32_bf16 v[24:27], v[164:167], v[208:211], v[24:27]
	v_mfma_f32_16x16x32_bf16 v[12:15], v[156:159], v[216:219], v[12:15]
	v_mfma_f32_16x16x32_bf16 v[8:11], v[164:167], v[216:219], v[8:11]
	v_mfma_f32_16x16x32_bf16 v[52:55], v[168:171], v[184:187], v[52:55]
	v_mfma_f32_16x16x32_bf16 v[48:51], v[176:179], v[184:187], v[48:51]
	v_mfma_f32_16x16x32_bf16 v[36:39], v[168:171], v[192:195], v[36:39]
	v_mfma_f32_16x16x32_bf16 v[32:35], v[176:179], v[192:195], v[32:35]
	v_mfma_f32_16x16x32_bf16 v[20:23], v[168:171], v[200:203], v[20:23]
	v_mfma_f32_16x16x32_bf16 v[16:19], v[176:179], v[200:203], v[16:19]
	v_mfma_f32_16x16x32_bf16 v[4:7], v[168:171], v[212:215], v[4:7]
	v_mfma_f32_16x16x32_bf16 v[0:3], v[176:179], v[212:215], v[0:3]
	v_mfma_f32_16x16x32_bf16 v[52:55], v[172:175], v[188:191], v[52:55]
	v_mfma_f32_16x16x32_bf16 v[48:51], v[180:183], v[188:191], v[48:51]
	v_mfma_f32_16x16x32_bf16 v[36:39], v[172:175], v[196:199], v[36:39]
	v_mfma_f32_16x16x32_bf16 v[32:35], v[180:183], v[196:199], v[32:35]
	v_mfma_f32_16x16x32_bf16 v[20:23], v[172:175], v[208:211], v[20:23]
	v_mfma_f32_16x16x32_bf16 v[16:19], v[180:183], v[208:211], v[16:19]
	v_mfma_f32_16x16x32_bf16 v[4:7], v[172:175], v[216:219], v[4:7]
	v_mfma_f32_16x16x32_bf16 v[0:3], v[180:183], v[216:219], v[0:3]
	s_barrier
	s_add_i32 s53, s53, 2
	s_add_u32 s51, s51, 0x100
	s_addc_u32 s52, s52, 0
	s_add_u32 s24, s24, 0x100
	s_addc_u32 s25, s25, 0
	s_cmp_gt_u32 s53, 13
	s_cbranch_scc0 .LBB0_1365
	s_setprio 0
	s_and_b64 vcc, exec, s[14:15]
	s_cbranch_vccz .LBB0_1368
	s_barrier

.LBB0_1561:
	s_bitcmp1_b32 s97, 0
	s_cbranch_scc1 .Lstg_11_0_b
	s_cmp_eq_i32 s61, -2
	s_cbranch_scc1 .Lbal_first_11
	s_mov_b32 m0, s51
	s_nop 0
	global_load_lds_dwordx4 v204, s[100:101]
	s_mov_b32 m0, s52
	s_nop 0
	global_load_lds_dwordx4 v205, s[100:101]
.Lbal_first_11:
	s_add_u32 s38, s36, 0xfffc0080
	s_addc_u32 s39, s37, -1
	s_cmp_eq_u32 s61, 12
	s_cselect_b32 s41, s3, s39
	s_cselect_b32 s40, s29, s38
	s_cselect_b32 s39, s27, s60
	s_cselect_b32 s38, s58, s59
	s_add_i32 m0, s46, 0xc000
	s_nop 0
	global_load_lds_dwordx4 v134, s[36:37]
	s_add_i32 m0, s46, 0xe000
	s_nop 0
	global_load_lds_dwordx4 v132, s[36:37]
	ds_read_b128 v[140:143], v151
	ds_read_b128 v[144:147], v151 offset:1024
	ds_read_b128 v[156:159], v151 offset:2048
	ds_read_b128 v[160:163], v151 offset:3072
	ds_read_b128 v[164:167], v152
	ds_read_b128 v[168:171], v152 offset:1024
	ds_read_b128 v[172:175], v152 offset:2048
	ds_read_b128 v[176:179], v152 offset:3072
	ds_read_b128 v[180:183], v153
	ds_read_b128 v[184:187], v153 offset:1024
	ds_read_b128 v[188:191], v153 offset:2048
	ds_read_b128 v[192:195], v153 offset:3072
	ds_read_b128 v[196:199], v153 offset:4096
	ds_read_b128 v[200:203], v153 offset:5120
	ds_read_b128 v[208:211], v153 offset:6144
	ds_read_b128 v[212:215], v153 offset:7168
	s_branch .Lstg_11_0_j

.Lbal_first_11_b:
	ds_read_b128 v[140:143], v151
	ds_read_b128 v[144:147], v151 offset:1024
	ds_read_b128 v[156:159], v151 offset:2048
	ds_read_b128 v[160:163], v151 offset:3072
	ds_read_b128 v[164:167], v152
	ds_read_b128 v[168:171], v152 offset:1024
	ds_read_b128 v[172:175], v152 offset:2048
	ds_read_b128 v[176:179], v152 offset:3072
	s_add_u32 s38, s36, 0xfffc0080
	s_addc_u32 s39, s37, -1
	s_cmp_eq_u32 s61, 12
	s_cselect_b32 s41, s3, s39
	s_cselect_b32 s40, s29, s38
	s_cselect_b32 s39, s27, s60
	s_cselect_b32 s38, s58, s59
	s_add_i32 m0, s46, 0xc000
	ds_read_b128 v[180:183], v153
	ds_read_b128 v[184:187], v153 offset:1024
	ds_read_b128 v[188:191], v153 offset:2048
	ds_read_b128 v[192:195], v153 offset:3072
	ds_read_b128 v[196:199], v153 offset:4096
	ds_read_b128 v[200:203], v153 offset:5120
	ds_read_b128 v[208:211], v153 offset:6144
	ds_read_b128 v[212:215], v153 offset:7168
	global_load_lds_dwordx4 v134, s[36:37]
	s_add_i32 m0, s46, 0xe000
	s_nop 0
	global_load_lds_dwordx4 v132, s[36:37]
.Lstg_11_0_j:
	s_waitcnt vmcnt(8)
	s_waitcnt lgkmcnt(0)
	s_barrier
	s_waitcnt lgkmcnt(0)
	v_mfma_f32_16x16x32_bf16 v[124:127], v[140:143], v[180:183], v[124:127]
	v_mfma_f32_16x16x32_bf16 v[120:123], v[156:159], v[180:183], v[120:123]
	v_mfma_f32_16x16x32_bf16 v[108:111], v[140:143], v[188:191], v[108:111]
	v_mfma_f32_16x16x32_bf16 v[104:107], v[156:159], v[188:191], v[104:107]
	v_mfma_f32_16x16x32_bf16 v[92:95], v[140:143], v[196:199], v[92:95]
	v_mfma_f32_16x16x32_bf16 v[88:91], v[156:159], v[196:199], v[88:91]
	v_mfma_f32_16x16x32_bf16 v[76:79], v[140:143], v[208:211], v[76:79]
	v_mfma_f32_16x16x32_bf16 v[72:75], v[156:159], v[208:211], v[72:75]
	v_mfma_f32_16x16x32_bf16 v[124:127], v[144:147], v[184:187], v[124:127]
	v_mfma_f32_16x16x32_bf16 v[120:123], v[160:163], v[184:187], v[120:123]
	v_mfma_f32_16x16x32_bf16 v[108:111], v[144:147], v[192:195], v[108:111]
	v_mfma_f32_16x16x32_bf16 v[104:107], v[160:163], v[192:195], v[104:107]
	v_mfma_f32_16x16x32_bf16 v[92:95], v[144:147], v[200:203], v[92:95]
	v_mfma_f32_16x16x32_bf16 v[88:91], v[160:163], v[200:203], v[88:91]
	v_mfma_f32_16x16x32_bf16 v[76:79], v[144:147], v[212:215], v[76:79]
	v_mfma_f32_16x16x32_bf16 v[72:75], v[160:163], v[212:215], v[72:75]
	v_mfma_f32_16x16x32_bf16 v[116:119], v[164:167], v[180:183], v[116:119]
	v_mfma_f32_16x16x32_bf16 v[112:115], v[172:175], v[180:183], v[112:115]
	v_mfma_f32_16x16x32_bf16 v[100:103], v[164:167], v[188:191], v[100:103]
	v_mfma_f32_16x16x32_bf16 v[96:99], v[172:175], v[188:191], v[96:99]
	v_mfma_f32_16x16x32_bf16 v[84:87], v[164:167], v[196:199], v[84:87]
	v_mfma_f32_16x16x32_bf16 v[80:83], v[172:175], v[196:199], v[80:83]
	v_mfma_f32_16x16x32_bf16 v[68:71], v[164:167], v[208:211], v[68:71]
	v_mfma_f32_16x16x32_bf16 v[64:67], v[172:175], v[208:211], v[64:67]
	v_mfma_f32_16x16x32_bf16 v[116:119], v[168:171], v[184:187], v[116:119]
	v_mfma_f32_16x16x32_bf16 v[112:115], v[176:179], v[184:187], v[112:115]
	v_mfma_f32_16x16x32_bf16 v[100:103], v[168:171], v[192:195], v[100:103]
	v_mfma_f32_16x16x32_bf16 v[96:99], v[176:179], v[192:195], v[96:99]
	v_mfma_f32_16x16x32_bf16 v[84:87], v[168:171], v[200:203], v[84:87]
	v_mfma_f32_16x16x32_bf16 v[80:83], v[176:179], v[200:203], v[80:83]
	v_mfma_f32_16x16x32_bf16 v[68:71], v[168:171], v[212:215], v[68:71]
	v_mfma_f32_16x16x32_bf16 v[64:67], v[176:179], v[212:215], v[64:67]
	s_barrier
	s_bitcmp1_b32 s97, 0
	s_cbranch_scc1 .Lstg_11_1_b
	s_add_i32 s62, s54, s45
	s_mov_b32 m0, s62
	s_nop 0
	global_load_lds_dwordx4 v128, s[38:39]
	s_add_i32 m0, s62, 0x2000
	s_add_u32 s62, s38, 0x40000
	s_mov_b64 s[98:99], s[38:39]
	s_addc_u32 s63, s39, 0
	s_add_i32 s64, s55, s45
	global_load_lds_dwordx4 v130, s[38:39]
	s_mov_b32 m0, s64
	s_mov_b64 s[100:101], s[40:41]
	global_load_lds_dwordx4 v128, s[62:63]
	s_add_i32 m0, s64, 0x2000
	s_nop 0
	global_load_lds_dwordx4 v130, s[62:63]
	ds_read_b128 v[180:183], v153 offset:16384
	ds_read_b128 v[184:187], v153 offset:17408
	ds_read_b128 v[188:191], v153 offset:18432
	ds_read_b128 v[192:195], v153 offset:19456
	ds_read_b128 v[196:199], v153 offset:20480
	ds_read_b128 v[200:203], v153 offset:21504
	ds_read_b128 v[208:211], v153 offset:22528
	ds_read_b128 v[212:215], v153 offset:23552
	s_branch .Lstg_11_1_j
.Lstg_11_1_b:
	s_add_i32 s62, s54, s45
	s_mov_b32 m0, s62
	ds_read_b128 v[180:183], v153 offset:16384
	ds_read_b128 v[184:187], v153 offset:17408
	ds_read_b128 v[188:191], v153 offset:18432
	ds_read_b128 v[192:195], v153 offset:19456
	ds_read_b128 v[196:199], v153 offset:20480
	ds_read_b128 v[200:203], v153 offset:21504
	ds_read_b128 v[208:211], v153 offset:22528
	ds_read_b128 v[212:215], v153 offset:23552
	global_load_lds_dwordx4 v128, s[38:39]
	s_add_i32 m0, s62, 0x2000
	s_add_u32 s62, s38, 0x40000
	s_mov_b64 s[98:99], s[38:39]
	s_addc_u32 s63, s39, 0
	s_add_i32 s64, s55, s45
	global_load_lds_dwordx4 v130, s[38:39]
	s_mov_b32 m0, s64
	s_mov_b64 s[100:101], s[40:41]
	global_load_lds_dwordx4 v128, s[62:63]
	s_add_i32 m0, s64, 0x2000
	s_nop 0
	global_load_lds_dwordx4 v130, s[62:63]
.Lstg_11_1_j:
	s_waitcnt vmcnt(6)
	s_waitcnt lgkmcnt(0)
	s_barrier
	s_waitcnt lgkmcnt(0)
	v_mfma_f32_16x16x32_bf16 v[60:63], v[140:143], v[180:183], v[60:63]
	v_mfma_f32_16x16x32_bf16 v[56:59], v[156:159], v[180:183], v[56:59]
	v_mfma_f32_16x16x32_bf16 v[44:47], v[140:143], v[188:191], v[44:47]
	v_mfma_f32_16x16x32_bf16 v[40:43], v[156:159], v[188:191], v[40:43]
	v_mfma_f32_16x16x32_bf16 v[28:31], v[140:143], v[196:199], v[28:31]
	v_mfma_f32_16x16x32_bf16 v[24:27], v[156:159], v[196:199], v[24:27]
	v_mfma_f32_16x16x32_bf16 v[12:15], v[140:143], v[208:211], v[12:15]
	v_mfma_f32_16x16x32_bf16 v[8:11], v[156:159], v[208:211], v[8:11]
	v_mfma_f32_16x16x32_bf16 v[60:63], v[144:147], v[184:187], v[60:63]
	v_mfma_f32_16x16x32_bf16 v[56:59], v[160:163], v[184:187], v[56:59]
	v_mfma_f32_16x16x32_bf16 v[44:47], v[144:147], v[192:195], v[44:47]
	v_mfma_f32_16x16x32_bf16 v[40:43], v[160:163], v[192:195], v[40:43]
	v_mfma_f32_16x16x32_bf16 v[28:31], v[144:147], v[200:203], v[28:31]
	v_mfma_f32_16x16x32_bf16 v[24:27], v[160:163], v[200:203], v[24:27]
	v_mfma_f32_16x16x32_bf16 v[12:15], v[144:147], v[212:215], v[12:15]
	v_mfma_f32_16x16x32_bf16 v[8:11], v[160:163], v[212:215], v[8:11]
	v_mfma_f32_16x16x32_bf16 v[52:55], v[164:167], v[180:183], v[52:55]
	v_mfma_f32_16x16x32_bf16 v[48:51], v[172:175], v[180:183], v[48:51]
	v_mfma_f32_16x16x32_bf16 v[36:39], v[164:167], v[188:191], v[36:39]
	v_mfma_f32_16x16x32_bf16 v[32:35], v[172:175], v[188:191], v[32:35]
	v_mfma_f32_16x16x32_bf16 v[20:23], v[164:167], v[196:199], v[20:23]
	v_mfma_f32_16x16x32_bf16 v[16:19], v[172:175], v[196:199], v[16:19]
	v_mfma_f32_16x16x32_bf16 v[4:7], v[164:167], v[208:211], v[4:7]
	v_mfma_f32_16x16x32_bf16 v[0:3], v[172:175], v[208:211], v[0:3]
	v_mfma_f32_16x16x32_bf16 v[52:55], v[168:171], v[184:187], v[52:55]
	v_mfma_f32_16x16x32_bf16 v[48:51], v[176:179], v[184:187], v[48:51]
	v_mfma_f32_16x16x32_bf16 v[36:39], v[168:171], v[192:195], v[36:39]
	v_mfma_f32_16x16x32_bf16 v[32:35], v[176:179], v[192:195], v[32:35]
	v_mfma_f32_16x16x32_bf16 v[20:23], v[168:171], v[200:203], v[20:23]
	v_mfma_f32_16x16x32_bf16 v[16:19], v[176:179], v[200:203], v[16:19]
	v_mfma_f32_16x16x32_bf16 v[4:7], v[168:171], v[212:215], v[4:7]
	v_mfma_f32_16x16x32_bf16 v[0:3], v[176:179], v[212:215], v[0:3]
	s_barrier
	s_bitcmp1_b32 s97, 0
	s_cbranch_scc1 .Lstg_11_2_b
	s_mov_b32 m0, s46
	s_nop 0
	global_load_lds_dwordx4 v128, s[40:41]
	s_mov_b32 m0, s47
	s_nop 0
	global_load_lds_dwordx4 v130, s[40:41]
	s_add_i32 s62, 0, 0x18000
	s_add_i32 s63, 0, 0x1c000
	s_add_u32 s40, s40, 0x40000
	s_addc_u32 s41, s41, 0
	s_mov_b32 m0, s48
	s_nop 0
	global_load_lds_dwordx4 v128, s[40:41]
	s_mov_b32 m0, s49
	s_nop 0
	global_load_lds_dwordx4 v130, s[40:41]
	v_add_u32_e32 v155, s62, v149
	ds_read_b128 v[140:143], v155
	ds_read_b128 v[144:147], v155 offset:1024
	ds_read_b128 v[156:159], v155 offset:2048
	ds_read_b128 v[160:163], v155 offset:3072
	v_add_u32_e32 v155, s63, v149
	ds_read_b128 v[164:167], v155
	ds_read_b128 v[168:171], v155 offset:1024
	ds_read_b128 v[172:175], v155 offset:2048
	ds_read_b128 v[176:179], v155 offset:3072
	ds_read_b128 v[180:183], v153 offset:32768
	ds_read_b128 v[184:187], v153 offset:33792
	ds_read_b128 v[188:191], v153 offset:34816
	ds_read_b128 v[192:195], v153 offset:35840
	ds_read_b128 v[196:199], v153 offset:36864
	ds_read_b128 v[200:203], v153 offset:37888
	ds_read_b128 v[208:211], v153 offset:38912
	ds_read_b128 v[212:215], v153 offset:39936
	s_branch .Lstg_11_2_j
.Lstg_11_2_b:
	s_mov_b32 m0, s46
	s_nop 0
	global_load_lds_dwordx4 v128, s[40:41]
	s_mov_b32 m0, s47
	s_nop 0
	global_load_lds_dwordx4 v130, s[40:41]
	s_add_i32 s62, 0, 0x18000
	v_add_u32_e32 v155, s62, v149
	s_add_i32 s63, 0, 0x1c000
	ds_read_b128 v[140:143], v155
	ds_read_b128 v[144:147], v155 offset:1024
	ds_read_b128 v[156:159], v155 offset:2048
	ds_read_b128 v[160:163], v155 offset:3072
	v_add_u32_e32 v155, s63, v149
	ds_read_b128 v[164:167], v155
	ds_read_b128 v[168:171], v155 offset:1024
	ds_read_b128 v[172:175], v155 offset:2048
	ds_read_b128 v[176:179], v155 offset:3072
	s_add_u32 s40, s40, 0x40000
	s_addc_u32 s41, s41, 0
	s_mov_b32 m0, s48
	ds_read_b128 v[180:183], v153 offset:32768
	ds_read_b128 v[184:187], v153 offset:33792
	ds_read_b128 v[188:191], v153 offset:34816
	ds_read_b128 v[192:195], v153 offset:35840
	ds_read_b128 v[196:199], v153 offset:36864
	ds_read_b128 v[200:203], v153 offset:37888
	ds_read_b128 v[208:211], v153 offset:38912
	ds_read_b128 v[212:215], v153 offset:39936
	global_load_lds_dwordx4 v128, s[40:41]
	s_mov_b32 m0, s49
	s_nop 0
	global_load_lds_dwordx4 v130, s[40:41]
.Lstg_11_2_j:
	s_waitcnt vmcnt(8)
	s_waitcnt lgkmcnt(0)
	s_barrier
	s_waitcnt lgkmcnt(0)
	v_mfma_f32_16x16x32_bf16 v[124:127], v[140:143], v[180:183], v[124:127]
	v_mfma_f32_16x16x32_bf16 v[120:123], v[156:159], v[180:183], v[120:123]
	v_mfma_f32_16x16x32_bf16 v[108:111], v[140:143], v[188:191], v[108:111]
	v_mfma_f32_16x16x32_bf16 v[104:107], v[156:159], v[188:191], v[104:107]
	v_mfma_f32_16x16x32_bf16 v[92:95], v[140:143], v[196:199], v[92:95]
	v_mfma_f32_16x16x32_bf16 v[88:91], v[156:159], v[196:199], v[88:91]
	v_mfma_f32_16x16x32_bf16 v[76:79], v[140:143], v[208:211], v[76:79]
	v_mfma_f32_16x16x32_bf16 v[72:75], v[156:159], v[208:211], v[72:75]
	v_mfma_f32_16x16x32_bf16 v[124:127], v[144:147], v[184:187], v[124:127]
	v_mfma_f32_16x16x32_bf16 v[120:123], v[160:163], v[184:187], v[120:123]
	v_mfma_f32_16x16x32_bf16 v[108:111], v[144:147], v[192:195], v[108:111]
	v_mfma_f32_16x16x32_bf16 v[104:107], v[160:163], v[192:195], v[104:107]
	v_mfma_f32_16x16x32_bf16 v[92:95], v[144:147], v[200:203], v[92:95]
	v_mfma_f32_16x16x32_bf16 v[88:91], v[160:163], v[200:203], v[88:91]
	v_mfma_f32_16x16x32_bf16 v[76:79], v[144:147], v[212:215], v[76:79]
	v_mfma_f32_16x16x32_bf16 v[72:75], v[160:163], v[212:215], v[72:75]
	v_mfma_f32_16x16x32_bf16 v[116:119], v[164:167], v[180:183], v[116:119]
	v_mfma_f32_16x16x32_bf16 v[112:115], v[172:175], v[180:183], v[112:115]
	v_mfma_f32_16x16x32_bf16 v[100:103], v[164:167], v[188:191], v[100:103]
	v_mfma_f32_16x16x32_bf16 v[96:99], v[172:175], v[188:191], v[96:99]
	v_mfma_f32_16x16x32_bf16 v[84:87], v[164:167], v[196:199], v[84:87]
	v_mfma_f32_16x16x32_bf16 v[80:83], v[172:175], v[196:199], v[80:83]
	v_mfma_f32_16x16x32_bf16 v[68:71], v[164:167], v[208:211], v[68:71]
	v_mfma_f32_16x16x32_bf16 v[64:67], v[172:175], v[208:211], v[64:67]
	v_mfma_f32_16x16x32_bf16 v[116:119], v[168:171], v[184:187], v[116:119]
	v_mfma_f32_16x16x32_bf16 v[112:115], v[176:179], v[184:187], v[112:115]
	v_mfma_f32_16x16x32_bf16 v[100:103], v[168:171], v[192:195], v[100:103]
	v_mfma_f32_16x16x32_bf16 v[96:99], v[176:179], v[192:195], v[96:99]
	v_mfma_f32_16x16x32_bf16 v[84:87], v[168:171], v[200:203], v[84:87]
	v_mfma_f32_16x16x32_bf16 v[80:83], v[176:179], v[200:203], v[80:83]
	v_mfma_f32_16x16x32_bf16 v[68:71], v[168:171], v[212:215], v[68:71]
	v_mfma_f32_16x16x32_bf16 v[64:67], v[176:179], v[212:215], v[64:67]
	s_barrier
	s_bitcmp1_b32 s97, 0
	s_cbranch_scc1 .Lstg_11_3_b
	s_add_i32 s40, s62, s45
	s_mov_b32 m0, s40
	s_nop 0
	global_load_lds_dwordx4 v204, s[38:39]
	s_add_i32 m0, s40, 0x2000
	s_add_u32 s38, s38, 0x40080
	s_addc_u32 s39, s39, 0
	s_add_i32 s40, s63, s45
	global_load_lds_dwordx4 v205, s[98:99]
	s_mov_b32 m0, s40
	s_nop 0
	global_load_lds_dwordx4 v128, s[38:39]
	s_add_i32 m0, s40, 0x2000
	s_nop 0
	global_load_lds_dwordx4 v130, s[38:39]
	s_cmp_lg_u32 s61, 12
	s_cbranch_scc1 .Lbal_last_11
	s_mov_b32 m0, s51
	s_nop 0
	global_load_lds_dwordx4 v204, s[100:101]
	s_mov_b32 m0, s52
	s_nop 0
	global_load_lds_dwordx4 v205, s[100:101]
.Lbal_last_11:
	ds_read_b128 v[180:183], v153 offset:49152
	ds_read_b128 v[184:187], v153 offset:50176
	ds_read_b128 v[188:191], v153 offset:51200
	ds_read_b128 v[192:195], v153 offset:52224
	ds_read_b128 v[196:199], v153 offset:53248
	ds_read_b128 v[200:203], v153 offset:54272
	ds_read_b128 v[208:211], v153 offset:55296
	ds_read_b128 v[212:215], v153 offset:56320
	s_branch .Lstg_11_3_j
.Lstg_11_3_b:
	s_add_i32 s40, s62, s45
	s_mov_b32 m0, s40
	ds_read_b128 v[180:183], v153 offset:49152
	ds_read_b128 v[184:187], v153 offset:50176
	ds_read_b128 v[188:191], v153 offset:51200
	ds_read_b128 v[192:195], v153 offset:52224
	ds_read_b128 v[196:199], v153 offset:53248
	ds_read_b128 v[200:203], v153 offset:54272
	ds_read_b128 v[208:211], v153 offset:55296
	ds_read_b128 v[212:215], v153 offset:56320
	global_load_lds_dwordx4 v204, s[38:39]
	s_add_i32 m0, s40, 0x2000
	s_add_u32 s38, s38, 0x40080
	s_addc_u32 s39, s39, 0
	s_add_i32 s40, s63, s45
	global_load_lds_dwordx4 v205, s[98:99]
	s_mov_b32 m0, s40
	s_nop 0
	global_load_lds_dwordx4 v128, s[38:39]
	s_add_i32 m0, s40, 0x2000
	s_nop 0
	global_load_lds_dwordx4 v130, s[38:39]
	s_cmp_lg_u32 s61, 12
	s_cbranch_scc1 .Lbal_last_11_b
	s_mov_b32 m0, s51
	s_nop 0
	global_load_lds_dwordx4 v204, s[100:101]
	s_mov_b32 m0, s52
	s_nop 0
	global_load_lds_dwordx4 v205, s[100:101]
.Lbal_last_11_b:
.Lstg_11_3_j:
	s_waitcnt vmcnt(6)
	s_waitcnt lgkmcnt(0)
	s_barrier
	s_waitcnt lgkmcnt(0)
	v_mfma_f32_16x16x32_bf16 v[60:63], v[140:143], v[180:183], v[60:63]
	v_mfma_f32_16x16x32_bf16 v[56:59], v[156:159], v[180:183], v[56:59]
	v_mfma_f32_16x16x32_bf16 v[44:47], v[140:143], v[188:191], v[44:47]
	v_mfma_f32_16x16x32_bf16 v[40:43], v[156:159], v[188:191], v[40:43]
	v_mfma_f32_16x16x32_bf16 v[28:31], v[140:143], v[196:199], v[28:31]
	v_mfma_f32_16x16x32_bf16 v[24:27], v[156:159], v[196:199], v[24:27]
	v_mfma_f32_16x16x32_bf16 v[12:15], v[140:143], v[208:211], v[12:15]
	v_mfma_f32_16x16x32_bf16 v[8:11], v[156:159], v[208:211], v[8:11]
	v_mfma_f32_16x16x32_bf16 v[60:63], v[144:147], v[184:187], v[60:63]
	v_mfma_f32_16x16x32_bf16 v[56:59], v[160:163], v[184:187], v[56:59]
	v_mfma_f32_16x16x32_bf16 v[44:47], v[144:147], v[192:195], v[44:47]
	v_mfma_f32_16x16x32_bf16 v[40:43], v[160:163], v[192:195], v[40:43]
	v_mfma_f32_16x16x32_bf16 v[28:31], v[144:147], v[200:203], v[28:31]
	v_mfma_f32_16x16x32_bf16 v[24:27], v[160:163], v[200:203], v[24:27]
	v_mfma_f32_16x16x32_bf16 v[12:15], v[144:147], v[212:215], v[12:15]
	v_mfma_f32_16x16x32_bf16 v[8:11], v[160:163], v[212:215], v[8:11]
	v_mfma_f32_16x16x32_bf16 v[52:55], v[164:167], v[180:183], v[52:55]
	v_mfma_f32_16x16x32_bf16 v[48:51], v[172:175], v[180:183], v[48:51]
	v_mfma_f32_16x16x32_bf16 v[36:39], v[164:167], v[188:191], v[36:39]
	v_mfma_f32_16x16x32_bf16 v[32:35], v[172:175], v[188:191], v[32:35]
	v_mfma_f32_16x16x32_bf16 v[20:23], v[164:167], v[196:199], v[20:23]
	v_mfma_f32_16x16x32_bf16 v[16:19], v[172:175], v[196:199], v[16:19]
	v_mfma_f32_16x16x32_bf16 v[4:7], v[164:167], v[208:211], v[4:7]
	v_mfma_f32_16x16x32_bf16 v[0:3], v[172:175], v[208:211], v[0:3]
	v_mfma_f32_16x16x32_bf16 v[52:55], v[168:171], v[184:187], v[52:55]
	v_mfma_f32_16x16x32_bf16 v[48:51], v[176:179], v[184:187], v[48:51]
	v_mfma_f32_16x16x32_bf16 v[36:39], v[168:171], v[192:195], v[36:39]
	v_mfma_f32_16x16x32_bf16 v[32:35], v[176:179], v[192:195], v[32:35]
	v_mfma_f32_16x16x32_bf16 v[20:23], v[168:171], v[200:203], v[20:23]
	v_mfma_f32_16x16x32_bf16 v[16:19], v[176:179], v[200:203], v[16:19]
	v_mfma_f32_16x16x32_bf16 v[4:7], v[168:171], v[212:215], v[4:7]
	v_mfma_f32_16x16x32_bf16 v[0:3], v[176:179], v[212:215], v[0:3]
	s_barrier
	s_add_i32 s61, s61, 2
	s_add_u32 s59, s59, 0x100
	s_addc_u32 s60, s60, 0
	s_add_u32 s36, s36, 0x100
	s_addc_u32 s37, s37, 0
	s_cmp_gt_u32 s61, 13
	s_cbranch_scc0 .LBB0_1561
	s_setprio 0
	s_and_b64 vcc, exec, s[24:25]
	s_cbranch_vccz .LBB0_1564
	s_barrier

.LBB0_1646:
	s_bitcmp1_b32 s97, 0
	s_cbranch_scc1 .Lstg_10_0_b
	s_cmp_eq_i32 s54, -2
	s_cbranch_scc1 .Lbal_first_10
	s_mov_b32 m0, s45
	s_nop 0
	global_load_lds_dwordx4 v221, s[100:101]
	s_mov_b32 m0, s46
	s_nop 0
	global_load_lds_dwordx4 v205, s[100:101]
.Lbal_first_10:
	s_add_u32 s26, s24, 0xfffc0080
	s_addc_u32 s27, s25, -1
	s_cmp_eq_u32 s54, 12
	s_cselect_b32 s29, s19, s27
	s_cselect_b32 s28, s50, s26
	s_cselect_b32 s27, s17, s53
	s_cselect_b32 s26, s51, s52
	s_add_i32 m0, s38, 0xc000
	s_nop 0
	global_load_lds_dwordx4 v138, s[24:25]
	s_add_i32 m0, s38, 0xe000
	s_nop 0
	global_load_lds_dwordx4 v136, s[24:25]
	ds_read_b128 v[144:147], v151
	ds_read_b128 v[156:159], v151 offset:1024
	ds_read_b128 v[160:163], v151 offset:2048
	ds_read_b128 v[164:167], v151 offset:3072
	ds_read_b128 v[168:171], v152
	ds_read_b128 v[172:175], v152 offset:1024
	ds_read_b128 v[176:179], v152 offset:2048
	ds_read_b128 v[180:183], v152 offset:3072
	ds_read_b128 v[184:187], v153
	ds_read_b128 v[188:191], v153 offset:1024
	ds_read_b128 v[192:195], v153 offset:2048
	ds_read_b128 v[196:199], v153 offset:3072
	ds_read_b128 v[200:203], v153 offset:4096
	ds_read_b128 v[208:211], v153 offset:5120
	ds_read_b128 v[212:215], v153 offset:6144
	ds_read_b128 v[216:219], v153 offset:7168
	s_branch .Lstg_10_0_j

.Lbal_first_10_b:
	ds_read_b128 v[144:147], v151
	ds_read_b128 v[156:159], v151 offset:1024
	ds_read_b128 v[160:163], v151 offset:2048
	ds_read_b128 v[164:167], v151 offset:3072
	ds_read_b128 v[168:171], v152
	ds_read_b128 v[172:175], v152 offset:1024
	ds_read_b128 v[176:179], v152 offset:2048
	ds_read_b128 v[180:183], v152 offset:3072
	s_add_u32 s26, s24, 0xfffc0080
	s_addc_u32 s27, s25, -1
	s_cmp_eq_u32 s54, 12
	s_cselect_b32 s29, s19, s27
	s_cselect_b32 s28, s50, s26
	s_cselect_b32 s27, s17, s53
	s_cselect_b32 s26, s51, s52
	s_add_i32 m0, s38, 0xc000
	ds_read_b128 v[184:187], v153
	ds_read_b128 v[188:191], v153 offset:1024
	ds_read_b128 v[192:195], v153 offset:2048
	ds_read_b128 v[196:199], v153 offset:3072
	ds_read_b128 v[200:203], v153 offset:4096
	ds_read_b128 v[208:211], v153 offset:5120
	ds_read_b128 v[212:215], v153 offset:6144
	ds_read_b128 v[216:219], v153 offset:7168
	global_load_lds_dwordx4 v138, s[24:25]
	s_add_i32 m0, s38, 0xe000
	s_nop 0
	global_load_lds_dwordx4 v136, s[24:25]
.Lstg_10_0_j:
	s_waitcnt vmcnt(8)
	s_waitcnt lgkmcnt(0)
	s_barrier
	s_waitcnt lgkmcnt(0)
	v_mfma_f32_16x16x32_bf16 v[124:127], v[144:147], v[184:187], v[124:127]
	v_mfma_f32_16x16x32_bf16 v[120:123], v[160:163], v[184:187], v[120:123]
	v_mfma_f32_16x16x32_bf16 v[108:111], v[144:147], v[192:195], v[108:111]
	v_mfma_f32_16x16x32_bf16 v[104:107], v[160:163], v[192:195], v[104:107]
	v_mfma_f32_16x16x32_bf16 v[92:95], v[144:147], v[200:203], v[92:95]
	v_mfma_f32_16x16x32_bf16 v[88:91], v[160:163], v[200:203], v[88:91]
	v_mfma_f32_16x16x32_bf16 v[76:79], v[144:147], v[212:215], v[76:79]
	v_mfma_f32_16x16x32_bf16 v[72:75], v[160:163], v[212:215], v[72:75]
	v_mfma_f32_16x16x32_bf16 v[124:127], v[156:159], v[188:191], v[124:127]
	v_mfma_f32_16x16x32_bf16 v[120:123], v[164:167], v[188:191], v[120:123]
	v_mfma_f32_16x16x32_bf16 v[108:111], v[156:159], v[196:199], v[108:111]
	v_mfma_f32_16x16x32_bf16 v[104:107], v[164:167], v[196:199], v[104:107]
	v_mfma_f32_16x16x32_bf16 v[92:95], v[156:159], v[208:211], v[92:95]
	v_mfma_f32_16x16x32_bf16 v[88:91], v[164:167], v[208:211], v[88:91]
	v_mfma_f32_16x16x32_bf16 v[76:79], v[156:159], v[216:219], v[76:79]
	v_mfma_f32_16x16x32_bf16 v[72:75], v[164:167], v[216:219], v[72:75]
	v_mfma_f32_16x16x32_bf16 v[116:119], v[168:171], v[184:187], v[116:119]
	v_mfma_f32_16x16x32_bf16 v[112:115], v[176:179], v[184:187], v[112:115]
	v_mfma_f32_16x16x32_bf16 v[100:103], v[168:171], v[192:195], v[100:103]
	v_mfma_f32_16x16x32_bf16 v[96:99], v[176:179], v[192:195], v[96:99]
	v_mfma_f32_16x16x32_bf16 v[84:87], v[168:171], v[200:203], v[84:87]
	v_mfma_f32_16x16x32_bf16 v[80:83], v[176:179], v[200:203], v[80:83]
	v_mfma_f32_16x16x32_bf16 v[68:71], v[168:171], v[212:215], v[68:71]
	v_mfma_f32_16x16x32_bf16 v[64:67], v[176:179], v[212:215], v[64:67]
	v_mfma_f32_16x16x32_bf16 v[116:119], v[172:175], v[188:191], v[116:119]
	v_mfma_f32_16x16x32_bf16 v[112:115], v[180:183], v[188:191], v[112:115]
	v_mfma_f32_16x16x32_bf16 v[100:103], v[172:175], v[196:199], v[100:103]
	v_mfma_f32_16x16x32_bf16 v[96:99], v[180:183], v[196:199], v[96:99]
	v_mfma_f32_16x16x32_bf16 v[84:87], v[172:175], v[208:211], v[84:87]
	v_mfma_f32_16x16x32_bf16 v[80:83], v[180:183], v[208:211], v[80:83]
	v_mfma_f32_16x16x32_bf16 v[68:71], v[172:175], v[216:219], v[68:71]
	v_mfma_f32_16x16x32_bf16 v[64:67], v[180:183], v[216:219], v[64:67]
	s_barrier
	s_bitcmp1_b32 s97, 0
	s_cbranch_scc1 .Lstg_10_1_b
	s_add_i32 s55, s47, s35
	s_mov_b32 m0, s55
	s_nop 0
	global_load_lds_dwordx4 v132, s[26:27]
	s_add_i32 m0, s55, 0x2000
	s_add_u32 s56, s26, 0x40000
	s_mov_b64 s[98:99], s[26:27]
	s_addc_u32 s57, s27, 0
	s_add_i32 s55, s48, s35
	global_load_lds_dwordx4 v128, s[26:27]
	s_mov_b32 m0, s55
	s_mov_b64 s[100:101], s[28:29]
	global_load_lds_dwordx4 v132, s[56:57]
	s_add_i32 m0, s55, 0x2000
	s_nop 0
	global_load_lds_dwordx4 v128, s[56:57]
	ds_read_b128 v[184:187], v153 offset:16384
	ds_read_b128 v[188:191], v153 offset:17408
	ds_read_b128 v[192:195], v153 offset:18432
	ds_read_b128 v[196:199], v153 offset:19456
	ds_read_b128 v[200:203], v153 offset:20480
	ds_read_b128 v[208:211], v153 offset:21504
	ds_read_b128 v[212:215], v153 offset:22528
	ds_read_b128 v[216:219], v153 offset:23552
	s_branch .Lstg_10_1_j
.Lstg_10_1_b:
	s_add_i32 s55, s47, s35
	s_mov_b32 m0, s55
	ds_read_b128 v[184:187], v153 offset:16384
	ds_read_b128 v[188:191], v153 offset:17408
	ds_read_b128 v[192:195], v153 offset:18432
	ds_read_b128 v[196:199], v153 offset:19456
	ds_read_b128 v[200:203], v153 offset:20480
	ds_read_b128 v[208:211], v153 offset:21504
	ds_read_b128 v[212:215], v153 offset:22528
	ds_read_b128 v[216:219], v153 offset:23552
	global_load_lds_dwordx4 v132, s[26:27]
	s_add_i32 m0, s55, 0x2000
	s_add_u32 s56, s26, 0x40000
	s_mov_b64 s[98:99], s[26:27]
	s_addc_u32 s57, s27, 0
	s_add_i32 s55, s48, s35
	global_load_lds_dwordx4 v128, s[26:27]
	s_mov_b32 m0, s55
	s_mov_b64 s[100:101], s[28:29]
	global_load_lds_dwordx4 v132, s[56:57]
	s_add_i32 m0, s55, 0x2000
	s_nop 0
	global_load_lds_dwordx4 v128, s[56:57]
.Lstg_10_1_j:
	s_waitcnt vmcnt(6)
	s_waitcnt lgkmcnt(0)
	s_barrier
	s_waitcnt lgkmcnt(0)
	v_mfma_f32_16x16x32_bf16 v[60:63], v[144:147], v[184:187], v[60:63]
	v_mfma_f32_16x16x32_bf16 v[56:59], v[160:163], v[184:187], v[56:59]
	v_mfma_f32_16x16x32_bf16 v[44:47], v[144:147], v[192:195], v[44:47]
	v_mfma_f32_16x16x32_bf16 v[40:43], v[160:163], v[192:195], v[40:43]
	v_mfma_f32_16x16x32_bf16 v[28:31], v[144:147], v[200:203], v[28:31]
	v_mfma_f32_16x16x32_bf16 v[24:27], v[160:163], v[200:203], v[24:27]
	v_mfma_f32_16x16x32_bf16 v[12:15], v[144:147], v[212:215], v[12:15]
	v_mfma_f32_16x16x32_bf16 v[8:11], v[160:163], v[212:215], v[8:11]
	v_mfma_f32_16x16x32_bf16 v[60:63], v[156:159], v[188:191], v[60:63]
	v_mfma_f32_16x16x32_bf16 v[56:59], v[164:167], v[188:191], v[56:59]
	v_mfma_f32_16x16x32_bf16 v[44:47], v[156:159], v[196:199], v[44:47]
	v_mfma_f32_16x16x32_bf16 v[40:43], v[164:167], v[196:199], v[40:43]
	v_mfma_f32_16x16x32_bf16 v[28:31], v[156:159], v[208:211], v[28:31]
	v_mfma_f32_16x16x32_bf16 v[24:27], v[164:167], v[208:211], v[24:27]
	v_mfma_f32_16x16x32_bf16 v[12:15], v[156:159], v[216:219], v[12:15]
	v_mfma_f32_16x16x32_bf16 v[8:11], v[164:167], v[216:219], v[8:11]
	v_mfma_f32_16x16x32_bf16 v[52:55], v[168:171], v[184:187], v[52:55]
	v_mfma_f32_16x16x32_bf16 v[48:51], v[176:179], v[184:187], v[48:51]
	v_mfma_f32_16x16x32_bf16 v[36:39], v[168:171], v[192:195], v[36:39]
	v_mfma_f32_16x16x32_bf16 v[32:35], v[176:179], v[192:195], v[32:35]
	v_mfma_f32_16x16x32_bf16 v[20:23], v[168:171], v[200:203], v[20:23]
	v_mfma_f32_16x16x32_bf16 v[16:19], v[176:179], v[200:203], v[16:19]
	v_mfma_f32_16x16x32_bf16 v[4:7], v[168:171], v[212:215], v[4:7]
	v_mfma_f32_16x16x32_bf16 v[0:3], v[176:179], v[212:215], v[0:3]
	v_mfma_f32_16x16x32_bf16 v[52:55], v[172:175], v[188:191], v[52:55]
	v_mfma_f32_16x16x32_bf16 v[48:51], v[180:183], v[188:191], v[48:51]
	v_mfma_f32_16x16x32_bf16 v[36:39], v[172:175], v[196:199], v[36:39]
	v_mfma_f32_16x16x32_bf16 v[32:35], v[180:183], v[196:199], v[32:35]
	v_mfma_f32_16x16x32_bf16 v[20:23], v[172:175], v[208:211], v[20:23]
	v_mfma_f32_16x16x32_bf16 v[16:19], v[180:183], v[208:211], v[16:19]
	v_mfma_f32_16x16x32_bf16 v[4:7], v[172:175], v[216:219], v[4:7]
	v_mfma_f32_16x16x32_bf16 v[0:3], v[180:183], v[216:219], v[0:3]
	s_barrier
	s_bitcmp1_b32 s97, 0
	s_cbranch_scc1 .Lstg_10_2_b
	s_mov_b32 m0, s38
	s_nop 0
	global_load_lds_dwordx4 v134, s[28:29]
	s_mov_b32 m0, s39
	s_nop 0
	global_load_lds_dwordx4 v130, s[28:29]
	s_add_i32 s55, 0, 0x18000
	s_add_i32 s56, 0, 0x1c000
	s_add_u32 s28, s28, 0x40000
	s_addc_u32 s29, s29, 0
	s_mov_b32 m0, s40
	s_nop 0
	global_load_lds_dwordx4 v134, s[28:29]
	s_mov_b32 m0, s41
	s_nop 0
	global_load_lds_dwordx4 v130, s[28:29]
	v_add_u32_e32 v164, s55, v149
	v_add_u32_e32 v180, s56, v149
	ds_read_b128 v[144:147], v164
	ds_read_b128 v[156:159], v164 offset:1024
	ds_read_b128 v[160:163], v164 offset:2048
	ds_read_b128 v[164:167], v164 offset:3072
	ds_read_b128 v[168:171], v180
	ds_read_b128 v[172:175], v180 offset:1024
	ds_read_b128 v[176:179], v180 offset:2048
	ds_read_b128 v[180:183], v180 offset:3072
	ds_read_b128 v[184:187], v153 offset:32768
	ds_read_b128 v[188:191], v153 offset:33792
	ds_read_b128 v[192:195], v153 offset:34816
	ds_read_b128 v[196:199], v153 offset:35840
	ds_read_b128 v[200:203], v153 offset:36864
	ds_read_b128 v[208:211], v153 offset:37888
	ds_read_b128 v[212:215], v153 offset:38912
	ds_read_b128 v[216:219], v153 offset:39936
	s_branch .Lstg_10_2_j
.Lstg_10_2_b:
	s_mov_b32 m0, s38
	s_nop 0
	global_load_lds_dwordx4 v134, s[28:29]
	s_mov_b32 m0, s39
	s_nop 0
	global_load_lds_dwordx4 v130, s[28:29]
	s_add_i32 s55, 0, 0x18000
	s_add_i32 s56, 0, 0x1c000
	v_add_u32_e32 v164, s55, v149
	v_add_u32_e32 v180, s56, v149
	ds_read_b128 v[144:147], v164
	ds_read_b128 v[156:159], v164 offset:1024
	ds_read_b128 v[160:163], v164 offset:2048
	ds_read_b128 v[164:167], v164 offset:3072
	ds_read_b128 v[168:171], v180
	ds_read_b128 v[172:175], v180 offset:1024
	ds_read_b128 v[176:179], v180 offset:2048
	ds_read_b128 v[180:183], v180 offset:3072
	s_add_u32 s28, s28, 0x40000
	s_addc_u32 s29, s29, 0
	s_mov_b32 m0, s40
	ds_read_b128 v[184:187], v153 offset:32768
	ds_read_b128 v[188:191], v153 offset:33792
	ds_read_b128 v[192:195], v153 offset:34816
	ds_read_b128 v[196:199], v153 offset:35840
	ds_read_b128 v[200:203], v153 offset:36864
	ds_read_b128 v[208:211], v153 offset:37888
	ds_read_b128 v[212:215], v153 offset:38912
	ds_read_b128 v[216:219], v153 offset:39936
	global_load_lds_dwordx4 v134, s[28:29]
	s_mov_b32 m0, s41
	s_nop 0
	global_load_lds_dwordx4 v130, s[28:29]
.Lstg_10_2_j:
	s_waitcnt vmcnt(8)
	s_waitcnt lgkmcnt(0)
	s_barrier
	s_waitcnt lgkmcnt(0)
	v_mfma_f32_16x16x32_bf16 v[124:127], v[144:147], v[184:187], v[124:127]
	v_mfma_f32_16x16x32_bf16 v[120:123], v[160:163], v[184:187], v[120:123]
	v_mfma_f32_16x16x32_bf16 v[108:111], v[144:147], v[192:195], v[108:111]
	v_mfma_f32_16x16x32_bf16 v[104:107], v[160:163], v[192:195], v[104:107]
	v_mfma_f32_16x16x32_bf16 v[92:95], v[144:147], v[200:203], v[92:95]
	v_mfma_f32_16x16x32_bf16 v[88:91], v[160:163], v[200:203], v[88:91]
	v_mfma_f32_16x16x32_bf16 v[76:79], v[144:147], v[212:215], v[76:79]
	v_mfma_f32_16x16x32_bf16 v[72:75], v[160:163], v[212:215], v[72:75]
	v_mfma_f32_16x16x32_bf16 v[124:127], v[156:159], v[188:191], v[124:127]
	v_mfma_f32_16x16x32_bf16 v[120:123], v[164:167], v[188:191], v[120:123]
	v_mfma_f32_16x16x32_bf16 v[108:111], v[156:159], v[196:199], v[108:111]
	v_mfma_f32_16x16x32_bf16 v[104:107], v[164:167], v[196:199], v[104:107]
	v_mfma_f32_16x16x32_bf16 v[92:95], v[156:159], v[208:211], v[92:95]
	v_mfma_f32_16x16x32_bf16 v[88:91], v[164:167], v[208:211], v[88:91]
	v_mfma_f32_16x16x32_bf16 v[76:79], v[156:159], v[216:219], v[76:79]
	v_mfma_f32_16x16x32_bf16 v[72:75], v[164:167], v[216:219], v[72:75]
	v_mfma_f32_16x16x32_bf16 v[116:119], v[168:171], v[184:187], v[116:119]
	v_mfma_f32_16x16x32_bf16 v[112:115], v[176:179], v[184:187], v[112:115]
	v_mfma_f32_16x16x32_bf16 v[100:103], v[168:171], v[192:195], v[100:103]
	v_mfma_f32_16x16x32_bf16 v[96:99], v[176:179], v[192:195], v[96:99]
	v_mfma_f32_16x16x32_bf16 v[84:87], v[168:171], v[200:203], v[84:87]
	v_mfma_f32_16x16x32_bf16 v[80:83], v[176:179], v[200:203], v[80:83]
	v_mfma_f32_16x16x32_bf16 v[68:71], v[168:171], v[212:215], v[68:71]
	v_mfma_f32_16x16x32_bf16 v[64:67], v[176:179], v[212:215], v[64:67]
	v_mfma_f32_16x16x32_bf16 v[116:119], v[172:175], v[188:191], v[116:119]
	v_mfma_f32_16x16x32_bf16 v[112:115], v[180:183], v[188:191], v[112:115]
	v_mfma_f32_16x16x32_bf16 v[100:103], v[172:175], v[196:199], v[100:103]
	v_mfma_f32_16x16x32_bf16 v[96:99], v[180:183], v[196:199], v[96:99]
	v_mfma_f32_16x16x32_bf16 v[84:87], v[172:175], v[208:211], v[84:87]
	v_mfma_f32_16x16x32_bf16 v[80:83], v[180:183], v[208:211], v[80:83]
	v_mfma_f32_16x16x32_bf16 v[68:71], v[172:175], v[216:219], v[68:71]
	v_mfma_f32_16x16x32_bf16 v[64:67], v[180:183], v[216:219], v[64:67]
	s_barrier
	s_bitcmp1_b32 s97, 0
	s_cbranch_scc1 .Lstg_10_3_b
	s_add_i32 s28, s55, s35
	s_mov_b32 m0, s28
	s_nop 0
	global_load_lds_dwordx4 v220, s[26:27]
	s_add_i32 m0, s28, 0x2000
	s_add_u32 s26, s26, 0x40080
	s_addc_u32 s27, s27, 0
	s_add_i32 s28, s56, s35
	global_load_lds_dwordx4 v204, s[98:99]
	s_mov_b32 m0, s28
	s_nop 0
	global_load_lds_dwordx4 v132, s[26:27]
	s_add_i32 m0, s28, 0x2000
	s_nop 0
	global_load_lds_dwordx4 v128, s[26:27]
	s_cmp_lg_u32 s54, 12
	s_cbranch_scc1 .Lbal_last_10
	s_mov_b32 m0, s45
	s_nop 0
	global_load_lds_dwordx4 v221, s[100:101]
	s_mov_b32 m0, s46
	s_nop 0
	global_load_lds_dwordx4 v205, s[100:101]

.Lstg_10_3_b:
	s_add_i32 s28, s55, s35
	s_mov_b32 m0, s28
	ds_read_b128 v[184:187], v153 offset:49152
	ds_read_b128 v[188:191], v153 offset:50176
	ds_read_b128 v[192:195], v153 offset:51200
	ds_read_b128 v[196:199], v153 offset:52224
	ds_read_b128 v[200:203], v153 offset:53248
	ds_read_b128 v[208:211], v153 offset:54272
	ds_read_b128 v[212:215], v153 offset:55296
	ds_read_b128 v[216:219], v153 offset:56320
	global_load_lds_dwordx4 v220, s[26:27]
	s_add_i32 m0, s28, 0x2000
	s_add_u32 s26, s26, 0x40080
	s_addc_u32 s27, s27, 0
	s_add_i32 s28, s56, s35
	global_load_lds_dwordx4 v204, s[98:99]
	s_mov_b32 m0, s28
	s_nop 0
	global_load_lds_dwordx4 v132, s[26:27]
	s_add_i32 m0, s28, 0x2000
	s_nop 0
	global_load_lds_dwordx4 v128, s[26:27]
	s_cmp_lg_u32 s54, 12
	s_cbranch_scc1 .Lbal_last_10_b
	s_mov_b32 m0, s45
	s_nop 0
	global_load_lds_dwordx4 v221, s[100:101]
	s_mov_b32 m0, s46
	s_nop 0
	global_load_lds_dwordx4 v205, s[100:101]
.Lbal_last_10_b:
.Lstg_10_3_j:
	s_waitcnt vmcnt(6)
	s_waitcnt lgkmcnt(0)
	s_barrier
	s_waitcnt lgkmcnt(0)
	v_mfma_f32_16x16x32_bf16 v[60:63], v[144:147], v[184:187], v[60:63]
	v_mfma_f32_16x16x32_bf16 v[56:59], v[160:163], v[184:187], v[56:59]
	v_mfma_f32_16x16x32_bf16 v[44:47], v[144:147], v[192:195], v[44:47]
	v_mfma_f32_16x16x32_bf16 v[40:43], v[160:163], v[192:195], v[40:43]
	v_mfma_f32_16x16x32_bf16 v[28:31], v[144:147], v[200:203], v[28:31]
	v_mfma_f32_16x16x32_bf16 v[24:27], v[160:163], v[200:203], v[24:27]
	v_mfma_f32_16x16x32_bf16 v[12:15], v[144:147], v[212:215], v[12:15]
	v_mfma_f32_16x16x32_bf16 v[8:11], v[160:163], v[212:215], v[8:11]
	v_mfma_f32_16x16x32_bf16 v[60:63], v[156:159], v[188:191], v[60:63]
	v_mfma_f32_16x16x32_bf16 v[56:59], v[164:167], v[188:191], v[56:59]
	v_mfma_f32_16x16x32_bf16 v[44:47], v[156:159], v[196:199], v[44:47]
	v_mfma_f32_16x16x32_bf16 v[40:43], v[164:167], v[196:199], v[40:43]
	v_mfma_f32_16x16x32_bf16 v[28:31], v[156:159], v[208:211], v[28:31]
	v_mfma_f32_16x16x32_bf16 v[24:27], v[164:167], v[208:211], v[24:27]
	v_mfma_f32_16x16x32_bf16 v[12:15], v[156:159], v[216:219], v[12:15]
	v_mfma_f32_16x16x32_bf16 v[8:11], v[164:167], v[216:219], v[8:11]
	v_mfma_f32_16x16x32_bf16 v[52:55], v[168:171], v[184:187], v[52:55]
	v_mfma_f32_16x16x32_bf16 v[48:51], v[176:179], v[184:187], v[48:51]
	v_mfma_f32_16x16x32_bf16 v[36:39], v[168:171], v[192:195], v[36:39]
	v_mfma_f32_16x16x32_bf16 v[32:35], v[176:179], v[192:195], v[32:35]
	v_mfma_f32_16x16x32_bf16 v[20:23], v[168:171], v[200:203], v[20:23]
	v_mfma_f32_16x16x32_bf16 v[16:19], v[176:179], v[200:203], v[16:19]
	v_mfma_f32_16x16x32_bf16 v[4:7], v[168:171], v[212:215], v[4:7]
	v_mfma_f32_16x16x32_bf16 v[0:3], v[176:179], v[212:215], v[0:3]
	v_mfma_f32_16x16x32_bf16 v[52:55], v[172:175], v[188:191], v[52:55]
	v_mfma_f32_16x16x32_bf16 v[48:51], v[180:183], v[188:191], v[48:51]
	v_mfma_f32_16x16x32_bf16 v[36:39], v[172:175], v[196:199], v[36:39]
	v_mfma_f32_16x16x32_bf16 v[32:35], v[180:183], v[196:199], v[32:35]
	v_mfma_f32_16x16x32_bf16 v[20:23], v[172:175], v[208:211], v[20:23]
	v_mfma_f32_16x16x32_bf16 v[16:19], v[180:183], v[208:211], v[16:19]
	v_mfma_f32_16x16x32_bf16 v[4:7], v[172:175], v[216:219], v[4:7]
	v_mfma_f32_16x16x32_bf16 v[0:3], v[180:183], v[216:219], v[0:3]
	s_barrier
	s_add_i32 s54, s54, 2
	s_add_u32 s52, s52, 0x100
	s_addc_u32 s53, s53, 0
	s_add_u32 s24, s24, 0x100
	s_addc_u32 s25, s25, 0
	s_cmp_gt_u32 s54, 13
	s_cbranch_scc0 .LBB0_1646
	s_setprio 0
	s_and_b64 vcc, exec, s[14:15]
	s_cbranch_vccz .LBB0_1649
	s_barrier
